# v19 + 7-14 of each unit's first 16 fragment ds_reads issued at the previous unit's epilogue start (LDS latency under epilogue VALU), prologue-entry copy, exit-path lgkmcnt wait
# speedup vs baseline: 1.0012x; 1.0004x over previous
;     __device__ __forceinline__ const char* pa(const Gemm& g, const Unit& u, size_t tstep) const { return (const char*)g.A + (size_t)u.pm * tstep; }
;     __device__ __forceinline__ const char* pb(const Gemm& g, const Unit& u, size_t tstep) const { return (const char*)g.Bt + (size_t)u.pn * tstep; }
;     __device__ __forceinline__ const char* pa(const Gemm& g, const Unit& u, size_t tstep) const { return (const char*)g.A + (size_t)(u.pn >> 1) * 512 + (size_t)u.pm * tstep; }
;     __device__ __forceinline__ bool next(int i, Unit& u) const { const int ti = i / 3, sg = i - 3 * ti; if (!StaticOrder::next(ti, u)) return false; u.seg = sg; return true; }
; #define PG8_WAIT_V(n) asm volatile("s_waitcnt vmcnt(" #n ")" ::: "memory")
; #define PG8_BAR __builtin_amdgcn_s_barrier()
;     ...
;     for (int i = 0; i < 2; ++i) { int R, C; stage_rc(tid * 16 + i * 8192, R, C); const int Rb = Epi::PERM ? ((R & ~31) + perm32(R & 31)) : R;
;         voffA[i] = (unsigned)(R * (LDA ? LDA : K) + C) * 2u; voffB[i] = (unsigned)(Rb * K + C) * 2u; }
;     const size_t kstep = (size_t)(BK * 2);
;     const size_t hstepB = (size_t)HALF * K * 2, hstepA = LDA ? (size_t)HALF * LDA * 2 : hstepB;
;     const size_t tstepA = 2 * hstepA, tstepB = 2 * hstepB;
;     const unsigned ldsw = (unsigned)wid * 1024u;
;     const int aoff = lds_byte(wr * 64 + fr, fq * 8), boff = lds_byte(wc * 32 + fr, fq * 8);
;     ...
;     Unit cur, nxt; int ui = 0;
;     if (!S.next(0, cur)) return;
;     f32x4 acc[2][2][4][2];
; #pragma unroll
;     for (int a = 0; a < 2; ++a)
; #pragma unroll
;         for (int b = 0; b < 2; ++b)
; #pragma unroll
;             for (int m = 0; m < 4; ++m)
; #pragma unroll
;                 for (int n = 0; n < 2; ++n) acc[a][b][m][n] = (f32x4){0.f, 0.f, 0.f, 0.f};
;     bf16x8 At[4][2], B0[2][2], B1[2][2];
;     const char* cA = S.pa(g, cur, tstepA); const char* cB = S.pb(g, cur, tstepB);
;     S.a_ready(cur);
;     if constexpr (SP2) {
;         PG8_STAGE(PG8_SB(0, 0), cB, voffB); PG8_STAGE(PG8_SB(0, 1), cB + hstepB, voffB); PG8_STAGE(PG8_SA(0, 0), cA, voffA); PG8_STAGE(PG8_SA(0, 1), cA + hstepA, voffA);
;         if (wr == 1) PG8_BAR;
;         PG8_WAIT_V(2); PG8_BAR;
;         PG8_STAGE(PG8_SB(1, 0), cB + kstep, voffB); PG8_STAGE(PG8_SA(1, 0), cA + kstep, voffA); PG8_STAGE(PG8_SB(1, 1), cB + hstepB + kstep, voffB);
;         PG8_WAIT_V(6); PG8_BAR;
.LBB0_532:
	s_add_u32 s36, s18, 0x42c00000
	s_addc_u32 s37, s19, 0
	s_add_u32 s50, s18, 0x180000
	s_addc_u32 s51, s19, 0
	s_lshl_b32 s12, s12, 5
	s_and_b32 s42, s12, 0x60
	s_lshl_b32 s15, s8, 13
	s_lshl_b32 s40, s42, 7
	s_cmp_lt_u32 s20, 4
	s_cselect_b64 s[12:13], -1, 0
	s_cmp_eq_u32 s20, 7
	s_cselect_b64 s[34:35], -1, 0
	s_or_b64 s[12:13], s[12:13], s[34:35]
	s_and_b64 s[12:13], s[12:13], exec
	v_readlane_b32 s12, v255, 20
	s_cselect_b32 s85, 0, s12
	s_add_i32 m0, s81, 0x18000
	v_lshl_add_u64 v[8:9], v[8:9], 0, s[22:23]
	s_waitcnt vmcnt(2)
	s_barrier
	global_load_lds_dwordx4 v[8:9], off
	v_lshl_add_u64 v[6:7], v[6:7], 0, s[22:23]
	s_add_i32 m0, s81, 0x1a000
	s_add_i32 s86, s81, 0x8000
	s_add_i32 s87, s81, 0xa000
	global_load_lds_dwordx4 v[6:7], off
	v_lshl_add_u64 v[2:3], v[2:3], 0, s[22:23]
	s_mov_b32 m0, s86
	s_add_u32 s12, s66, 0x40080
	global_load_lds_dwordx4 v[2:3], off
	v_lshl_add_u64 v[2:3], v[4:5], 0, s[22:23]
	s_mov_b32 m0, s87
	s_addc_u32 s13, s67, 0
	global_load_lds_dwordx4 v[2:3], off
	s_add_i32 m0, s81, 0x1c000
	v_lshl_add_u64 v[2:3], s[12:13], 0, v[34:35]
	global_load_lds_dwordx4 v[2:3], off
	v_lshl_add_u64 v[2:3], s[12:13], 0, v[136:137]
	s_add_i32 m0, s81, 0x1e000
	s_waitcnt vmcnt(0)
	v_div_scale_f32 v6, s[12:13], v10, v10, 1.0
	global_load_lds_dwordx4 v[2:3], off
	v_bfe_u32 v3, v11, 4, 2
	v_rcp_f32_e32 v7, v6
	v_and_b32_e32 v2, 15, v11
	v_lshlrev_b32_e32 v4, 4, v3
	v_lshlrev_b32_e32 v5, 2, v11
	v_lshl_or_b32 v152, s8, 6, v2
	v_lshl_or_b32 v4, v2, 6, v4
	v_and_b32_e32 v5, 32, v5
	v_or_b32_e32 v2, v3, v2
	v_bitop3_b32 v153, v4, s40, v5 bitop3:0xde
	v_cmp_eq_u32_e64 s[40:41], 0, v2
	v_lshlrev_b32_e32 v2, 14, v12
	v_bitop3_b32 v8, v4, s15, v5 bitop3:0xde
	v_fma_f32 v4, -v6, v7, 1.0
	v_and_b32_e32 v2, 0xffff8000, v2
	v_fmac_f32_e32 v7, v4, v7
	v_div_scale_f32 v4, vcc, 1.0, v10, 1.0
	v_lshl_or_b32 v155, v3, 3, s42
	v_lshl_add_u32 v2, v13, 11, v2
	v_and_b32_e32 v3, 1, v12
	v_mul_f32_e32 v5, v4, v7
	v_lshl_or_b32 v2, v3, 6, v2
	v_fma_f32 v9, -v6, v5, v4
	v_lshl_add_u32 v138, v14, 1, v2
	v_lshlrev_b32_e32 v2, 14, v15
	v_fmac_f32_e32 v5, v9, v7
	v_and_b32_e32 v2, 0xffff8000, v2
	v_fma_f32 v4, -v6, v5, v4
	s_waitcnt vmcnt(6)
	v_lshl_add_u32 v2, v16, 11, v2
	v_and_b32_e32 v3, 1, v15
	v_div_fmas_f32 v4, v4, v7, v5
	s_cmpk_lt_u32 s6, 0x100
	v_lshl_or_b32 v2, v3, 6, v2
	v_div_fixup_f32 v154, v4, v10, 1.0
	s_mov_b32 s8, 0
	s_cselect_b64 s[52:53], -1, 0
	s_ashr_i32 s12, s78, 31
	s_ashr_i32 s13, s77, 31
	v_mov_b32_e32 v139, v35
	v_lshl_add_u32 v140, v17, 1, v2
	v_mov_b32_e32 v141, v35
	v_add_u32_e32 v156, 0, v8
	s_barrier
	v_add_u32_e32 v162, 0x10000, v153
	ds_read_b128 v[202:205], v162 offset:19456
	ds_read_b128 v[206:209], v156
	ds_read_b128 v[210:213], v156 offset:1024
	ds_read_b128 v[214:217], v156 offset:2048
	ds_read_b128 v[218:221], v156 offset:3072
	ds_read_b128 v[222:225], v156 offset:4096
	ds_read_b128 v[234:237], v156 offset:5120
	ds_read_b128 v[238:241], v156 offset:6144
	ds_read_b128 v[242:245], v156 offset:7168
	s_branch .LBB0_535

;     __device__ __forceinline__ const char* pa(const Gemm& g, const Unit& u, size_t tstep) const { return (const char*)g.A + (size_t)u.pm * tstep; }
;     __device__ __forceinline__ const char* pb(const Gemm& g, const Unit& u, size_t tstep) const { return (const char*)g.Bt + (size_t)u.pn * tstep; }
;     __device__ __forceinline__ const char* pa(const Gemm& g, const Unit& u, size_t tstep) const { return (const char*)g.A + (size_t)(u.pn >> 1) * 512 + (size_t)u.pm * tstep; }
;     __device__ __forceinline__ bool next(int i, Unit& u) const { const int ti = i / 3, sg = i - 3 * ti; if (!StaticOrder::next(ti, u)) return false; u.seg = sg; return true; }
;     __device__ __forceinline__ const char* pa(const Gemm& g, const Unit& u, size_t tstep) const { return (const char*)g.A + (size_t)u.seg * astride + (size_t)u.pm * tstep; }
;     __device__ __forceinline__ const char* pb(const Gemm& g, const Unit& u, size_t tstep) const { return (const char*)g.Bt + (size_t)u.seg * bstride + (size_t)u.pn * tstep; }
; #define PG8_LDA(dst, b, h) do { _Pragma("unroll") for (int m = 0; m < 4; ++m) _Pragma("unroll") for (int k = 0; k < 2; ++k) dst[m][k] = *(const PG8_LAS bf16x8*)(lds + PG8_SA(b, h) + aoff + m * 2048 + k * 1024); } while (0)
;     ...
;         const bool has_next = S.next(ui + 1, nxt);
;         const char* nA = has_next ? S.pa(g, nxt, tstepA) : cA; const char* nB = has_next ? S.pb(g, nxt, tstepB) : cB;
;         for (int t = 0; t < nt; t += 2) {
;             const bool last = (t == nt - 2);
;             const char* a1 = cA + (size_t)(t + 1) * kstep;
;             const char* a2 = last ? nA : cA + (size_t)(t + 2) * kstep; const char* b2 = last ? nB : cB + (size_t)(t + 2) * kstep;
;             const char* a3 = a2 + kstep; const char* b3 = b2 + kstep;
;             if (last && has_next) S.a_ready(nxt);
;             if constexpr (SP2) {
;             PG8_LDB(B0, 0, 0); PG8_LDB(B1, 0, 1); PG8_SCHED; PG8_LDA(At, 0, 0); PG8_STAGE(PG8_SA(1, 1), a1 + hstepA, voffA);
;             PG8_WAIT_V(8); PG8_WAIT_L(0); PG8_BAR; PG8_MMA(0, 0, At, B0); PG8_MMA(0, 1, At, B1); PG8_BAR; PG8_SCHED;
;             PG8_LDA(At, 0, 1); PG8_STAGE(PG8_SB(0, 0), b2, voffB); PG8_STAGE(PG8_SB(0, 1), b2 + hstepB, voffB); PG8_STAGE(PG8_SA(0, 0), a2, voffA);
;             PG8_WAIT_V(8); PG8_WAIT_L(0); PG8_BAR; PG8_MMA(1, 0, At, B0); PG8_MMA(1, 1, At, B1); PG8_BAR; PG8_SCHED;
.LBB0_537:
	s_ashr_i32 s57, s56, 31
	s_lshl_b64 s[34:35], s[56:57], 19
	s_add_u32 s58, s11, s34
	s_addc_u32 s59, s24, s35
	s_and_b64 s[34:35], s[42:43], exec
	s_cselect_b32 s6, s59, s65
	s_cselect_b32 s15, s58, s64
	s_ashr_i32 s55, s54, 31
	s_lshl_b64 s[34:35], s[54:55], 19
	s_add_u32 s60, s79, s34
	s_addc_u32 s61, s80, s35
	s_and_b64 s[34:35], s[42:43], exec
	s_cselect_b32 s34, s61, s67
	s_cselect_b32 s35, s60, s66
	s_add_u32 s64, s64, 0x40080
	s_addc_u32 s65, s65, 0
	s_add_u32 s45, s66, 0x100
	s_addc_u32 s55, s67, 0
	s_mov_b32 s57, -2
	s_waitcnt lgkmcnt(0)
	v_add_u32_e32 v162, 0x10000, v153
	s_add_u32 s63, s64, 0xfffc0080
	s_addc_u32 s66, s65, -1
	s_add_i32 s68, 0, 0x10000
	s_cmp_eq_u32 s57, 12
	s_cselect_b32 s75, s6, s66
	s_cselect_b32 s74, s15, s63
	s_cselect_b32 s67, s34, s55
	s_cselect_b32 s66, s35, s45
	s_add_i32 s63, 0, 0x14000
	ds_read_b128 v[142:145], v162
	ds_read_b128 v[146:149], v162 offset:1024
	ds_read_b128 v[158:161], v162 offset:2048
	ds_read_b128 v[186:189], v162 offset:3072
	ds_read_b128 v[190:193], v162 offset:16384
	ds_read_b128 v[194:197], v162 offset:17408
	ds_read_b128 v[198:201], v162 offset:18432
	s_add_i32 m0, s81, 0xc000
	global_load_lds_dwordx4 v138, s[64:65]
	s_add_i32 m0, s81, 0xe000
	s_nop 0
	global_load_lds_dwordx4 v140, s[64:65]
	s_waitcnt vmcnt(8)
	s_waitcnt lgkmcnt(0)
	s_barrier
	v_mfma_i32_16x16x64_i8 v[128:131], v[142:145], v[206:209], 0
	v_mfma_i32_16x16x64_i8 v[120:123], v[158:161], v[206:209], 0
	v_mfma_i32_16x16x64_i8 v[112:115], v[142:145], v[214:217], 0
	v_mfma_i32_16x16x64_i8 v[104:107], v[158:161], v[214:217], 0
	v_mfma_i32_16x16x64_i8 v[96:99], v[142:145], v[222:225], 0
	v_mfma_i32_16x16x64_i8 v[88:91], v[158:161], v[222:225], 0
	v_mfma_i32_16x16x64_i8 v[80:83], v[142:145], v[238:241], 0
	v_mfma_i32_16x16x64_i8 v[72:75], v[158:161], v[238:241], 0
	v_mfma_i32_16x16x64_i8 v[128:131], v[146:149], v[210:213], v[128:131]
	v_mfma_i32_16x16x64_i8 v[120:123], v[186:189], v[210:213], v[120:123]
	v_mfma_i32_16x16x64_i8 v[112:115], v[146:149], v[218:221], v[112:115]
	v_mfma_i32_16x16x64_i8 v[104:107], v[186:189], v[218:221], v[104:107]
	v_mfma_i32_16x16x64_i8 v[96:99], v[146:149], v[234:237], v[96:99]
	v_mfma_i32_16x16x64_i8 v[88:91], v[186:189], v[234:237], v[88:91]
	v_mfma_i32_16x16x64_i8 v[80:83], v[146:149], v[242:245], v[80:83]
	v_mfma_i32_16x16x64_i8 v[72:75], v[186:189], v[242:245], v[72:75]
	v_mfma_i32_16x16x64_i8 v[124:127], v[190:193], v[206:209], 0
	v_mfma_i32_16x16x64_i8 v[116:119], v[198:201], v[206:209], 0
	v_mfma_i32_16x16x64_i8 v[108:111], v[190:193], v[214:217], 0
	v_mfma_i32_16x16x64_i8 v[100:103], v[198:201], v[214:217], 0
	v_mfma_i32_16x16x64_i8 v[92:95], v[190:193], v[222:225], 0
	v_mfma_i32_16x16x64_i8 v[84:87], v[198:201], v[222:225], 0
	v_mfma_i32_16x16x64_i8 v[76:79], v[190:193], v[238:241], 0
	v_mfma_i32_16x16x64_i8 v[68:71], v[198:201], v[238:241], 0
	v_mfma_i32_16x16x64_i8 v[124:127], v[194:197], v[210:213], v[124:127]
	v_mfma_i32_16x16x64_i8 v[116:119], v[202:205], v[210:213], v[116:119]
	v_mfma_i32_16x16x64_i8 v[108:111], v[194:197], v[218:221], v[108:111]
	v_mfma_i32_16x16x64_i8 v[100:103], v[202:205], v[218:221], v[100:103]
	v_mfma_i32_16x16x64_i8 v[92:95], v[194:197], v[234:237], v[92:95]
	v_mfma_i32_16x16x64_i8 v[84:87], v[202:205], v[234:237], v[84:87]
	v_mfma_i32_16x16x64_i8 v[76:79], v[194:197], v[242:245], v[76:79]
	v_mfma_i32_16x16x64_i8 v[68:71], v[202:205], v[242:245], v[68:71]
	s_barrier
	s_add_i32 s68, s68, s10
	s_mov_b32 m0, s68
	ds_read_b128 v[206:209], v156 offset:16384
	ds_read_b128 v[210:213], v156 offset:17408
	ds_read_b128 v[214:217], v156 offset:18432
	ds_read_b128 v[218:221], v156 offset:19456
	ds_read_b128 v[222:225], v156 offset:20480
	ds_read_b128 v[234:237], v156 offset:21504
	ds_read_b128 v[238:241], v156 offset:22528
	ds_read_b128 v[242:245], v156 offset:23552
	global_load_lds_dwordx4 v34, s[66:67]
	s_add_i32 m0, s68, 0x2000
	s_add_u32 s70, s66, 0x40000
	s_addc_u32 s71, s67, 0
	s_add_i32 s63, s63, s10
	global_load_lds_dwordx4 v136, s[66:67]
	s_mov_b32 m0, s63
	s_nop 0
	global_load_lds_dwordx4 v34, s[70:71]
	s_add_i32 m0, s63, 0x2000
	s_nop 0
	global_load_lds_dwordx4 v136, s[70:71]
	s_mov_b32 m0, s81
	s_nop 0
	global_load_lds_dwordx4 v132, s[74:75]
	s_mov_b32 m0, s82
	s_nop 0
	global_load_lds_dwordx4 v134, s[74:75]
	s_waitcnt vmcnt(8)
	s_waitcnt lgkmcnt(0)
	s_barrier
	v_mfma_i32_16x16x64_i8 v[64:67], v[142:145], v[206:209], 0
	v_mfma_i32_16x16x64_i8 v[56:59], v[158:161], v[206:209], 0
	v_mfma_i32_16x16x64_i8 v[48:51], v[142:145], v[214:217], 0
	v_mfma_i32_16x16x64_i8 v[40:43], v[158:161], v[214:217], 0
	v_mfma_i32_16x16x64_i8 v[30:33], v[142:145], v[222:225], 0
	v_mfma_i32_16x16x64_i8 v[22:25], v[158:161], v[222:225], 0
	v_mfma_i32_16x16x64_i8 v[14:17], v[142:145], v[238:241], 0
	v_mfma_i32_16x16x64_i8 v[6:9], v[158:161], v[238:241], 0
	v_mfma_i32_16x16x64_i8 v[64:67], v[146:149], v[210:213], v[64:67]
	v_mfma_i32_16x16x64_i8 v[56:59], v[186:189], v[210:213], v[56:59]
	v_mfma_i32_16x16x64_i8 v[48:51], v[146:149], v[218:221], v[48:51]
	v_mfma_i32_16x16x64_i8 v[40:43], v[186:189], v[218:221], v[40:43]
	v_mfma_i32_16x16x64_i8 v[30:33], v[146:149], v[234:237], v[30:33]
	v_mfma_i32_16x16x64_i8 v[22:25], v[186:189], v[234:237], v[22:25]
	v_mfma_i32_16x16x64_i8 v[14:17], v[146:149], v[242:245], v[14:17]
	v_mfma_i32_16x16x64_i8 v[6:9], v[186:189], v[242:245], v[6:9]
	v_mfma_i32_16x16x64_i8 v[60:63], v[190:193], v[206:209], 0
	v_mfma_i32_16x16x64_i8 v[52:55], v[198:201], v[206:209], 0
	v_mfma_i32_16x16x64_i8 v[44:47], v[190:193], v[214:217], 0
	v_mfma_i32_16x16x64_i8 v[36:39], v[198:201], v[214:217], 0
	v_mfma_i32_16x16x64_i8 v[26:29], v[190:193], v[222:225], 0
	v_mfma_i32_16x16x64_i8 v[18:21], v[198:201], v[222:225], 0
	v_mfma_i32_16x16x64_i8 v[10:13], v[190:193], v[238:241], 0
	v_mfma_i32_16x16x64_i8 v[2:5], v[198:201], v[238:241], 0
	v_mfma_i32_16x16x64_i8 v[60:63], v[194:197], v[210:213], v[60:63]
	v_mfma_i32_16x16x64_i8 v[52:55], v[202:205], v[210:213], v[52:55]
	v_mfma_i32_16x16x64_i8 v[44:47], v[194:197], v[218:221], v[44:47]
	v_mfma_i32_16x16x64_i8 v[36:39], v[202:205], v[218:221], v[36:39]
	v_mfma_i32_16x16x64_i8 v[26:29], v[194:197], v[234:237], v[26:29]
	v_mfma_i32_16x16x64_i8 v[18:21], v[202:205], v[234:237], v[18:21]
	v_mfma_i32_16x16x64_i8 v[10:13], v[194:197], v[242:245], v[10:13]
	v_mfma_i32_16x16x64_i8 v[2:5], v[202:205], v[242:245], v[2:5]
	s_barrier
	s_branch .Lpeel_mid_538
	.p2align	6

; __device__ __forceinline__ float sigmoidf_fast(float x) { return __builtin_amdgcn_rcpf(1.0f + __builtin_amdgcn_exp2f(-1.44269504089f * x)); }
; __device__ __forceinline__ unsigned cvt_pk4_fp8(float a, float b, float c, float d) { int w = 0; w = __builtin_amdgcn_cvt_pk_fp8_f32(a, b, w, false); w = __builtin_amdgcn_cvt_pk_fp8_f32(c, d, w, true); return (unsigned)w; }
;     __device__ __forceinline__ void operator()(const f32x4 (&acc)[2][2][4][2], const Unit& u, int wr, int wc, int fr, int fq) const {
;     ...
;             for (int m = 0; m < 4; ++m) { const size_t ro = (size_t)(row0 + ai * HALF + m * 16) * ldc + col0;
;                 float r[8]; const float scr_ = rs ? rs[row0 + ai * HALF + m * 16] * sc : sc;
; #pragma unroll
;                 for (int n = 0; n < 2; ++n)
; #pragma unroll
;                     for (int j = 0; j < 4; ++j) { const float ga = acc[ai][0][m][n][j], ua = acc[ai][1][m][n][j];
;                         const float g = (rs ? (float)__float_as_int(ga) : ga) * scr_, up = (rs ? (float)__float_as_int(ua) : ua) * scr_; r[n * 4 + j] = g * sigmoidf_fast(g) * up; }
; #pragma unroll
;                 for (int k = 0; k < 8; ++k) lm = fmaxf(lm, fabsf(r[k]));
;                 if (O8) {
; #pragma unroll
;                     for (int k = 0; k < 8; ++k) r[k] = __builtin_amdgcn_fmed3f(r[k] * s8, -448.0f, 448.0f);
;                     u32x2 w; w.x = cvt_pk4_fp8(r[0], r[1], r[2], r[3]); w.y = cvt_pk4_fp8(r[4], r[5], r[6], r[7]); *(u32x2*)(O8 + ro) = w; }
.LBB0_541:
	s_mov_b32 s98, 0xbfb8aa3b
	s_mov_b32 s99, 0xbfb8aa3b
	v_cvt_f32_i32_e32 v120, v120
	v_cvt_f32_i32_e32 v121, v121
	v_cvt_f32_i32_e32 v122, v122
	v_cvt_f32_i32_e32 v123, v123
	v_cvt_f32_i32_e32 v128, v128
	v_cvt_f32_i32_e32 v129, v129
	v_cvt_f32_i32_e32 v130, v130
	ds_read_b128 v[202:205], v162 offset:19456
	ds_read_b128 v[206:209], v156
	ds_read_b128 v[210:213], v156 offset:1024
	ds_read_b128 v[214:217], v156 offset:2048
	ds_read_b128 v[218:221], v156 offset:3072
	ds_read_b128 v[222:225], v156 offset:4096
	ds_read_b128 v[234:237], v156 offset:5120
	ds_read_b128 v[238:241], v156 offset:6144
	ds_read_b128 v[242:245], v156 offset:7168
	v_cvt_f32_i32_e32 v131, v131
	v_cvt_f32_i32_e32 v116, v116
	v_cvt_f32_i32_e32 v117, v117
	v_cvt_f32_i32_e32 v118, v118
	v_cvt_f32_i32_e32 v119, v119
	v_cvt_f32_i32_e32 v124, v124
	v_cvt_f32_i32_e32 v125, v125
	v_cvt_f32_i32_e32 v126, v126
	v_cvt_f32_i32_e32 v127, v127
	v_lshl_or_b32 v142, s44, 7, v155
	v_ashrrev_i32_e32 v143, 31, v142
	v_mad_i64_i32 v[148:149], s[34:35], v144, s1, v[142:143]
	s_mov_b64 s[44:45], -1
	s_and_b64 vcc, exec, s[28:29]
	s_waitcnt vmcnt(0)
	v_mul_f32_e32 v158, v154, v186
	v_pk_mul_f32 v[120:121], v[158:159], v[120:121] op_sel_hi:[0,1]
	v_pk_mul_f32 v[122:123], v[158:159], v[122:123] op_sel_hi:[0,1]
	v_pk_mul_f32 v[128:129], v[158:159], v[128:129] op_sel_hi:[0,1]
	v_pk_mul_f32 v[130:131], v[158:159], v[130:131] op_sel_hi:[0,1]
	v_pk_mul_f32 v[194:195], v[120:121], s[98:99]
	v_pk_mul_f32 v[196:197], v[122:123], s[98:99]
	v_pk_mul_f32 v[198:199], v[128:129], s[98:99]
	v_pk_mul_f32 v[200:201], v[130:131], s[98:99]
	v_pk_mul_f32 v[116:117], v[158:159], v[116:117] op_sel_hi:[0,1]
	v_pk_mul_f32 v[118:119], v[158:159], v[118:119] op_sel_hi:[0,1]
	v_pk_mul_f32 v[124:125], v[158:159], v[124:125] op_sel_hi:[0,1]
	v_pk_mul_f32 v[126:127], v[158:159], v[126:127] op_sel_hi:[0,1]
	v_exp_f32_e32 v194, v194
	v_exp_f32_e32 v195, v195
	v_exp_f32_e32 v196, v196
	v_exp_f32_e32 v197, v197
	v_exp_f32_e32 v198, v198
	v_exp_f32_e32 v199, v199
	v_exp_f32_e32 v200, v200
	v_exp_f32_e32 v201, v201
	v_pk_add_f32 v[194:195], v[194:195], 1.0 op_sel_hi:[1,0]
	v_pk_add_f32 v[196:197], v[196:197], 1.0 op_sel_hi:[1,0]
	v_pk_add_f32 v[198:199], v[198:199], 1.0 op_sel_hi:[1,0]
	v_pk_add_f32 v[200:201], v[200:201], 1.0 op_sel_hi:[1,0]
	v_rcp_f32_e32 v194, v194
	v_rcp_f32_e32 v195, v195
	v_rcp_f32_e32 v196, v196
	v_rcp_f32_e32 v197, v197
	v_rcp_f32_e32 v198, v198
	v_rcp_f32_e32 v199, v199
	v_rcp_f32_e32 v200, v200
	v_rcp_f32_e32 v201, v201
	v_pk_mul_f32 v[120:121], v[120:121], v[194:195]
	v_pk_mul_f32 v[122:123], v[122:123], v[196:197]
	v_pk_mul_f32 v[128:129], v[128:129], v[198:199]
	v_pk_mul_f32 v[130:131], v[130:131], v[200:201]
	v_pk_mul_f32 v[116:117], v[116:117], v[120:121]
	v_pk_mul_f32 v[118:119], v[118:119], v[122:123]
	v_pk_mul_f32 v[124:125], v[124:125], v[128:129]
	v_pk_mul_f32 v[126:127], v[126:127], v[130:131]
	s_cbranch_vccz .LBB0_543
	v_mul_f32_e32 v120, v151, v124
	v_med3_f32 v121, v120, s69, v228
	v_mul_f32_e32 v120, v151, v125
	v_med3_f32 v122, v120, s69, v228
	v_mul_f32_e32 v120, v151, v126
	v_med3_f32 v123, v120, s69, v228
	v_mul_f32_e32 v120, v151, v127
	v_med3_f32 v128, v120, s69, v228
	v_mul_f32_e32 v120, v151, v116
	v_med3_f32 v129, v120, s69, v228
	v_mul_f32_e32 v120, v151, v117
	v_med3_f32 v130, v120, s69, v228
	v_mul_f32_e32 v120, v151, v118
	v_med3_f32 v131, v120, s69, v228
	v_mov_b32_e32 v120, v35
	v_cvt_pk_fp8_f32 v120, v121, v122
	v_mov_b32_e32 v121, v35
	v_cvt_pk_fp8_f32 v121, v129, v130
	v_mul_f32_e32 v122, v151, v119
	v_med3_f32 v122, v122, s69, v228
	v_cvt_pk_fp8_f32 v120, v123, v128 op_sel:[0,0,1]
	v_cvt_pk_fp8_f32 v121, v131, v122 op_sel:[0,0,1]
	v_lshl_add_u64 v[122:123], s[36:37], 0, v[148:149]
	s_mov_b64 s[44:45], 0
	global_store_dwordx2 v[122:123], v[120:121], off

; #define PG8_WAIT_V(n) asm volatile("s_waitcnt vmcnt(" #n ")" ::: "memory")
; #define PG8_BAR __builtin_amdgcn_s_barrier()
;     ...
;     PG8_WAIT_V(0);
;     if constexpr (!ALIGN_EPI) { if (wr == 0) PG8_BAR; }
;     PG8_BAR;
.LBB0_588:
	s_waitcnt lgkmcnt(0)
	s_waitcnt vmcnt(0)
	v_readlane_b32 s86, v255, 28
	v_readlane_b32 s67, v255, 26
	s_barrier
	v_readlane_b32 s87, v255, 29
	s_and_saveexec_b64 s[28:29], s[38:39]
	s_cbranch_execz .LBB0_596

;     __device__ __forceinline__ const char* pa(const Gemm& g, const Unit& u, size_t tstep) const { return (const char*)g.A + (size_t)u.pm * tstep; }
;     __device__ __forceinline__ const char* pb(const Gemm& g, const Unit& u, size_t tstep) const { return (const char*)g.Bt + (size_t)u.pn * tstep; }
;     __device__ __forceinline__ const char* pa(const Gemm& g, const Unit& u, size_t tstep) const { return (const char*)g.A + (size_t)(u.pn >> 1) * 512 + (size_t)u.pm * tstep; }
;     __device__ __forceinline__ bool next(int i, Unit& u) const { const int ti = i / 3, sg = i - 3 * ti; if (!StaticOrder::next(ti, u)) return false; u.seg = sg; return true; }
; #define PG8_WAIT_V(n) asm volatile("s_waitcnt vmcnt(" #n ")" ::: "memory")
; #define PG8_BAR __builtin_amdgcn_s_barrier()
;     ...
;     for (int i = 0; i < 2; ++i) { int R, C; stage_rc(tid * 16 + i * 8192, R, C); const int Rb = Epi::PERM ? ((R & ~31) + perm32(R & 31)) : R;
;         voffA[i] = (unsigned)(R * (LDA ? LDA : K) + C) * 2u; voffB[i] = (unsigned)(Rb * K + C) * 2u; }
;     const size_t kstep = (size_t)(BK * 2);
;     const size_t hstepB = (size_t)HALF * K * 2, hstepA = LDA ? (size_t)HALF * LDA * 2 : hstepB;
;     const size_t tstepA = 2 * hstepA, tstepB = 2 * hstepB;
;     const unsigned ldsw = (unsigned)wid * 1024u;
;     const int aoff = lds_byte(wr * 64 + fr, fq * 8), boff = lds_byte(wc * 32 + fr, fq * 8);
;     ...
;     Unit cur, nxt; int ui = 0;
;     if (!S.next(0, cur)) return;
;     f32x4 acc[2][2][4][2];
; #pragma unroll
;     for (int a = 0; a < 2; ++a)
; #pragma unroll
;         for (int b = 0; b < 2; ++b)
; #pragma unroll
;             for (int m = 0; m < 4; ++m)
; #pragma unroll
;                 for (int n = 0; n < 2; ++n) acc[a][b][m][n] = (f32x4){0.f, 0.f, 0.f, 0.f};
;     bf16x8 At[4][2], B0[2][2], B1[2][2];
;     const char* cA = S.pa(g, cur, tstepA); const char* cB = S.pb(g, cur, tstepB);
;     S.a_ready(cur);
;     if constexpr (SP2) {
;         PG8_STAGE(PG8_SB(0, 0), cB, voffB); PG8_STAGE(PG8_SB(0, 1), cB + hstepB, voffB); PG8_STAGE(PG8_SA(0, 0), cA, voffA); PG8_STAGE(PG8_SA(0, 1), cA + hstepA, voffA);
;         if (wr == 1) PG8_BAR;
;         PG8_WAIT_V(2); PG8_BAR;
;         PG8_STAGE(PG8_SB(1, 0), cB + kstep, voffB); PG8_STAGE(PG8_SA(1, 0), cA + kstep, voffA); PG8_STAGE(PG8_SB(1, 1), cB + hstepB + kstep, voffB);
;         PG8_WAIT_V(6); PG8_BAR;
.LBB0_602:
	v_bfe_u32 v18, v16, 4, 2
	s_add_u32 s18, s18, 0x42c00000
	v_and_b32_e32 v17, 15, v16
	v_lshlrev_b32_e32 v19, 4, v18
	v_lshlrev_b32_e32 v16, 2, v16
	s_sext_i32_i16 s57, s24
	s_addc_u32 s19, s19, 0
	v_lshl_or_b32 v144, s30, 6, v17
	v_lshl_or_b32 v17, v17, 6, v19
	s_lshl_b32 s24, s30, 13
	v_and_b32_e32 v16, 32, v16
	v_bitop3_b32 v19, v17, s24, v16 bitop3:0xde
	s_lshl_b32 s24, s29, 5
	s_and_b32 s36, s24, 0x60
	s_lshl_b32 s24, s36, 7
	s_add_i32 m0, s12, 0x18000
	v_lshl_add_u64 v[8:9], v[8:9], 0, s[22:23]
	v_bitop3_b32 v145, v17, s24, v16 bitop3:0xde
	s_waitcnt vmcnt(2)
	s_barrier
	global_load_lds_dwordx4 v[8:9], off
	v_lshl_add_u64 v[6:7], v[6:7], 0, s[22:23]
	s_add_i32 m0, s12, 0x1a000
	s_add_i32 s24, s12, 0x8000
	s_add_i32 s35, s12, 0xa000
	global_load_lds_dwordx4 v[6:7], off
	v_lshl_add_u64 v[2:3], v[2:3], 0, s[22:23]
	s_mov_b32 m0, s24
	s_add_u32 s30, s52, 0x80080
	global_load_lds_dwordx4 v[2:3], off
	v_lshl_add_u64 v[2:3], v[4:5], 0, s[22:23]
	s_mov_b32 m0, s35
	s_addc_u32 s31, s53, 0
	global_load_lds_dwordx4 v[2:3], off
	s_add_i32 m0, s12, 0x1c000
	v_lshl_add_u64 v[2:3], s[30:31], 0, v[34:35]
	global_load_lds_dwordx4 v[2:3], off
	v_lshl_add_u64 v[2:3], s[30:31], 0, v[132:133]
	s_add_i32 m0, s12, 0x1e000
	s_cmpk_lt_u32 s28, 0x100
	global_load_lds_dwordx4 v[2:3], off
	v_lshlrev_b32_e32 v2, 15, v14
	v_and_b32_e32 v2, 0xffff0000, v2
	v_lshl_add_u32 v2, v13, 12, v2
	v_and_b32_e32 v3, 1, v14
	v_lshl_or_b32 v2, v3, 6, v2
	v_lshl_add_u32 v138, v15, 1, v2
	v_lshlrev_b32_e32 v2, 15, v10
	v_and_b32_e32 v2, 0xffff0000, v2
	s_waitcnt vmcnt(6)
	v_lshl_add_u32 v2, v11, 12, v2
	v_and_b32_e32 v3, 1, v10
	v_lshl_or_b32 v2, v3, 6, v2
	s_cselect_b64 s[28:29], -1, 0
	s_ashr_i32 s45, s78, 31
	v_lshl_or_b32 v146, v18, 3, s36
	v_mov_b32_e32 v139, v35
	v_lshl_add_u32 v140, v12, 1, v2
	v_mov_b32_e32 v141, v35
	s_mov_b32 s56, 0
	v_add_u32_e32 v147, 0, v19
	s_barrier
	v_add_u32_e32 v226, 0x10000, v145
	ds_read_b128 v[156:159], v226 offset:2048
	ds_read_b128 v[160:163], v226 offset:3072
	ds_read_b128 v[186:189], v226 offset:16384
	ds_read_b128 v[190:193], v226 offset:17408
	ds_read_b128 v[194:197], v226 offset:18432
	ds_read_b128 v[198:201], v226 offset:19456
	ds_read_b128 v[202:205], v147
	ds_read_b128 v[206:209], v147 offset:1024
	ds_read_b128 v[210:213], v147 offset:2048
	ds_read_b128 v[214:217], v147 offset:3072
	ds_read_b128 v[218:221], v147 offset:4096
	ds_read_b128 v[222:225], v147 offset:5120
	ds_read_b128 v[234:237], v147 offset:6144
	ds_read_b128 v[238:241], v147 offset:7168
	s_branch .LBB0_605

;     __device__ __forceinline__ const char* pa(const Gemm& g, const Unit& u, size_t tstep) const { return (const char*)g.A + (size_t)u.pm * tstep; }
;     __device__ __forceinline__ const char* pb(const Gemm& g, const Unit& u, size_t tstep) const { return (const char*)g.Bt + (size_t)u.pn * tstep; }
;     __device__ __forceinline__ const char* pa(const Gemm& g, const Unit& u, size_t tstep) const { return (const char*)g.A + (size_t)(u.pn >> 1) * 512 + (size_t)u.pm * tstep; }
;     __device__ __forceinline__ bool next(int i, Unit& u) const { const int ti = i / 3, sg = i - 3 * ti; if (!StaticOrder::next(ti, u)) return false; u.seg = sg; return true; }
;     __device__ __forceinline__ const char* pa(const Gemm& g, const Unit& u, size_t tstep) const { return (const char*)g.A + (size_t)u.seg * astride + (size_t)u.pm * tstep; }
;     __device__ __forceinline__ const char* pb(const Gemm& g, const Unit& u, size_t tstep) const { return (const char*)g.Bt + (size_t)u.seg * bstride + (size_t)u.pn * tstep; }
; #define PG8_LDA(dst, b, h) do { _Pragma("unroll") for (int m = 0; m < 4; ++m) _Pragma("unroll") for (int k = 0; k < 2; ++k) dst[m][k] = *(const PG8_LAS bf16x8*)(lds + PG8_SA(b, h) + aoff + m * 2048 + k * 1024); } while (0)
;     ...
;         const bool has_next = S.next(ui + 1, nxt);
;         const char* nA = has_next ? S.pa(g, nxt, tstepA) : cA; const char* nB = has_next ? S.pb(g, nxt, tstepB) : cB;
;         for (int t = 0; t < nt; t += 2) {
;             const bool last = (t == nt - 2);
;             const char* a1 = cA + (size_t)(t + 1) * kstep;
;             const char* a2 = last ? nA : cA + (size_t)(t + 2) * kstep; const char* b2 = last ? nB : cB + (size_t)(t + 2) * kstep;
;             const char* a3 = a2 + kstep; const char* b3 = b2 + kstep;
;             if (last && has_next) S.a_ready(nxt);
;             if constexpr (SP2) {
;             PG8_LDB(B0, 0, 0); PG8_LDB(B1, 0, 1); PG8_SCHED; PG8_LDA(At, 0, 0); PG8_STAGE(PG8_SA(1, 1), a1 + hstepA, voffA);
;             PG8_WAIT_V(8); PG8_WAIT_L(0); PG8_BAR; PG8_MMA(0, 0, At, B0); PG8_MMA(0, 1, At, B1); PG8_BAR; PG8_SCHED;
;             PG8_LDA(At, 0, 1); PG8_STAGE(PG8_SB(0, 0), b2, voffB); PG8_STAGE(PG8_SB(0, 1), b2 + hstepB, voffB); PG8_STAGE(PG8_SA(0, 0), a2, voffA);
;             PG8_WAIT_V(8); PG8_WAIT_L(0); PG8_BAR; PG8_MMA(1, 0, At, B0); PG8_MMA(1, 1, At, B1); PG8_BAR; PG8_SCHED;
.LBB0_607:
	s_ashr_i32 s37, s36, 31
	s_lshl_b64 s[40:41], s[36:37], 20
	s_add_u32 s40, s8, s40
	s_addc_u32 s41, s10, s41
	s_and_b64 s[42:43], s[38:39], exec
	s_cselect_b32 s37, s41, s51
	s_cselect_b32 s58, s40, s50
	s_ashr_i32 s31, s30, 31
	s_lshl_b64 s[42:43], s[30:31], 20
	s_add_u32 s42, s9, s42
	s_addc_u32 s43, s76, s43
	s_and_b64 s[54:55], s[38:39], exec
	s_cselect_b32 s31, s43, s53
	s_cselect_b32 s59, s42, s52
	s_add_u32 s50, s50, 0x80080
	s_addc_u32 s51, s51, 0
	s_add_u32 s60, s52, 0x100
	s_addc_u32 s61, s53, 0
	s_mov_b32 s62, -2
	v_add_u32_e32 v226, 0x10000, v145
	s_add_u32 s52, s50, 0xfff80080
	s_addc_u32 s53, s51, -1
	s_add_i32 s63, 0, 0x10000
	s_cmp_eq_u32 s62, 28
	s_cselect_b32 s55, s37, s53
	s_cselect_b32 s54, s58, s52
	s_cselect_b32 s53, s31, s61
	s_cselect_b32 s52, s59, s60
	s_add_i32 s66, 0, 0x14000
	ds_read_b128 v[148:151], v226
	ds_read_b128 v[152:155], v226 offset:1024
	s_add_i32 m0, s12, 0xc000
	global_load_lds_dwordx4 v138, s[50:51]
	s_add_i32 m0, s12, 0xe000
	s_nop 0
	global_load_lds_dwordx4 v140, s[50:51]
	s_waitcnt vmcnt(8)
	s_waitcnt lgkmcnt(0)
	s_barrier
	v_mfma_f32_16x16x32_bf16 v[128:131], v[148:151], v[202:205], 0
	v_mfma_f32_16x16x32_bf16 v[124:127], v[156:159], v[202:205], 0
	v_mfma_f32_16x16x32_bf16 v[112:115], v[148:151], v[210:213], 0
	v_mfma_f32_16x16x32_bf16 v[108:111], v[156:159], v[210:213], 0
	v_mfma_f32_16x16x32_bf16 v[96:99], v[148:151], v[218:221], 0
	v_mfma_f32_16x16x32_bf16 v[92:95], v[156:159], v[218:221], 0
	v_mfma_f32_16x16x32_bf16 v[80:83], v[148:151], v[234:237], 0
	v_mfma_f32_16x16x32_bf16 v[76:79], v[156:159], v[234:237], 0
	v_mfma_f32_16x16x32_bf16 v[128:131], v[152:155], v[206:209], v[128:131]
	v_mfma_f32_16x16x32_bf16 v[124:127], v[160:163], v[206:209], v[124:127]
	v_mfma_f32_16x16x32_bf16 v[112:115], v[152:155], v[214:217], v[112:115]
	v_mfma_f32_16x16x32_bf16 v[108:111], v[160:163], v[214:217], v[108:111]
	v_mfma_f32_16x16x32_bf16 v[96:99], v[152:155], v[222:225], v[96:99]
	v_mfma_f32_16x16x32_bf16 v[92:95], v[160:163], v[222:225], v[92:95]
	v_mfma_f32_16x16x32_bf16 v[80:83], v[152:155], v[238:241], v[80:83]
	v_mfma_f32_16x16x32_bf16 v[76:79], v[160:163], v[238:241], v[76:79]
	v_mfma_f32_16x16x32_bf16 v[120:123], v[186:189], v[202:205], 0
	v_mfma_f32_16x16x32_bf16 v[116:119], v[194:197], v[202:205], 0
	v_mfma_f32_16x16x32_bf16 v[104:107], v[186:189], v[210:213], 0
	v_mfma_f32_16x16x32_bf16 v[100:103], v[194:197], v[210:213], 0
	v_mfma_f32_16x16x32_bf16 v[88:91], v[186:189], v[218:221], 0
	v_mfma_f32_16x16x32_bf16 v[84:87], v[194:197], v[218:221], 0
	v_mfma_f32_16x16x32_bf16 v[72:75], v[186:189], v[234:237], 0
	v_mfma_f32_16x16x32_bf16 v[68:71], v[194:197], v[234:237], 0
	v_mfma_f32_16x16x32_bf16 v[120:123], v[190:193], v[206:209], v[120:123]
	v_mfma_f32_16x16x32_bf16 v[116:119], v[198:201], v[206:209], v[116:119]
	v_mfma_f32_16x16x32_bf16 v[104:107], v[190:193], v[214:217], v[104:107]
	v_mfma_f32_16x16x32_bf16 v[100:103], v[198:201], v[214:217], v[100:103]
	v_mfma_f32_16x16x32_bf16 v[88:91], v[190:193], v[222:225], v[88:91]
	v_mfma_f32_16x16x32_bf16 v[84:87], v[198:201], v[222:225], v[84:87]
	v_mfma_f32_16x16x32_bf16 v[72:75], v[190:193], v[238:241], v[72:75]
	v_mfma_f32_16x16x32_bf16 v[68:71], v[198:201], v[238:241], v[68:71]
	s_barrier
	s_add_i32 s63, s63, s6
	s_mov_b32 m0, s63
	ds_read_b128 v[202:205], v147 offset:16384
	ds_read_b128 v[206:209], v147 offset:17408
	ds_read_b128 v[210:213], v147 offset:18432
	ds_read_b128 v[214:217], v147 offset:19456
	ds_read_b128 v[218:221], v147 offset:20480
	ds_read_b128 v[222:225], v147 offset:21504
	ds_read_b128 v[234:237], v147 offset:22528
	ds_read_b128 v[238:241], v147 offset:23552
	global_load_lds_dwordx4 v34, s[52:53]
	s_add_i32 m0, s63, 0x2000
	s_add_u32 s64, s52, 0x80000
	s_addc_u32 s65, s53, 0
	s_add_i32 s63, s66, s6
	global_load_lds_dwordx4 v132, s[52:53]
	s_mov_b32 m0, s63
	s_add_u32 s98, s54, 0x80
	s_addc_u32 s99, s55, 0
	global_load_lds_dwordx4 v34, s[64:65]
	s_add_i32 m0, s63, 0x2000
	s_nop 0
	global_load_lds_dwordx4 v132, s[64:65]
	s_mov_b32 m0, s12
	s_nop 0
	global_load_lds_dwordx4 v136, s[54:55]
	s_mov_b32 m0, s13
	s_nop 0
	global_load_lds_dwordx4 v134, s[54:55]
	s_waitcnt vmcnt(8)
	s_waitcnt lgkmcnt(0)
	s_barrier
	v_mfma_f32_16x16x32_bf16 v[64:67], v[148:151], v[202:205], 0
	v_mfma_f32_16x16x32_bf16 v[60:63], v[156:159], v[202:205], 0
	v_mfma_f32_16x16x32_bf16 v[48:51], v[148:151], v[210:213], 0
	v_mfma_f32_16x16x32_bf16 v[44:47], v[156:159], v[210:213], 0
	v_mfma_f32_16x16x32_bf16 v[30:33], v[148:151], v[218:221], 0
	v_mfma_f32_16x16x32_bf16 v[26:29], v[156:159], v[218:221], 0
	v_mfma_f32_16x16x32_bf16 v[14:17], v[148:151], v[234:237], 0
	v_mfma_f32_16x16x32_bf16 v[10:13], v[156:159], v[234:237], 0
	v_mfma_f32_16x16x32_bf16 v[64:67], v[152:155], v[206:209], v[64:67]
	v_mfma_f32_16x16x32_bf16 v[60:63], v[160:163], v[206:209], v[60:63]
	v_mfma_f32_16x16x32_bf16 v[48:51], v[152:155], v[214:217], v[48:51]
	v_mfma_f32_16x16x32_bf16 v[44:47], v[160:163], v[214:217], v[44:47]
	v_mfma_f32_16x16x32_bf16 v[30:33], v[152:155], v[222:225], v[30:33]
	v_mfma_f32_16x16x32_bf16 v[26:29], v[160:163], v[222:225], v[26:29]
	v_mfma_f32_16x16x32_bf16 v[14:17], v[152:155], v[238:241], v[14:17]
	v_mfma_f32_16x16x32_bf16 v[10:13], v[160:163], v[238:241], v[10:13]
	v_mfma_f32_16x16x32_bf16 v[56:59], v[186:189], v[202:205], 0
	v_mfma_f32_16x16x32_bf16 v[52:55], v[194:197], v[202:205], 0
	v_mfma_f32_16x16x32_bf16 v[40:43], v[186:189], v[210:213], 0
	v_mfma_f32_16x16x32_bf16 v[36:39], v[194:197], v[210:213], 0
	v_mfma_f32_16x16x32_bf16 v[22:25], v[186:189], v[218:221], 0
	v_mfma_f32_16x16x32_bf16 v[18:21], v[194:197], v[218:221], 0
	v_mfma_f32_16x16x32_bf16 v[6:9], v[186:189], v[234:237], 0
	v_mfma_f32_16x16x32_bf16 v[2:5], v[194:197], v[234:237], 0
	v_mfma_f32_16x16x32_bf16 v[56:59], v[190:193], v[206:209], v[56:59]
	v_mfma_f32_16x16x32_bf16 v[52:55], v[198:201], v[206:209], v[52:55]
	v_mfma_f32_16x16x32_bf16 v[40:43], v[190:193], v[214:217], v[40:43]
	v_mfma_f32_16x16x32_bf16 v[36:39], v[198:201], v[214:217], v[36:39]
	v_mfma_f32_16x16x32_bf16 v[22:25], v[190:193], v[222:225], v[22:25]
	v_mfma_f32_16x16x32_bf16 v[18:21], v[198:201], v[222:225], v[18:21]
	v_mfma_f32_16x16x32_bf16 v[6:9], v[190:193], v[238:241], v[6:9]
	v_mfma_f32_16x16x32_bf16 v[2:5], v[198:201], v[238:241], v[2:5]
	s_barrier
	s_branch .Lpeel_mid_608
	.p2align	6

; __device__ __forceinline__ unsigned cvt_pk_bf16(float lo, float hi) { f32x2c v = {lo, hi}; bf16x2c b = __builtin_convertvector(v, bf16x2c); return __builtin_bit_cast(unsigned, b); }
; __device__ __forceinline__ float sigmoidf_fast(float x) { return __builtin_amdgcn_rcpf(1.0f + __builtin_amdgcn_exp2f(-1.44269504089f * x)); }
;     __device__ __forceinline__ void operator()(const f32x4 (&acc)[2][2][4][2], const Unit& u, int wr, int wc, int fr, int fq) const {
;     ...
;             for (int m = 0; m < 4; ++m) { bf16_t* rowp = O + (size_t)(row0 + ai * HALF + m * 16) * ldc + col0;
;                 float r[8];
; #pragma unroll
;                 for (int n = 0; n < 2; ++n)
; #pragma unroll
;                     for (int j = 0; j < 4; ++j) { const float g = acc[ai][0][m][n][j], up = acc[ai][1][m][n][j]; r[n * 4 + j] = g * sigmoidf_fast(g) * up; }
;                 if (mx) {
; #pragma unroll
;                     for (int k = 0; k < 8; ++k) lm = fmaxf(lm, fabsf(r[k])); }
;                 u32x4 w; w.x = cvt_pk_bf16(r[0], r[1]); w.y = cvt_pk_bf16(r[2], r[3]); w.z = cvt_pk_bf16(r[4], r[5]); w.w = cvt_pk_bf16(r[6], r[7]);
;                 *(u32x4*)rowp = w; }
.LBB0_611:
	v_mul_f32_e32 v142, 0xbfb8aa3b, v128
	v_exp_f32_e32 v142, v142
	v_mul_f32_e32 v143, 0xbfb8aa3b, v129
	v_exp_f32_e32 v143, v143
	v_mul_f32_e32 v149, 0xbfb8aa3b, v130
	v_add_f32_e32 v142, 1.0, v142
	v_rcp_f32_e32 v152, v142
	v_add_f32_e32 v142, 1.0, v143
	v_rcp_f32_e32 v153, v142
	v_exp_f32_e32 v149, v149
	v_lshl_or_b32 v150, s57, 7, v146
	v_lshl_add_u32 v148, s44, 8, v144
	v_pk_mul_f32 v[128:129], v[128:129], v[152:153]
	v_mul_f32_e32 v152, 0xbfb8aa3b, v131
	ds_read_b128 v[156:159], v226 offset:2048
	ds_read_b128 v[160:163], v226 offset:3072
	ds_read_b128 v[186:189], v226 offset:16384
	ds_read_b128 v[190:193], v226 offset:17408
	ds_read_b128 v[194:197], v226 offset:18432
	ds_read_b128 v[198:201], v226 offset:19456
	ds_read_b128 v[202:205], v147
	ds_read_b128 v[206:209], v147 offset:1024
	ds_read_b128 v[210:213], v147 offset:2048
	ds_read_b128 v[214:217], v147 offset:3072
	ds_read_b128 v[218:221], v147 offset:4096
	ds_read_b128 v[222:225], v147 offset:5120
	ds_read_b128 v[234:237], v147 offset:6144
	ds_read_b128 v[238:241], v147 offset:7168
	v_exp_f32_e32 v152, v152
	v_pk_mul_f32 v[120:121], v[128:129], v[120:121]
	v_add_f32_e32 v128, 1.0, v149
	v_mul_f32_e32 v149, 0xbfb8aa3b, v124
	v_add_f32_e32 v129, 1.0, v152
	v_rcp_f32_e32 v128, v128
	v_rcp_f32_e32 v129, v129
	v_exp_f32_e32 v149, v149
	v_mul_f32_e32 v152, 0xbfb8aa3b, v125
	v_exp_f32_e32 v152, v152
	v_pk_mul_f32 v[128:129], v[130:131], v[128:129]
	v_add_f32_e32 v130, 1.0, v149
	v_mul_f32_e32 v149, 0xbfb8aa3b, v126
	v_add_f32_e32 v131, 1.0, v152
	v_exp_f32_e32 v149, v149
	v_mul_f32_e32 v152, 0xbfb8aa3b, v127
	v_exp_f32_e32 v153, v152
	v_rcp_f32_e32 v130, v130
	v_add_f32_e32 v149, 1.0, v149
	v_rcp_f32_e32 v131, v131
	v_rcp_f32_e32 v152, v149
	v_add_f32_e32 v149, 1.0, v153
	v_rcp_f32_e32 v153, v149
	v_pk_mul_f32 v[124:125], v[124:125], v[130:131]
	v_pk_mul_f32 v[122:123], v[128:129], v[122:123]
	v_pk_mul_f32 v[124:125], v[124:125], v[116:117]
	v_pk_mul_f32 v[116:117], v[126:127], v[152:153]
	v_ashrrev_i32_e32 v151, 31, v150
	v_pk_mul_f32 v[126:127], v[116:117], v[118:119]
	v_cvt_pk_bf16_f32 v119, v122, v123
	v_mul_f32_e32 v122, 0xbfb8aa3b, v112
	v_mul_f32_e32 v123, 0xbfb8aa3b, v113
	v_exp_f32_e32 v122, v122
	v_exp_f32_e32 v123, v123
	v_mov_b64_e32 v[142:143], s[18:19]
	s_movk_i32 s31, 0x2c00
	v_mad_i64_i32 v[154:155], s[50:51], v148, s31, v[142:143]
	v_lshlrev_b64 v[116:117], 1, v[150:151]
	v_lshl_add_u64 v[128:129], v[154:155], 0, v[116:117]
	v_cvt_pk_bf16_f32 v118, v120, v121
	v_cvt_pk_bf16_f32 v120, v124, v125
	v_cvt_pk_bf16_f32 v121, v126, v127
	global_store_dwordx4 v[128:129], v[118:121], off
	s_andn2_b64 vcc, exec, s[38:39]
	s_mov_b64 s[38:39], -1
	v_add_f32_e32 v118, 1.0, v122
	v_add_f32_e32 v119, 1.0, v123
	v_rcp_f32_e32 v118, v118
	v_rcp_f32_e32 v119, v119
	v_or_b32_e32 v120, 16, v148
	v_mad_i64_i32 v[120:121], s[50:51], v120, s31, v[142:143]
	v_pk_mul_f32 v[112:113], v[112:113], v[118:119]
	v_mul_f32_e32 v118, 0xbfb8aa3b, v114
	v_mul_f32_e32 v119, 0xbfb8aa3b, v115
	v_exp_f32_e32 v118, v118
	v_exp_f32_e32 v119, v119
	v_pk_mul_f32 v[104:105], v[112:113], v[104:105]
	v_add_f32_e32 v112, 1.0, v118
	v_add_f32_e32 v113, 1.0, v119
	v_mul_f32_e32 v118, 0xbfb8aa3b, v108
	v_mul_f32_e32 v119, 0xbfb8aa3b, v109
	v_rcp_f32_e32 v112, v112
	v_rcp_f32_e32 v113, v113
	v_exp_f32_e32 v118, v118
	v_exp_f32_e32 v119, v119
	v_pk_mul_f32 v[112:113], v[114:115], v[112:113]
	v_add_f32_e32 v114, 1.0, v118
	v_add_f32_e32 v115, 1.0, v119
	v_mul_f32_e32 v118, 0xbfb8aa3b, v110
	v_mul_f32_e32 v119, 0xbfb8aa3b, v111
	v_exp_f32_e32 v118, v118
	v_exp_f32_e32 v119, v119
	v_rcp_f32_e32 v114, v114
	v_rcp_f32_e32 v115, v115
	v_add_f32_e32 v118, 1.0, v118
	v_add_f32_e32 v119, 1.0, v119
	v_rcp_f32_e32 v118, v118
	v_rcp_f32_e32 v119, v119
	v_pk_mul_f32 v[108:109], v[108:109], v[114:115]
	v_pk_mul_f32 v[106:107], v[112:113], v[106:107]
	v_pk_mul_f32 v[108:109], v[108:109], v[100:101]
	v_pk_mul_f32 v[100:101], v[110:111], v[118:119]
	v_lshl_add_u64 v[112:113], v[120:121], 0, v[116:117]
	v_pk_mul_f32 v[110:111], v[100:101], v[102:103]
	v_cvt_pk_bf16_f32 v100, v104, v105
	v_mul_f32_e32 v104, 0xbfb8aa3b, v96
	v_mul_f32_e32 v105, 0xbfb8aa3b, v97
	v_exp_f32_e32 v104, v104
	v_exp_f32_e32 v105, v105
	v_cvt_pk_bf16_f32 v101, v106, v107
	v_cvt_pk_bf16_f32 v102, v108, v109
	v_cvt_pk_bf16_f32 v103, v110, v111
	global_store_dwordx4 v[112:113], v[100:103], off
	s_nop 1
	v_add_f32_e32 v100, 1.0, v104
	v_add_f32_e32 v101, 1.0, v105
	v_rcp_f32_e32 v100, v100
	v_rcp_f32_e32 v101, v101
	v_or_b32_e32 v102, 32, v148
	v_mad_i64_i32 v[102:103], s[50:51], v102, s31, v[142:143]
	v_pk_mul_f32 v[96:97], v[96:97], v[100:101]
	v_mul_f32_e32 v100, 0xbfb8aa3b, v98
	v_mul_f32_e32 v101, 0xbfb8aa3b, v99
	v_exp_f32_e32 v100, v100
	v_exp_f32_e32 v101, v101
	v_pk_mul_f32 v[88:89], v[96:97], v[88:89]
	v_add_f32_e32 v96, 1.0, v100
	v_add_f32_e32 v97, 1.0, v101
	v_mul_f32_e32 v100, 0xbfb8aa3b, v92
	v_mul_f32_e32 v101, 0xbfb8aa3b, v93
	v_rcp_f32_e32 v96, v96
	v_rcp_f32_e32 v97, v97
	v_exp_f32_e32 v100, v100
	v_exp_f32_e32 v101, v101
	v_pk_mul_f32 v[96:97], v[98:99], v[96:97]
	v_add_f32_e32 v98, 1.0, v100
	v_add_f32_e32 v99, 1.0, v101
	v_mul_f32_e32 v100, 0xbfb8aa3b, v94
	v_mul_f32_e32 v101, 0xbfb8aa3b, v95
	v_exp_f32_e32 v100, v100
	v_exp_f32_e32 v101, v101
	v_rcp_f32_e32 v98, v98
	v_rcp_f32_e32 v99, v99
	v_add_f32_e32 v100, 1.0, v100
	v_add_f32_e32 v101, 1.0, v101
	v_rcp_f32_e32 v100, v100
	v_rcp_f32_e32 v101, v101
	v_pk_mul_f32 v[92:93], v[92:93], v[98:99]
	v_pk_mul_f32 v[90:91], v[96:97], v[90:91]
	v_pk_mul_f32 v[92:93], v[92:93], v[84:85]
	v_pk_mul_f32 v[84:85], v[94:95], v[100:101]
	v_lshl_add_u64 v[96:97], v[102:103], 0, v[116:117]
; __device__ __forceinline__ unsigned cvt_pk_bf16(float lo, float hi) { f32x2c v = {lo, hi}; bf16x2c b = __builtin_convertvector(v, bf16x2c); return __builtin_bit_cast(unsigned, b); }
; __device__ __forceinline__ float sigmoidf_fast(float x) { return __builtin_amdgcn_rcpf(1.0f + __builtin_amdgcn_exp2f(-1.44269504089f * x)); }
;     __device__ __forceinline__ void operator()(const f32x4 (&acc)[2][2][4][2], const Unit& u, int wr, int wc, int fr, int fq) const {
;     ...
;             for (int m = 0; m < 4; ++m) { bf16_t* rowp = O + (size_t)(row0 + ai * HALF + m * 16) * ldc + col0;
;                 float r[8];
; #pragma unroll
;                 for (int n = 0; n < 2; ++n)
; #pragma unroll
;                     for (int j = 0; j < 4; ++j) { const float g = acc[ai][0][m][n][j], up = acc[ai][1][m][n][j]; r[n * 4 + j] = g * sigmoidf_fast(g) * up; }
;                 if (mx) {
; #pragma unroll
;                     for (int k = 0; k < 8; ++k) lm = fmaxf(lm, fabsf(r[k])); }
;                 u32x4 w; w.x = cvt_pk_bf16(r[0], r[1]); w.y = cvt_pk_bf16(r[2], r[3]); w.z = cvt_pk_bf16(r[4], r[5]); w.w = cvt_pk_bf16(r[6], r[7]);
;                 *(u32x4*)rowp = w; }
	v_pk_mul_f32 v[94:95], v[84:85], v[86:87]
	v_cvt_pk_bf16_f32 v84, v88, v89
	v_mul_f32_e32 v88, 0xbfb8aa3b, v80
	v_mul_f32_e32 v89, 0xbfb8aa3b, v81
	v_exp_f32_e32 v88, v88
	v_exp_f32_e32 v89, v89
	v_cvt_pk_bf16_f32 v85, v90, v91
	v_cvt_pk_bf16_f32 v86, v92, v93
	v_cvt_pk_bf16_f32 v87, v94, v95
	global_store_dwordx4 v[96:97], v[84:87], off
	s_nop 1
	v_add_f32_e32 v84, 1.0, v88
	v_add_f32_e32 v85, 1.0, v89
	v_rcp_f32_e32 v84, v84
	v_rcp_f32_e32 v85, v85
	v_or_b32_e32 v86, 48, v148
	v_mad_i64_i32 v[86:87], s[50:51], v86, s31, v[142:143]
	v_pk_mul_f32 v[80:81], v[80:81], v[84:85]
	v_mul_f32_e32 v84, 0xbfb8aa3b, v82
	v_mul_f32_e32 v85, 0xbfb8aa3b, v83
	v_exp_f32_e32 v84, v84
	v_exp_f32_e32 v85, v85
	v_pk_mul_f32 v[72:73], v[80:81], v[72:73]
	v_add_f32_e32 v80, 1.0, v84
	v_add_f32_e32 v81, 1.0, v85
	v_mul_f32_e32 v84, 0xbfb8aa3b, v76
	v_mul_f32_e32 v85, 0xbfb8aa3b, v77
	v_rcp_f32_e32 v80, v80
	v_rcp_f32_e32 v81, v81
	v_exp_f32_e32 v84, v84
	v_exp_f32_e32 v85, v85
	v_pk_mul_f32 v[80:81], v[82:83], v[80:81]
	v_add_f32_e32 v82, 1.0, v84
	v_add_f32_e32 v83, 1.0, v85
	v_mul_f32_e32 v84, 0xbfb8aa3b, v78
	v_mul_f32_e32 v85, 0xbfb8aa3b, v79
	v_exp_f32_e32 v84, v84
	v_exp_f32_e32 v85, v85
	v_rcp_f32_e32 v82, v82
	v_rcp_f32_e32 v83, v83
	v_add_f32_e32 v84, 1.0, v84
	v_add_f32_e32 v85, 1.0, v85
	v_rcp_f32_e32 v84, v84
	v_rcp_f32_e32 v85, v85
	v_pk_mul_f32 v[76:77], v[76:77], v[82:83]
	v_pk_mul_f32 v[74:75], v[80:81], v[74:75]
	v_pk_mul_f32 v[76:77], v[76:77], v[68:69]
	v_pk_mul_f32 v[68:69], v[78:79], v[84:85]
	v_lshl_add_u64 v[80:81], v[86:87], 0, v[116:117]
	v_pk_mul_f32 v[78:79], v[68:69], v[70:71]
	v_cvt_pk_bf16_f32 v68, v72, v73
	v_mul_f32_e32 v72, 0xbfb8aa3b, v64
	v_mul_f32_e32 v73, 0xbfb8aa3b, v65
	v_exp_f32_e32 v72, v72
	v_exp_f32_e32 v73, v73
	v_cvt_pk_bf16_f32 v69, v74, v75
	v_cvt_pk_bf16_f32 v70, v76, v77
	v_cvt_pk_bf16_f32 v71, v78, v79
	global_store_dwordx4 v[80:81], v[68:71], off
	s_nop 1
	v_add_f32_e32 v68, 1.0, v72
	v_add_f32_e32 v69, 1.0, v73
	v_rcp_f32_e32 v68, v68
	v_rcp_f32_e32 v69, v69
	v_add_u32_e32 v70, 0x80, v148
	v_mad_i64_i32 v[70:71], s[50:51], v70, s31, v[142:143]
	v_pk_mul_f32 v[64:65], v[64:65], v[68:69]
	v_mul_f32_e32 v68, 0xbfb8aa3b, v66
	v_mul_f32_e32 v69, 0xbfb8aa3b, v67
	v_exp_f32_e32 v68, v68
	v_exp_f32_e32 v69, v69
	v_pk_mul_f32 v[56:57], v[64:65], v[56:57]
	v_add_f32_e32 v64, 1.0, v68
	v_add_f32_e32 v65, 1.0, v69
	v_mul_f32_e32 v68, 0xbfb8aa3b, v60
	v_mul_f32_e32 v69, 0xbfb8aa3b, v61
	v_rcp_f32_e32 v64, v64
	v_rcp_f32_e32 v65, v65
	v_exp_f32_e32 v68, v68
	v_exp_f32_e32 v69, v69
	v_pk_mul_f32 v[64:65], v[66:67], v[64:65]
	v_add_f32_e32 v66, 1.0, v68
	v_add_f32_e32 v67, 1.0, v69
	v_mul_f32_e32 v68, 0xbfb8aa3b, v62
	v_mul_f32_e32 v69, 0xbfb8aa3b, v63
	v_exp_f32_e32 v68, v68
	v_exp_f32_e32 v69, v69
	v_rcp_f32_e32 v66, v66
	v_rcp_f32_e32 v67, v67
	v_add_f32_e32 v68, 1.0, v68
	v_add_f32_e32 v69, 1.0, v69
	v_rcp_f32_e32 v68, v68
	v_rcp_f32_e32 v69, v69
	v_pk_mul_f32 v[60:61], v[60:61], v[66:67]
	v_pk_mul_f32 v[58:59], v[64:65], v[58:59]
	v_pk_mul_f32 v[60:61], v[60:61], v[52:53]
	v_pk_mul_f32 v[52:53], v[62:63], v[68:69]
	v_lshl_add_u64 v[64:65], v[70:71], 0, v[116:117]
	v_pk_mul_f32 v[62:63], v[52:53], v[54:55]
	v_cvt_pk_bf16_f32 v52, v56, v57
	v_mul_f32_e32 v56, 0xbfb8aa3b, v48
	v_mul_f32_e32 v57, 0xbfb8aa3b, v49
	v_exp_f32_e32 v56, v56
	v_exp_f32_e32 v57, v57
	v_cvt_pk_bf16_f32 v53, v58, v59
	v_cvt_pk_bf16_f32 v54, v60, v61
	v_cvt_pk_bf16_f32 v55, v62, v63
	global_store_dwordx4 v[64:65], v[52:55], off
	s_nop 1
	v_add_f32_e32 v52, 1.0, v56
	v_add_f32_e32 v53, 1.0, v57
	v_rcp_f32_e32 v52, v52
	v_rcp_f32_e32 v53, v53
	v_add_u32_e32 v54, 0x90, v148
	v_mad_i64_i32 v[54:55], s[50:51], v54, s31, v[142:143]
	v_pk_mul_f32 v[48:49], v[48:49], v[52:53]
	v_mul_f32_e32 v52, 0xbfb8aa3b, v50
	v_mul_f32_e32 v53, 0xbfb8aa3b, v51
	v_exp_f32_e32 v52, v52
	v_exp_f32_e32 v53, v53
	v_pk_mul_f32 v[40:41], v[48:49], v[40:41]
	v_add_f32_e32 v48, 1.0, v52
	v_add_f32_e32 v49, 1.0, v53
	v_mul_f32_e32 v52, 0xbfb8aa3b, v44
	v_mul_f32_e32 v53, 0xbfb8aa3b, v45
	v_rcp_f32_e32 v48, v48
	v_rcp_f32_e32 v49, v49
	v_exp_f32_e32 v52, v52
	v_exp_f32_e32 v53, v53
; __device__ __forceinline__ unsigned cvt_pk_bf16(float lo, float hi) { f32x2c v = {lo, hi}; bf16x2c b = __builtin_convertvector(v, bf16x2c); return __builtin_bit_cast(unsigned, b); }
; __device__ __forceinline__ float sigmoidf_fast(float x) { return __builtin_amdgcn_rcpf(1.0f + __builtin_amdgcn_exp2f(-1.44269504089f * x)); }
; #define PG8_WAIT_V(n) asm volatile("s_waitcnt vmcnt(" #n ")" ::: "memory")
; #define PG8_BAR __builtin_amdgcn_s_barrier()
;     __device__ __forceinline__ void operator()(const f32x4 (&acc)[2][2][4][2], const Unit& u, int wr, int wc, int fr, int fq) const {
;     ...
;             for (int m = 0; m < 4; ++m) { bf16_t* rowp = O + (size_t)(row0 + ai * HALF + m * 16) * ldc + col0;
;                 float r[8];
; #pragma unroll
;                 for (int n = 0; n < 2; ++n)
; #pragma unroll
;                     for (int j = 0; j < 4; ++j) { const float g = acc[ai][0][m][n][j], up = acc[ai][1][m][n][j]; r[n * 4 + j] = g * sigmoidf_fast(g) * up; }
;                 if (mx) {
; #pragma unroll
;                     for (int k = 0; k < 8; ++k) lm = fmaxf(lm, fabsf(r[k])); }
;                 u32x4 w; w.x = cvt_pk_bf16(r[0], r[1]); w.y = cvt_pk_bf16(r[2], r[3]); w.z = cvt_pk_bf16(r[4], r[5]); w.w = cvt_pk_bf16(r[6], r[7]);
;                 *(u32x4*)rowp = w; }
;     ...
;     PG8_WAIT_V(0);
;     if constexpr (!ALIGN_EPI) { if (wr == 0) PG8_BAR; }
;     PG8_BAR;
	v_pk_mul_f32 v[48:49], v[50:51], v[48:49]
	v_add_f32_e32 v50, 1.0, v52
	v_add_f32_e32 v51, 1.0, v53
	v_mul_f32_e32 v52, 0xbfb8aa3b, v46
	v_mul_f32_e32 v53, 0xbfb8aa3b, v47
	v_exp_f32_e32 v52, v52
	v_exp_f32_e32 v53, v53
	v_rcp_f32_e32 v50, v50
	v_rcp_f32_e32 v51, v51
	v_add_f32_e32 v52, 1.0, v52
	v_add_f32_e32 v53, 1.0, v53
	v_rcp_f32_e32 v52, v52
	v_rcp_f32_e32 v53, v53
	v_pk_mul_f32 v[44:45], v[44:45], v[50:51]
	v_pk_mul_f32 v[42:43], v[48:49], v[42:43]
	v_pk_mul_f32 v[44:45], v[44:45], v[36:37]
	v_pk_mul_f32 v[36:37], v[46:47], v[52:53]
	v_lshl_add_u64 v[48:49], v[54:55], 0, v[116:117]
	v_pk_mul_f32 v[46:47], v[36:37], v[38:39]
	v_cvt_pk_bf16_f32 v36, v40, v41
	v_mul_f32_e32 v40, 0xbfb8aa3b, v30
	v_mul_f32_e32 v41, 0xbfb8aa3b, v31
	v_exp_f32_e32 v40, v40
	v_exp_f32_e32 v41, v41
	v_cvt_pk_bf16_f32 v37, v42, v43
	v_cvt_pk_bf16_f32 v38, v44, v45
	v_cvt_pk_bf16_f32 v39, v46, v47
	global_store_dwordx4 v[48:49], v[36:39], off
	s_nop 1
	v_add_f32_e32 v36, 1.0, v40
	v_add_f32_e32 v37, 1.0, v41
	v_rcp_f32_e32 v36, v36
	v_rcp_f32_e32 v37, v37
	v_add_u32_e32 v38, 0xa0, v148
	v_mad_i64_i32 v[38:39], s[50:51], v38, s31, v[142:143]
	v_pk_mul_f32 v[30:31], v[30:31], v[36:37]
	v_mul_f32_e32 v36, 0xbfb8aa3b, v32
	v_mul_f32_e32 v37, 0xbfb8aa3b, v33
	v_exp_f32_e32 v36, v36
	v_exp_f32_e32 v37, v37
	v_pk_mul_f32 v[22:23], v[30:31], v[22:23]
	v_add_f32_e32 v30, 1.0, v36
	v_add_f32_e32 v31, 1.0, v37
	v_mul_f32_e32 v36, 0xbfb8aa3b, v26
	v_mul_f32_e32 v37, 0xbfb8aa3b, v27
	v_rcp_f32_e32 v30, v30
	v_rcp_f32_e32 v31, v31
	v_exp_f32_e32 v36, v36
	v_exp_f32_e32 v37, v37
	v_pk_mul_f32 v[30:31], v[32:33], v[30:31]
	v_add_f32_e32 v32, 1.0, v36
	v_add_f32_e32 v33, 1.0, v37
	v_mul_f32_e32 v36, 0xbfb8aa3b, v28
	v_mul_f32_e32 v37, 0xbfb8aa3b, v29
	v_exp_f32_e32 v36, v36
	v_exp_f32_e32 v37, v37
	v_rcp_f32_e32 v32, v32
	v_rcp_f32_e32 v33, v33
	v_add_f32_e32 v36, 1.0, v36
	v_add_f32_e32 v37, 1.0, v37
	v_rcp_f32_e32 v36, v36
	v_rcp_f32_e32 v37, v37
	v_pk_mul_f32 v[26:27], v[26:27], v[32:33]
	v_pk_mul_f32 v[24:25], v[30:31], v[24:25]
	v_pk_mul_f32 v[26:27], v[26:27], v[18:19]
	v_pk_mul_f32 v[18:19], v[28:29], v[36:37]
	v_lshl_add_u64 v[30:31], v[38:39], 0, v[116:117]
	v_pk_mul_f32 v[28:29], v[18:19], v[20:21]
	v_cvt_pk_bf16_f32 v18, v22, v23
	v_mul_f32_e32 v22, 0xbfb8aa3b, v14
	v_mul_f32_e32 v23, 0xbfb8aa3b, v15
	v_exp_f32_e32 v22, v22
	v_exp_f32_e32 v23, v23
	v_cvt_pk_bf16_f32 v19, v24, v25
	v_cvt_pk_bf16_f32 v20, v26, v27
	v_cvt_pk_bf16_f32 v21, v28, v29
	global_store_dwordx4 v[30:31], v[18:21], off
	s_nop 1
	v_add_f32_e32 v18, 1.0, v22
	v_add_f32_e32 v19, 1.0, v23
	v_rcp_f32_e32 v18, v18
	v_rcp_f32_e32 v19, v19
	v_add_u32_e32 v20, 0xb0, v148
	v_mad_i64_i32 v[20:21], s[50:51], v20, s31, v[142:143]
	v_pk_mul_f32 v[14:15], v[14:15], v[18:19]
	v_mul_f32_e32 v18, 0xbfb8aa3b, v16
	v_mul_f32_e32 v19, 0xbfb8aa3b, v17
	v_exp_f32_e32 v18, v18
	v_exp_f32_e32 v19, v19
	v_pk_mul_f32 v[6:7], v[14:15], v[6:7]
	v_add_f32_e32 v14, 1.0, v18
	v_add_f32_e32 v15, 1.0, v19
	v_mul_f32_e32 v18, 0xbfb8aa3b, v10
	v_mul_f32_e32 v19, 0xbfb8aa3b, v11
	v_rcp_f32_e32 v14, v14
	v_rcp_f32_e32 v15, v15
	v_exp_f32_e32 v18, v18
	v_exp_f32_e32 v19, v19
	v_pk_mul_f32 v[14:15], v[16:17], v[14:15]
	v_add_f32_e32 v16, 1.0, v18
	v_add_f32_e32 v17, 1.0, v19
	v_mul_f32_e32 v18, 0xbfb8aa3b, v12
	v_mul_f32_e32 v19, 0xbfb8aa3b, v13
	v_exp_f32_e32 v18, v18
	v_exp_f32_e32 v19, v19
	v_rcp_f32_e32 v16, v16
	v_rcp_f32_e32 v17, v17
	v_add_f32_e32 v18, 1.0, v18
	v_add_f32_e32 v19, 1.0, v19
	v_rcp_f32_e32 v18, v18
	v_rcp_f32_e32 v19, v19
	v_pk_mul_f32 v[10:11], v[10:11], v[16:17]
	v_pk_mul_f32 v[8:9], v[14:15], v[8:9]
	v_pk_mul_f32 v[10:11], v[10:11], v[2:3]
	v_pk_mul_f32 v[2:3], v[12:13], v[18:19]
	v_lshl_add_u64 v[14:15], v[20:21], 0, v[116:117]
	v_pk_mul_f32 v[12:13], v[2:3], v[4:5]
	v_cvt_pk_bf16_f32 v2, v6, v7
	v_cvt_pk_bf16_f32 v3, v8, v9
	v_cvt_pk_bf16_f32 v4, v10, v11
	v_cvt_pk_bf16_f32 v5, v12, v13
	global_store_dwordx4 v[14:15], v[2:5], off
	s_cbranch_vccnz .LBB0_604
	s_andn2_b64 vcc, exec, s[26:27]
	s_cbranch_vccnz .LBB0_603
	s_barrier
	s_branch .LBB0_603
.LBB0_614:
	s_waitcnt lgkmcnt(0)
	s_waitcnt vmcnt(0)
	s_barrier

;     __device__ __forceinline__ const char* pa(const Gemm& g, const Unit& u, size_t tstep) const { return (const char*)g.A + (size_t)u.pm * tstep; }
;     __device__ __forceinline__ const char* pb(const Gemm& g, const Unit& u, size_t tstep) const { return (const char*)g.Bt + (size_t)u.pn * tstep; }
;     __device__ __forceinline__ const char* pa(const Gemm& g, const Unit& u, size_t tstep) const { return (const char*)g.A + (size_t)(u.pn >> 1) * 512 + (size_t)u.pm * tstep; }
;     __device__ __forceinline__ bool next(int i, Unit& u) const { const int ti = i / 3, sg = i - 3 * ti; if (!StaticOrder::next(ti, u)) return false; u.seg = sg; return true; }
; #define PG8_WAIT_V(n) asm volatile("s_waitcnt vmcnt(" #n ")" ::: "memory")
; #define PG8_BAR __builtin_amdgcn_s_barrier()
;     ...
;     for (int i = 0; i < 2; ++i) { int R, C; stage_rc(tid * 16 + i * 8192, R, C); const int Rb = Epi::PERM ? ((R & ~31) + perm32(R & 31)) : R;
;         voffA[i] = (unsigned)(R * (LDA ? LDA : K) + C) * 2u; voffB[i] = (unsigned)(Rb * K + C) * 2u; }
;     const size_t kstep = (size_t)(BK * 2);
;     const size_t hstepB = (size_t)HALF * K * 2, hstepA = LDA ? (size_t)HALF * LDA * 2 : hstepB;
;     const size_t tstepA = 2 * hstepA, tstepB = 2 * hstepB;
;     const unsigned ldsw = (unsigned)wid * 1024u;
;     const int aoff = lds_byte(wr * 64 + fr, fq * 8), boff = lds_byte(wc * 32 + fr, fq * 8);
;     ...
;     Unit cur, nxt; int ui = 0;
;     if (!S.next(0, cur)) return;
;     f32x4 acc[2][2][4][2];
; #pragma unroll
;     for (int a = 0; a < 2; ++a)
; #pragma unroll
;         for (int b = 0; b < 2; ++b)
; #pragma unroll
;             for (int m = 0; m < 4; ++m)
; #pragma unroll
;                 for (int n = 0; n < 2; ++n) acc[a][b][m][n] = (f32x4){0.f, 0.f, 0.f, 0.f};
;     bf16x8 At[4][2], B0[2][2], B1[2][2];
;     const char* cA = S.pa(g, cur, tstepA); const char* cB = S.pb(g, cur, tstepB);
;     S.a_ready(cur);
;     if constexpr (SP2) {
;         PG8_STAGE(PG8_SB(0, 0), cB, voffB); PG8_STAGE(PG8_SB(0, 1), cB + hstepB, voffB); PG8_STAGE(PG8_SA(0, 0), cA, voffA); PG8_STAGE(PG8_SA(0, 1), cA + hstepA, voffA);
;         if (wr == 1) PG8_BAR;
;         PG8_WAIT_V(2); PG8_BAR;
;         PG8_STAGE(PG8_SB(1, 0), cB + kstep, voffB); PG8_STAGE(PG8_SA(1, 0), cA + kstep, voffA); PG8_STAGE(PG8_SB(1, 1), cB + hstepB + kstep, voffB);
;         PG8_WAIT_V(6); PG8_BAR;
.LBB0_680:
	s_sext_i32_i8 s61, s28
	s_add_u32 s28, s18, 0x52c00000
	v_lshrrev_b32_e32 v20, 1, v18
	s_addc_u32 s29, s19, 0
	v_and_b32_e32 v20, 24, v20
	s_lshl_b32 s31, s31, 5
	v_and_b32_e32 v19, 15, v18
	v_lshlrev_b32_e32 v21, 1, v20
	v_lshlrev_b32_e32 v18, 2, v18
	s_and_b32 s38, s31, 0x60
	s_add_i32 m0, s34, 0x18000
	v_lshl_add_u64 v[8:9], v[8:9], 0, s[22:23]
	v_lshl_or_b32 v142, s36, 6, v19
	v_lshl_or_b32 v19, v19, 6, v21
	s_lshl_b32 s36, s36, 13
	v_and_b32_e32 v18, 32, v18
	s_lshl_b32 s31, s38, 7
	s_waitcnt vmcnt(2)
	s_barrier
	global_load_lds_dwordx4 v[8:9], off
	v_lshl_add_u64 v[6:7], v[6:7], 0, s[22:23]
	s_add_i32 m0, s34, 0x1a000
	s_add_i32 s56, s34, 0x8000
	s_add_i32 s57, s34, 0xa000
	v_bitop3_b32 v21, v19, s36, v18 bitop3:0xde
	global_load_lds_dwordx4 v[6:7], off
	v_lshl_add_u64 v[2:3], v[2:3], 0, s[22:23]
	s_mov_b32 m0, s56
	s_add_u32 s36, s44, 0x160080
	global_load_lds_dwordx4 v[2:3], off
	v_lshl_add_u64 v[2:3], v[4:5], 0, s[22:23]
	s_mov_b32 m0, s57
	s_addc_u32 s37, s45, 0
	global_load_lds_dwordx4 v[2:3], off
	s_add_i32 m0, s34, 0x1c000
	v_lshl_add_u64 v[2:3], s[36:37], 0, v[34:35]
	global_load_lds_dwordx4 v[2:3], off
	v_lshl_add_u64 v[2:3], s[36:37], 0, v[136:137]
	s_add_i32 m0, s34, 0x1e000
	v_or_b32_e32 v144, s38, v20
	global_load_lds_dwordx4 v[2:3], off
	v_lshrrev_b32_e32 v3, 1, v10
	v_mul_lo_u32 v2, v12, s1
	s_mov_b32 s38, 0x16000
	v_mad_u64_u32 v[2:3], s[36:37], v3, s38, v[2:3]
	v_or_b32_e32 v2, v2, v11
	v_add_lshl_u32 v2, v2, v13, 1
	v_mov_b32_e32 v3, v35
	s_mov_b64 s[40:41], 0x160080
	v_lshl_add_u64 v[138:139], v[2:3], 0, s[40:41]
	v_lshrrev_b32_e32 v3, 1, v14
	v_mul_lo_u32 v2, v16, s1
	v_mad_u64_u32 v[2:3], s[36:37], v3, s38, v[2:3]
	s_waitcnt vmcnt(6)
	v_or_b32_e32 v2, v2, v15
	s_cmpk_lt_u32 s30, 0x100
	v_add_lshl_u32 v2, v2, v17, 1
	v_mov_b32_e32 v3, v35
	v_bitop3_b32 v143, v19, s31, v18 bitop3:0xde
	s_cselect_b64 s[30:31], -1, 0
	s_ashr_i32 s58, s24, 31
	v_lshl_add_u64 v[140:141], v[2:3], 0, s[40:41]
	s_mov_b32 s60, 0
	v_add_u32_e32 v145, 0, v21
	s_barrier
	v_add_u32_e32 v163, 0x10000, v143
	ds_read_b128 v[154:157], v163 offset:2048
	ds_read_b128 v[158:161], v163 offset:3072
	ds_read_b128 v[186:189], v163 offset:16384
	ds_read_b128 v[190:193], v163 offset:17408
	ds_read_b128 v[194:197], v163 offset:18432
	ds_read_b128 v[198:201], v163 offset:19456
	ds_read_b128 v[202:205], v145
	ds_read_b128 v[206:209], v145 offset:1024
	ds_read_b128 v[210:213], v145 offset:2048
	ds_read_b128 v[214:217], v145 offset:3072
	ds_read_b128 v[218:221], v145 offset:4096
	ds_read_b128 v[222:225], v145 offset:5120
	ds_read_b128 v[234:237], v145 offset:6144
	ds_read_b128 v[238:241], v145 offset:7168
	s_branch .LBB0_683

;     __device__ __forceinline__ const char* pa(const Gemm& g, const Unit& u, size_t tstep) const { return (const char*)g.A + (size_t)u.pm * tstep; }
;     __device__ __forceinline__ const char* pb(const Gemm& g, const Unit& u, size_t tstep) const { return (const char*)g.Bt + (size_t)u.pn * tstep; }
;     __device__ __forceinline__ const char* pa(const Gemm& g, const Unit& u, size_t tstep) const { return (const char*)g.A + (size_t)(u.pn >> 1) * 512 + (size_t)u.pm * tstep; }
;     __device__ __forceinline__ bool next(int i, Unit& u) const { const int ti = i / 3, sg = i - 3 * ti; if (!StaticOrder::next(ti, u)) return false; u.seg = sg; return true; }
;     __device__ __forceinline__ const char* pa(const Gemm& g, const Unit& u, size_t tstep) const { return (const char*)g.A + (size_t)u.seg * astride + (size_t)u.pm * tstep; }
;     __device__ __forceinline__ const char* pb(const Gemm& g, const Unit& u, size_t tstep) const { return (const char*)g.Bt + (size_t)u.seg * bstride + (size_t)u.pn * tstep; }
; #define PG8_LDA(dst, b, h) do { _Pragma("unroll") for (int m = 0; m < 4; ++m) _Pragma("unroll") for (int k = 0; k < 2; ++k) dst[m][k] = *(const PG8_LAS bf16x8*)(lds + PG8_SA(b, h) + aoff + m * 2048 + k * 1024); } while (0)
;     ...
;         const bool has_next = S.next(ui + 1, nxt);
;         const char* nA = has_next ? S.pa(g, nxt, tstepA) : cA; const char* nB = has_next ? S.pb(g, nxt, tstepB) : cB;
;         for (int t = 0; t < nt; t += 2) {
;             const bool last = (t == nt - 2);
;             const char* a1 = cA + (size_t)(t + 1) * kstep;
;             const char* a2 = last ? nA : cA + (size_t)(t + 2) * kstep; const char* b2 = last ? nB : cB + (size_t)(t + 2) * kstep;
;             const char* a3 = a2 + kstep; const char* b3 = b2 + kstep;
;             if (last && has_next) S.a_ready(nxt);
;             if constexpr (SP2) {
;             PG8_LDB(B0, 0, 0); PG8_LDB(B1, 0, 1); PG8_SCHED; PG8_LDA(At, 0, 0); PG8_STAGE(PG8_SA(1, 1), a1 + hstepA, voffA);
;             PG8_WAIT_V(8); PG8_WAIT_L(0); PG8_BAR; PG8_MMA(0, 0, At, B0); PG8_MMA(0, 1, At, B1); PG8_BAR; PG8_SCHED;
;             PG8_LDA(At, 0, 1); PG8_STAGE(PG8_SB(0, 0), b2, voffB); PG8_STAGE(PG8_SB(0, 1), b2 + hstepB, voffB); PG8_STAGE(PG8_SA(0, 0), a2, voffA);
;             PG8_WAIT_V(8); PG8_WAIT_L(0); PG8_BAR; PG8_MMA(1, 0, At, B0); PG8_MMA(1, 1, At, B1); PG8_BAR; PG8_SCHED;
.LBB0_693:
	s_add_u32 s64, s44, 0x100
	s_addc_u32 s65, s45, 0
	s_mov_b32 s66, -2
	v_add_u32_e32 v163, 0x10000, v143
	s_add_u32 s44, s42, 0x100
	s_addc_u32 s45, s43, 0
	s_add_i32 s67, 0, 0x10000
	s_cmpk_eq_i32 s66, 0x54
	s_cselect_b32 s53, s37, s45
	s_cselect_b32 s52, s36, s44
	s_cselect_b32 s51, s41, s65
	s_cselect_b32 s50, s40, s64
	s_add_i32 s68, 0, 0x14000
	ds_read_b128 v[146:149], v163
	ds_read_b128 v[150:153], v163 offset:1024
	s_add_i32 m0, s34, 0xc000
	global_load_lds_dwordx4 v138, s[42:43]
	s_add_i32 m0, s34, 0xe000
	s_nop 0
	global_load_lds_dwordx4 v140, s[42:43]
	s_waitcnt vmcnt(8)
	s_waitcnt lgkmcnt(0)
	s_barrier
	v_mfma_f32_16x16x32_bf16 v[128:131], v[146:149], v[202:205], 0
	v_mfma_f32_16x16x32_bf16 v[124:127], v[154:157], v[202:205], 0
	v_mfma_f32_16x16x32_bf16 v[120:123], v[146:149], v[210:213], 0
	v_mfma_f32_16x16x32_bf16 v[116:119], v[154:157], v[210:213], 0
	v_mfma_f32_16x16x32_bf16 v[104:107], v[146:149], v[218:221], 0
	v_mfma_f32_16x16x32_bf16 v[100:103], v[154:157], v[218:221], 0
	v_mfma_f32_16x16x32_bf16 v[88:91], v[146:149], v[234:237], 0
	v_mfma_f32_16x16x32_bf16 v[84:87], v[154:157], v[234:237], 0
	v_mfma_f32_16x16x32_bf16 v[128:131], v[150:153], v[206:209], v[128:131]
	v_mfma_f32_16x16x32_bf16 v[124:127], v[158:161], v[206:209], v[124:127]
	v_mfma_f32_16x16x32_bf16 v[120:123], v[150:153], v[214:217], v[120:123]
	v_mfma_f32_16x16x32_bf16 v[116:119], v[158:161], v[214:217], v[116:119]
	v_mfma_f32_16x16x32_bf16 v[104:107], v[150:153], v[222:225], v[104:107]
	v_mfma_f32_16x16x32_bf16 v[100:103], v[158:161], v[222:225], v[100:103]
	v_mfma_f32_16x16x32_bf16 v[88:91], v[150:153], v[238:241], v[88:91]
	v_mfma_f32_16x16x32_bf16 v[84:87], v[158:161], v[238:241], v[84:87]
	v_mfma_f32_16x16x32_bf16 v[112:115], v[186:189], v[202:205], 0
	v_mfma_f32_16x16x32_bf16 v[108:111], v[194:197], v[202:205], 0
	v_mfma_f32_16x16x32_bf16 v[96:99], v[186:189], v[210:213], 0
	v_mfma_f32_16x16x32_bf16 v[92:95], v[194:197], v[210:213], 0
	v_mfma_f32_16x16x32_bf16 v[80:83], v[186:189], v[218:221], 0
	v_mfma_f32_16x16x32_bf16 v[76:79], v[194:197], v[218:221], 0
	v_mfma_f32_16x16x32_bf16 v[72:75], v[186:189], v[234:237], 0
	v_mfma_f32_16x16x32_bf16 v[68:71], v[194:197], v[234:237], 0
	v_mfma_f32_16x16x32_bf16 v[112:115], v[190:193], v[206:209], v[112:115]
	v_mfma_f32_16x16x32_bf16 v[108:111], v[198:201], v[206:209], v[108:111]
	v_mfma_f32_16x16x32_bf16 v[96:99], v[190:193], v[214:217], v[96:99]
	v_mfma_f32_16x16x32_bf16 v[92:95], v[198:201], v[214:217], v[92:95]
	v_mfma_f32_16x16x32_bf16 v[80:83], v[190:193], v[222:225], v[80:83]
	v_mfma_f32_16x16x32_bf16 v[76:79], v[198:201], v[222:225], v[76:79]
	v_mfma_f32_16x16x32_bf16 v[72:75], v[190:193], v[238:241], v[72:75]
	v_mfma_f32_16x16x32_bf16 v[68:71], v[198:201], v[238:241], v[68:71]
	s_barrier
	s_add_i32 s42, s67, s15
	s_mov_b32 m0, s42
	ds_read_b128 v[202:205], v145 offset:16384
	ds_read_b128 v[206:209], v145 offset:17408
	ds_read_b128 v[210:213], v145 offset:18432
	ds_read_b128 v[214:217], v145 offset:19456
	ds_read_b128 v[218:221], v145 offset:20480
	ds_read_b128 v[222:225], v145 offset:21504
	ds_read_b128 v[234:237], v145 offset:22528
	ds_read_b128 v[238:241], v145 offset:23552
	global_load_lds_dwordx4 v34, s[50:51]
	s_add_i32 m0, s42, 0x2000
	s_add_u32 s42, s50, 0x160000
	s_addc_u32 s43, s51, 0
	s_add_u32 s98, s50, 0x80
	s_addc_u32 s99, s51, 0
	s_add_i32 s67, s68, s15
	global_load_lds_dwordx4 v136, s[50:51]
	s_mov_b32 m0, s67
	s_nop 0
	global_load_lds_dwordx4 v34, s[42:43]
	s_add_i32 m0, s67, 0x2000
	s_nop 0
	global_load_lds_dwordx4 v136, s[42:43]
	s_mov_b32 m0, s34
	s_nop 0
	global_load_lds_dwordx4 v132, s[52:53]
	s_mov_b32 m0, s35
	s_nop 0
	global_load_lds_dwordx4 v134, s[52:53]
	s_waitcnt vmcnt(8)
	s_waitcnt lgkmcnt(0)
	s_barrier
	v_mfma_f32_16x16x32_bf16 v[64:67], v[146:149], v[202:205], 0
	v_mfma_f32_16x16x32_bf16 v[60:63], v[154:157], v[202:205], 0
	v_mfma_f32_16x16x32_bf16 v[56:59], v[146:149], v[210:213], 0
	v_mfma_f32_16x16x32_bf16 v[52:55], v[154:157], v[210:213], 0
	v_mfma_f32_16x16x32_bf16 v[40:43], v[146:149], v[218:221], 0
	v_mfma_f32_16x16x32_bf16 v[36:39], v[154:157], v[218:221], 0
	v_mfma_f32_16x16x32_bf16 v[22:25], v[146:149], v[234:237], 0
	v_mfma_f32_16x16x32_bf16 v[18:21], v[154:157], v[234:237], 0
	v_mfma_f32_16x16x32_bf16 v[64:67], v[150:153], v[206:209], v[64:67]
	v_mfma_f32_16x16x32_bf16 v[60:63], v[158:161], v[206:209], v[60:63]
	v_mfma_f32_16x16x32_bf16 v[56:59], v[150:153], v[214:217], v[56:59]
	v_mfma_f32_16x16x32_bf16 v[52:55], v[158:161], v[214:217], v[52:55]
	v_mfma_f32_16x16x32_bf16 v[40:43], v[150:153], v[222:225], v[40:43]
	v_mfma_f32_16x16x32_bf16 v[36:39], v[158:161], v[222:225], v[36:39]
	v_mfma_f32_16x16x32_bf16 v[22:25], v[150:153], v[238:241], v[22:25]
	v_mfma_f32_16x16x32_bf16 v[18:21], v[158:161], v[238:241], v[18:21]
	v_mfma_f32_16x16x32_bf16 v[48:51], v[186:189], v[202:205], 0
	v_mfma_f32_16x16x32_bf16 v[44:47], v[194:197], v[202:205], 0
	v_mfma_f32_16x16x32_bf16 v[30:33], v[186:189], v[210:213], 0
	v_mfma_f32_16x16x32_bf16 v[26:29], v[194:197], v[210:213], 0
	v_mfma_f32_16x16x32_bf16 v[14:17], v[186:189], v[218:221], 0
	v_mfma_f32_16x16x32_bf16 v[10:13], v[194:197], v[218:221], 0
	v_mfma_f32_16x16x32_bf16 v[6:9], v[186:189], v[234:237], 0
	v_mfma_f32_16x16x32_bf16 v[2:5], v[194:197], v[234:237], 0
	v_mfma_f32_16x16x32_bf16 v[48:51], v[190:193], v[206:209], v[48:51]
	v_mfma_f32_16x16x32_bf16 v[44:47], v[198:201], v[206:209], v[44:47]
	v_mfma_f32_16x16x32_bf16 v[30:33], v[190:193], v[214:217], v[30:33]
	v_mfma_f32_16x16x32_bf16 v[26:29], v[198:201], v[214:217], v[26:29]
	v_mfma_f32_16x16x32_bf16 v[14:17], v[190:193], v[222:225], v[14:17]
	v_mfma_f32_16x16x32_bf16 v[10:13], v[198:201], v[222:225], v[10:13]
	v_mfma_f32_16x16x32_bf16 v[6:9], v[190:193], v[238:241], v[6:9]
	v_mfma_f32_16x16x32_bf16 v[2:5], v[198:201], v[238:241], v[2:5]
	s_barrier
	s_branch .Lpeel_mid_694
	.p2align	6

; __device__ __forceinline__ unsigned cvt_pk_bf16(float lo, float hi) { f32x2c v = {lo, hi}; bf16x2c b = __builtin_convertvector(v, bf16x2c); return __builtin_bit_cast(unsigned, b); }
;     __device__ __forceinline__ void operator()(const f32x4 (&acc)[2][2][4][2], const Unit& u, int wr, int wc, int fr, int fq) const {
;         const int row0 = u.pm * BM + wr * 64 + fr, col0 = u.pn * BM + wc * 32 + 8 * fq;
; #pragma unroll
;         for (int ai = 0; ai < 2; ++ai)
; #pragma unroll
;             for (int m = 0; m < 4; ++m) { bf16_t* rowp = O + (size_t)(row0 + ai * HALF + m * 16) * ldc + col0;
; #pragma unroll
;                 for (int bj = 0; bj < 2; ++bj) { const f32x4 v0 = acc[ai][bj][m][0], v1 = acc[ai][bj][m][1];
;                     u32x4 w; w.x = cvt_pk_bf16(v0[0], v0[1]); w.y = cvt_pk_bf16(v0[2], v0[3]); w.z = cvt_pk_bf16(v1[0], v1[1]); w.w = cvt_pk_bf16(v1[2], v1[3]);
;                     *(u32x4*)(rowp + bj * HALF) = w; } }
.LBB0_697:
	v_lshl_add_u32 v146, s59, 8, v142
	v_lshl_or_b32 v148, s61, 8, v144
	v_ashrrev_i32_e32 v147, 31, v146
	v_ashrrev_i32_e32 v149, 31, v148
	v_lshlrev_b64 v[150:151], 12, v[146:147]
	v_lshl_add_u64 v[150:151], s[28:29], 0, v[150:151]
	v_lshlrev_b64 v[148:149], 1, v[148:149]
	v_lshl_add_u64 v[150:151], v[150:151], 0, v[148:149]
	s_mov_b64 s[42:43], 0x80000
	v_cvt_pk_bf16_f32 v72, v72, v73
	v_cvt_pk_bf16_f32 v73, v74, v75
	v_cvt_pk_bf16_f32 v74, v68, v69
	v_lshl_add_u64 v[68:69], v[150:151], 0, s[42:43]
	s_mov_b32 s42, 0x80000
	ds_read_b128 v[154:157], v163 offset:2048
	ds_read_b128 v[158:161], v163 offset:3072
	ds_read_b128 v[186:189], v163 offset:16384
	ds_read_b128 v[190:193], v163 offset:17408
	ds_read_b128 v[194:197], v163 offset:18432
	ds_read_b128 v[198:201], v163 offset:19456
	ds_read_b128 v[202:205], v145
	ds_read_b128 v[206:209], v145 offset:1024
	ds_read_b128 v[210:213], v145 offset:2048
	ds_read_b128 v[214:217], v145 offset:3072
	ds_read_b128 v[218:221], v145 offset:4096
	ds_read_b128 v[222:225], v145 offset:5120
	ds_read_b128 v[234:237], v145 offset:6144
	ds_read_b128 v[238:241], v145 offset:7168
	v_cvt_pk_bf16_f32 v64, v64, v65
	v_cvt_pk_bf16_f32 v65, v66, v67
	v_cvt_pk_bf16_f32 v66, v60, v61
	v_add_co_u32_e32 v60, vcc, s42, v150
	v_cvt_pk_bf16_f32 v48, v48, v49
	v_cvt_pk_bf16_f32 v49, v50, v51
	v_cvt_pk_bf16_f32 v50, v44, v45
	v_cvt_pk_bf16_f32 v51, v46, v47
	s_mov_b64 s[42:43], 0x90000
	v_addc_co_u32_e32 v61, vcc, 0, v151, vcc
	global_store_dwordx4 v[68:69], v[48:51], off offset:256 sc0 sc1
	v_cvt_pk_bf16_f32 v112, v112, v113
	v_cvt_pk_bf16_f32 v113, v114, v115
	v_lshl_add_u64 v[48:49], v[150:151], 0, s[42:43]
	s_mov_b32 s42, 0x90000
	v_cvt_pk_bf16_f32 v114, v108, v109
	v_or_b32_e32 v108, 16, v146
	v_add_co_u32_e32 v50, vcc, s42, v150
	v_cvt_pk_bf16_f32 v30, v30, v31
	v_cvt_pk_bf16_f32 v31, v32, v33
	v_cvt_pk_bf16_f32 v32, v26, v27
	v_cvt_pk_bf16_f32 v33, v28, v29
	s_mov_b64 s[42:43], 0xa0000
	v_ashrrev_i32_e32 v109, 31, v108
	v_cvt_pk_bf16_f32 v96, v96, v97
	v_cvt_pk_bf16_f32 v97, v98, v99
	v_cvt_pk_bf16_f32 v98, v92, v93
	v_or_b32_e32 v92, 32, v146
	v_addc_co_u32_e32 v51, vcc, 0, v151, vcc
	global_store_dwordx4 v[48:49], v[30:33], off offset:256 sc0 sc1
	v_lshlrev_b64 v[108:109], 12, v[108:109]
	v_ashrrev_i32_e32 v93, 31, v92
	v_lshl_add_u64 v[30:31], v[150:151], 0, s[42:43]
	s_mov_b32 s42, 0xa0000
	v_cvt_pk_bf16_f32 v80, v80, v81
	v_cvt_pk_bf16_f32 v81, v82, v83
	v_cvt_pk_bf16_f32 v82, v76, v77
	v_or_b32_e32 v76, 48, v146
	v_add_co_u32_e32 v32, vcc, s42, v150
	v_cvt_pk_bf16_f32 v14, v14, v15
	v_cvt_pk_bf16_f32 v15, v16, v17
	v_cvt_pk_bf16_f32 v16, v10, v11
	v_cvt_pk_bf16_f32 v17, v12, v13
	s_mov_b64 s[42:43], 0xb0000
	v_cvt_pk_bf16_f32 v115, v110, v111
	v_lshl_add_u64 v[108:109], s[28:29], 0, v[108:109]
	v_lshlrev_b64 v[92:93], 12, v[92:93]
	v_ashrrev_i32_e32 v77, 31, v76
	v_addc_co_u32_e32 v33, vcc, 0, v151, vcc
	global_store_dwordx4 v[30:31], v[14:17], off offset:256 sc0 sc1
	global_store_dwordx4 v[150:151], v[112:115], off offset:256 sc0 sc1
	v_cvt_pk_bf16_f32 v99, v94, v95
	v_lshl_add_u64 v[14:15], v[150:151], 0, s[42:43]
	s_mov_b32 s42, 0xb0000
	v_lshl_add_u64 v[112:113], v[108:109], 0, v[148:149]
	v_lshl_add_u64 v[92:93], s[28:29], 0, v[92:93]
	v_lshlrev_b64 v[76:77], 12, v[76:77]
	v_add_co_u32_e32 v16, vcc, s42, v150
	global_store_dwordx4 v[112:113], v[96:99], off offset:256 sc0 sc1
	v_cvt_pk_bf16_f32 v83, v78, v79
	v_lshl_add_u64 v[76:77], s[28:29], 0, v[76:77]
	v_lshl_add_u64 v[96:97], v[92:93], 0, v[148:149]
	v_addc_co_u32_e32 v17, vcc, 0, v151, vcc
	v_cvt_pk_bf16_f32 v128, v128, v129
	v_cvt_pk_bf16_f32 v129, v130, v131
	v_cvt_pk_bf16_f32 v130, v124, v125
	v_cvt_pk_bf16_f32 v131, v126, v127
	v_cvt_pk_bf16_f32 v108, v120, v121
	v_cvt_pk_bf16_f32 v109, v122, v123
	v_cvt_pk_bf16_f32 v110, v116, v117
	v_cvt_pk_bf16_f32 v111, v118, v119
	v_cvt_pk_bf16_f32 v92, v104, v105
	v_cvt_pk_bf16_f32 v93, v106, v107
	v_cvt_pk_bf16_f32 v94, v100, v101
	v_cvt_pk_bf16_f32 v95, v102, v103
	global_store_dwordx4 v[96:97], v[80:83], off offset:256 sc0 sc1
	v_cvt_pk_bf16_f32 v78, v84, v85
	v_cvt_pk_bf16_f32 v79, v86, v87
	v_lshl_add_u64 v[80:81], v[76:77], 0, v[148:149]
	v_cvt_pk_bf16_f32 v76, v88, v89
	v_cvt_pk_bf16_f32 v77, v90, v91
	v_cvt_pk_bf16_f32 v75, v70, v71
	v_cvt_pk_bf16_f32 v67, v62, v63
	v_cvt_pk_bf16_f32 v44, v56, v57
	v_cvt_pk_bf16_f32 v45, v58, v59
	v_cvt_pk_bf16_f32 v46, v52, v53
	v_cvt_pk_bf16_f32 v47, v54, v55
	v_cvt_pk_bf16_f32 v26, v40, v41
	v_cvt_pk_bf16_f32 v27, v42, v43
	v_cvt_pk_bf16_f32 v28, v36, v37
	v_cvt_pk_bf16_f32 v29, v38, v39
	v_cvt_pk_bf16_f32 v10, v22, v23
	v_cvt_pk_bf16_f32 v11, v24, v25
	v_cvt_pk_bf16_f32 v12, v18, v19
	v_cvt_pk_bf16_f32 v13, v20, v21
	v_cvt_pk_bf16_f32 v6, v6, v7
	v_cvt_pk_bf16_f32 v7, v8, v9
	v_cvt_pk_bf16_f32 v8, v2, v3
	v_cvt_pk_bf16_f32 v9, v4, v5
	s_and_b64 vcc, exec, s[38:39]
	s_mov_b64 s[38:39], -1
	global_store_dwordx4 v[150:151], v[128:131], off sc0 sc1
	global_store_dwordx4 v[112:113], v[108:111], off sc0 sc1
	global_store_dwordx4 v[96:97], v[92:95], off sc0 sc1
	global_store_dwordx4 v[80:81], v[76:79], off sc0 sc1
	global_store_dwordx4 v[80:81], v[72:75], off offset:256 sc0 sc1
	global_store_dwordx4 v[60:61], v[64:67], off sc0 sc1
	global_store_dwordx4 v[50:51], v[44:47], off sc0 sc1
	global_store_dwordx4 v[32:33], v[26:29], off sc0 sc1
	global_store_dwordx4 v[16:17], v[10:13], off sc0 sc1
	global_store_dwordx4 v[14:15], v[6:9], off offset:256 sc0 sc1
	s_cbranch_vccnz .LBB0_682
	s_andn2_b64 vcc, exec, s[26:27]
	s_cbranch_vccnz .LBB0_681
	s_barrier
	s_branch .LBB0_681

;     __device__ __forceinline__ const char* pa(const Gemm& g, const Unit& u, size_t tstep) const { return (const char*)g.A + (size_t)u.pm * tstep; }
;     __device__ __forceinline__ const char* pb(const Gemm& g, const Unit& u, size_t tstep) const { return (const char*)g.Bt + (size_t)u.pn * tstep; }
;     __device__ __forceinline__ const char* pa(const Gemm& g, const Unit& u, size_t tstep) const { return (const char*)g.A + (size_t)(u.pn >> 1) * 512 + (size_t)u.pm * tstep; }
; #define PG8_WAIT_V(n) asm volatile("s_waitcnt vmcnt(" #n ")" ::: "memory")
;     ...
;     for (int i = 0; i < 2; ++i) { int R, C; stage_rc(tid * 16 + i * 8192, R, C); const int Rb = Epi::PERM ? ((R & ~31) + perm32(R & 31)) : R;
;         voffA[i] = (unsigned)(R * (LDA ? LDA : K) + C) * 2u; voffB[i] = (unsigned)(Rb * K + C) * 2u; }
;     const size_t kstep = (size_t)(BK * 2);
;     const size_t hstepB = (size_t)HALF * K * 2, hstepA = LDA ? (size_t)HALF * LDA * 2 : hstepB;
;     const size_t tstepA = 2 * hstepA, tstepB = 2 * hstepB;
;     const unsigned ldsw = (unsigned)wid * 1024u;
;     const int aoff = lds_byte(wr * 64 + fr, fq * 8), boff = lds_byte(wc * 32 + fr, fq * 8);
;     ...
;     Unit cur, nxt; int ui = 0;
;     if (!S.next(0, cur)) return;
;     f32x4 acc[2][2][4][2];
; #pragma unroll
;     for (int a = 0; a < 2; ++a)
; #pragma unroll
;         for (int b = 0; b < 2; ++b)
; #pragma unroll
;             for (int m = 0; m < 4; ++m)
; #pragma unroll
;                 for (int n = 0; n < 2; ++n) acc[a][b][m][n] = (f32x4){0.f, 0.f, 0.f, 0.f};
;     bf16x8 At[4][2], B0[2][2], B1[2][2];
;     const char* cA = S.pa(g, cur, tstepA); const char* cB = S.pb(g, cur, tstepB);
;     S.a_ready(cur);
;     if constexpr (SP2) {
;         PG8_STAGE(PG8_SB(0, 0), cB, voffB); PG8_STAGE(PG8_SB(0, 1), cB + hstepB, voffB); PG8_STAGE(PG8_SA(0, 0), cA, voffA); PG8_STAGE(PG8_SA(0, 1), cA + hstepA, voffA);
;         if (wr == 1) PG8_BAR;
;         PG8_WAIT_V(2); PG8_BAR;
;         PG8_STAGE(PG8_SB(1, 0), cB + kstep, voffB); PG8_STAGE(PG8_SA(1, 0), cA + kstep, voffA); PG8_STAGE(PG8_SB(1, 1), cB + hstepB + kstep, voffB);
;         PG8_WAIT_V(6); PG8_BAR;
; __global__ void __launch_bounds__(NWAVES * 64, 2) fwd_kernel(Args args_unused) {
;     ...
;                 const float sc = 1.0f / (fp8_scale(4.0f * __uint_as_float(((const gu32*)(ws + WS_CTL))[CW_WMAX + SL_ACT(s)])) * wscale(ws, SL_DN(s)));
.LBB0_712:
	v_mul_f32_e32 v19, 4.0, v19
	s_sext_i32_i8 s56, s31
	v_max_f32_e32 v19, 0xda24260, v19
	s_mov_b32 s31, 0x43dc0000
	v_div_scale_f32 v21, s[36:37], v19, v19, s31
	v_rcp_f32_e32 v22, v21
	s_add_u32 s18, s18, 0x52c00000
	s_addc_u32 s19, s19, 0
	s_add_i32 m0, s21, 0x18000
	v_fma_f32 v23, -v21, v22, 1.0
	v_fmac_f32_e32 v22, v23, v22
	v_div_scale_f32 v23, vcc, s31, v19, s31
	v_mul_f32_e32 v24, v23, v22
	v_fma_f32 v25, -v21, v24, v23
	v_fmac_f32_e32 v24, v25, v22
	v_fma_f32 v21, -v21, v24, v23
	v_div_fmas_f32 v21, v21, v22, v24
	v_div_fixup_f32 v19, v21, v19, s31
	v_min_f32_e32 v19, 0x5368d4a5, v19
	v_and_b32_e32 v19, 0x7f800000, v19
	v_mul_f32_e32 v19, v20, v19
	v_div_scale_f32 v20, s[36:37], v19, v19, 1.0
	v_rcp_f32_e32 v21, v20
	v_lshl_add_u64 v[8:9], v[8:9], 0, s[22:23]
	s_waitcnt vmcnt(2)
	s_barrier
	v_fma_f32 v22, -v20, v21, 1.0
	v_fmac_f32_e32 v21, v22, v21
	v_div_scale_f32 v22, vcc, 1.0, v19, 1.0
	v_mul_f32_e32 v23, v22, v21
	v_fma_f32 v24, -v20, v23, v22
	v_fmac_f32_e32 v23, v24, v21
	v_fma_f32 v20, -v20, v23, v22
	v_div_fmas_f32 v20, v20, v21, v23
	v_div_fixup_f32 v192, v20, v19, 1.0
	v_lshrrev_b32_e32 v20, 1, v18
	v_and_b32_e32 v20, 24, v20
	v_and_b32_e32 v19, 15, v18
	v_lshlrev_b32_e32 v21, 1, v20
	v_lshlrev_b32_e32 v18, 2, v18
	v_lshl_or_b32 v208, s29, 6, v19
	v_lshl_or_b32 v19, v19, 6, v21
	s_lshl_b32 s29, s29, 13
	v_and_b32_e32 v18, 32, v18
	v_bitop3_b32 v21, v19, s29, v18 bitop3:0xde
	s_lshl_b32 s29, s30, 5
	s_and_b32 s30, s29, 0x60
	s_lshl_b32 s29, s30, 7
	global_load_lds_dwordx4 v[8:9], off
	v_lshl_add_u64 v[6:7], v[6:7], 0, s[22:23]
	s_add_i32 m0, s21, 0x1a000
	s_add_i32 s53, s21, 0x8000
	s_add_i32 s54, s21, 0xa000
	global_load_lds_dwordx4 v[6:7], off
	v_lshl_add_u64 v[2:3], v[2:3], 0, s[22:23]
	s_mov_b32 m0, s53
	s_add_u32 s36, s44, 0xb0080
	global_load_lds_dwordx4 v[2:3], off
	v_lshl_add_u64 v[2:3], v[4:5], 0, s[22:23]
	s_mov_b32 m0, s54
	s_addc_u32 s37, s45, 0
	global_load_lds_dwordx4 v[2:3], off
	s_add_i32 m0, s21, 0x1c000
	v_lshl_add_u64 v[2:3], s[36:37], 0, v[34:35]
	global_load_lds_dwordx4 v[2:3], off
	v_lshl_add_u64 v[2:3], s[36:37], 0, v[190:191]
	s_add_i32 m0, s21, 0x1e000
	s_movk_i32 s36, 0xb00
	global_load_lds_dwordx4 v[2:3], off
	v_lshrrev_b32_e32 v3, 1, v10
	v_mul_lo_u32 v2, v12, s36
	s_mov_b32 s37, 0xb000
	v_or_b32_e32 v210, s30, v20
	v_mad_u64_u32 v[2:3], s[30:31], v3, s37, v[2:3]
	v_or_b32_e32 v2, v2, v11
	v_add_lshl_u32 v2, v2, v13, 1
	v_mov_b32_e32 v3, v35
	s_mov_b64 s[38:39], 0xb0080
	v_lshl_add_u64 v[196:197], v[2:3], 0, s[38:39]
	v_lshrrev_b32_e32 v3, 1, v14
	v_mul_lo_u32 v2, v16, s36
	v_mad_u64_u32 v[2:3], s[30:31], v3, s37, v[2:3]
	s_waitcnt vmcnt(6)
	v_or_b32_e32 v2, v2, v15
	s_cmpk_lt_u32 s28, 0x100
	v_add_lshl_u32 v2, v2, v17, 1
	v_mov_b32_e32 v3, v35
	v_bitop3_b32 v209, v19, s29, v18 bitop3:0xde
	s_cselect_b64 s[28:29], -1, 0
	s_ashr_i32 s57, s24, 31
	v_mov_b32_e32 v194, v192
	v_mov_b32_e32 v195, v192
	v_lshl_add_u64 v[198:199], v[2:3], 0, s[38:39]
	s_mov_b32 s58, 0
	v_add_u32_e32 v211, 0, v21
	s_barrier
	v_add_u32_e32 v250, 0x10000, v209
	ds_read_b128 v[26:29], v250
	ds_read_b128 v[30:33], v250 offset:1024
	ds_read_b128 v[18:21], v250 offset:2048
	ds_read_b128 v[22:25], v250 offset:3072
	ds_read_b128 v[200:203], v211
	ds_read_b128 v[204:207], v211 offset:1024
	ds_read_b128 v[212:215], v211 offset:2048
	ds_read_b128 v[216:219], v211 offset:3072
	ds_read_b128 v[220:223], v211 offset:4096
	ds_read_b128 v[224:227], v211 offset:5120
	ds_read_b128 v[234:237], v211 offset:6144
	ds_read_b128 v[238:241], v211 offset:7168
	s_branch .LBB0_715

;     __device__ __forceinline__ const char* pa(const Gemm& g, const Unit& u, size_t tstep) const { return (const char*)g.A + (size_t)u.pm * tstep; }
;     __device__ __forceinline__ const char* pb(const Gemm& g, const Unit& u, size_t tstep) const { return (const char*)g.Bt + (size_t)u.pn * tstep; }
;     __device__ __forceinline__ const char* pa(const Gemm& g, const Unit& u, size_t tstep) const { return (const char*)g.A + (size_t)(u.pn >> 1) * 512 + (size_t)u.pm * tstep; }
;     __device__ __forceinline__ bool next(int i, Unit& u) const { const int ti = i / 3, sg = i - 3 * ti; if (!StaticOrder::next(ti, u)) return false; u.seg = sg; return true; }
;     __device__ __forceinline__ const char* pa(const Gemm& g, const Unit& u, size_t tstep) const { return (const char*)g.A + (size_t)u.seg * astride + (size_t)u.pm * tstep; }
;     __device__ __forceinline__ const char* pb(const Gemm& g, const Unit& u, size_t tstep) const { return (const char*)g.Bt + (size_t)u.seg * bstride + (size_t)u.pn * tstep; }
; #define PG8_LDA(dst, b, h) do { _Pragma("unroll") for (int m = 0; m < 4; ++m) _Pragma("unroll") for (int k = 0; k < 2; ++k) dst[m][k] = *(const PG8_LAS bf16x8*)(lds + PG8_SA(b, h) + aoff + m * 2048 + k * 1024); } while (0)
;     ...
;         const bool has_next = S.next(ui + 1, nxt);
;         const char* nA = has_next ? S.pa(g, nxt, tstepA) : cA; const char* nB = has_next ? S.pb(g, nxt, tstepB) : cB;
;         for (int t = 0; t < nt; t += 2) {
;             const bool last = (t == nt - 2);
;             const char* a1 = cA + (size_t)(t + 1) * kstep;
;             const char* a2 = last ? nA : cA + (size_t)(t + 2) * kstep; const char* b2 = last ? nB : cB + (size_t)(t + 2) * kstep;
;             const char* a3 = a2 + kstep; const char* b3 = b2 + kstep;
;             if (last && has_next) S.a_ready(nxt);
;             if constexpr (SP2) {
;             PG8_LDB(B0, 0, 0); PG8_LDB(B1, 0, 1); PG8_SCHED; PG8_LDA(At, 0, 0); PG8_STAGE(PG8_SA(1, 1), a1 + hstepA, voffA);
;             PG8_WAIT_V(8); PG8_WAIT_L(0); PG8_BAR; PG8_MMA(0, 0, At, B0); PG8_MMA(0, 1, At, B1); PG8_BAR; PG8_SCHED;
;             PG8_LDA(At, 0, 1); PG8_STAGE(PG8_SB(0, 0), b2, voffB); PG8_STAGE(PG8_SB(0, 1), b2 + hstepB, voffB); PG8_STAGE(PG8_SA(0, 0), a2, voffA);
;             PG8_WAIT_V(8); PG8_WAIT_L(0); PG8_BAR; PG8_MMA(1, 0, At, B0); PG8_MMA(1, 1, At, B1); PG8_BAR; PG8_SCHED;
.LBB0_725:
	s_add_u32 s61, s44, 0x100
	s_addc_u32 s62, s45, 0
	s_mov_b32 s63, -2
	v_add_u32_e32 v250, 0x10000, v209
	s_add_u32 s40, s42, 0x100
	s_addc_u32 s41, s43, 0
	s_add_i32 s64, 0, 0x10000
	s_cmp_eq_u32 s63, 40
	s_cselect_b32 s51, s31, s41
	s_cselect_b32 s50, s30, s40
	s_cselect_b32 s45, s37, s62
	s_cselect_b32 s44, s36, s61
	s_add_i32 s65, 0, 0x14000
	ds_read_b128 v[10:13], v250 offset:16384
	ds_read_b128 v[14:17], v250 offset:17408
	ds_read_b128 v[2:5], v250 offset:18432
	ds_read_b128 v[6:9], v250 offset:19456
	s_add_i32 m0, s21, 0xc000
	global_load_lds_dwordx4 v196, s[42:43]
	s_add_i32 m0, s21, 0xe000
	s_nop 0
	global_load_lds_dwordx4 v198, s[42:43]
	s_waitcnt vmcnt(8)
	s_waitcnt lgkmcnt(0)
	s_barrier
	v_mfma_f32_16x16x128_f8f6f4 v[160:163], v[26:33], v[200:207], 0
	v_mfma_f32_16x16x128_f8f6f4 v[156:159], v[18:25], v[200:207], 0
	v_mfma_f32_16x16x128_f8f6f4 v[152:155], v[26:33], v[212:219], 0
	v_mfma_f32_16x16x128_f8f6f4 v[144:147], v[18:25], v[212:219], 0
	v_mfma_f32_16x16x128_f8f6f4 v[136:139], v[26:33], v[220:227], 0
	v_mfma_f32_16x16x128_f8f6f4 v[128:131], v[18:25], v[220:227], 0
	v_mfma_f32_16x16x128_f8f6f4 v[120:123], v[26:33], v[234:241], 0
	v_mfma_f32_16x16x128_f8f6f4 v[112:115], v[18:25], v[234:241], 0
	v_mfma_f32_16x16x128_f8f6f4 v[148:151], v[10:17], v[200:207], 0
	v_mfma_f32_16x16x128_f8f6f4 v[140:143], v[2:9], v[200:207], 0
	v_mfma_f32_16x16x128_f8f6f4 v[132:135], v[10:17], v[212:219], 0
	v_mfma_f32_16x16x128_f8f6f4 v[124:127], v[2:9], v[212:219], 0
	v_mfma_f32_16x16x128_f8f6f4 v[116:119], v[10:17], v[220:227], 0
	v_mfma_f32_16x16x128_f8f6f4 v[108:111], v[2:9], v[220:227], 0
	v_mfma_f32_16x16x128_f8f6f4 v[104:107], v[10:17], v[234:241], 0
	v_mfma_f32_16x16x128_f8f6f4 v[100:103], v[2:9], v[234:241], 0
	s_barrier
	s_add_i32 s42, s64, s15
	s_mov_b32 m0, s42
	ds_read_b128 v[212:215], v211 offset:16384
	ds_read_b128 v[216:219], v211 offset:17408
	ds_read_b128 v[220:223], v211 offset:18432
	ds_read_b128 v[224:227], v211 offset:19456
	ds_read_b128 v[234:237], v211 offset:20480
	ds_read_b128 v[238:241], v211 offset:21504
	ds_read_b128 v[242:245], v211 offset:22528
	ds_read_b128 v[246:249], v211 offset:23552
	global_load_lds_dwordx4 v34, s[44:45]
	s_add_i32 m0, s42, 0x2000
	s_add_u32 s42, s44, 0xb0000
	s_addc_u32 s43, s45, 0
	s_add_u32 s98, s44, 0x80
	s_addc_u32 s99, s45, 0
	s_add_i32 s64, s65, s15
	global_load_lds_dwordx4 v190, s[44:45]
	s_mov_b32 m0, s64
	s_nop 0
	global_load_lds_dwordx4 v34, s[42:43]
	s_add_i32 m0, s64, 0x2000
	s_nop 0
	global_load_lds_dwordx4 v190, s[42:43]
	s_mov_b32 m0, s21
	s_nop 0
	global_load_lds_dwordx4 v186, s[50:51]
	s_mov_b32 m0, s34
	s_nop 0
	global_load_lds_dwordx4 v188, s[50:51]
	s_waitcnt vmcnt(8)
	s_waitcnt lgkmcnt(0)
	s_barrier
	v_mfma_f32_16x16x128_f8f6f4 v[96:99], v[26:33], v[212:219], 0
	v_mfma_f32_16x16x128_f8f6f4 v[92:95], v[18:25], v[212:219], 0
	v_mfma_f32_16x16x128_f8f6f4 v[88:91], v[26:33], v[220:227], 0
	v_mfma_f32_16x16x128_f8f6f4 v[80:83], v[18:25], v[220:227], 0
	v_mfma_f32_16x16x128_f8f6f4 v[72:75], v[26:33], v[234:241], 0
	v_mfma_f32_16x16x128_f8f6f4 v[64:67], v[18:25], v[234:241], 0
	v_mfma_f32_16x16x128_f8f6f4 v[56:59], v[26:33], v[242:249], 0
	v_mfma_f32_16x16x128_f8f6f4 v[48:51], v[18:25], v[242:249], 0
	v_mfma_f32_16x16x128_f8f6f4 v[84:87], v[10:17], v[212:219], 0
	v_mfma_f32_16x16x128_f8f6f4 v[76:79], v[2:9], v[212:219], 0
	v_mfma_f32_16x16x128_f8f6f4 v[68:71], v[10:17], v[220:227], 0
	v_mfma_f32_16x16x128_f8f6f4 v[60:63], v[2:9], v[220:227], 0
	v_mfma_f32_16x16x128_f8f6f4 v[52:55], v[10:17], v[234:241], 0
	v_mfma_f32_16x16x128_f8f6f4 v[44:47], v[2:9], v[234:241], 0
	v_mfma_f32_16x16x128_f8f6f4 v[40:43], v[10:17], v[242:249], 0
	v_mfma_f32_16x16x128_f8f6f4 v[36:39], v[2:9], v[242:249], 0
	s_barrier
	s_branch .Lpeel_mid_726
	.p2align	6

; __device__ __forceinline__ unsigned cvt_pk_bf16(float lo, float hi) { f32x2c v = {lo, hi}; bf16x2c b = __builtin_convertvector(v, bf16x2c); return __builtin_bit_cast(unsigned, b); }
;     __device__ __forceinline__ void operator()(const f32x4 (&acc)[2][2][4][2], const Unit& u, int wr, int wc, int fr, int fq) const {
;         const int row0 = u.pm * BM + wr * 64 + fr, col0 = u.pn * BM + wc * 32 + 8 * fq;
; #pragma unroll
;         for (int ai = 0; ai < 2; ++ai)
; #pragma unroll
;             for (int m = 0; m < 4; ++m) { bf16_t* rowp = O + (size_t)(row0 + ai * HALF + m * 16) * ldc + col0;
; #pragma unroll
;                 for (int bj = 0; bj < 2; ++bj) { const f32x4 v0 = acc[ai][bj][m][0] * sc, v1 = acc[ai][bj][m][1] * sc;
;                     u32x4 w; w.x = cvt_pk_bf16(v0[0], v0[1]); w.y = cvt_pk_bf16(v0[2], v0[3]); w.z = cvt_pk_bf16(v1[0], v1[1]); w.w = cvt_pk_bf16(v1[2], v1[3]);
;                     *(u32x4*)(rowp + bj * HALF) = w; } }
.LBB0_729:
	v_lshl_add_u32 v8, s55, 8, v208
	v_lshl_or_b32 v2, s56, 8, v210
	v_ashrrev_i32_e32 v9, 31, v8
	v_ashrrev_i32_e32 v3, 31, v2
	v_lshlrev_b64 v[4:5], 12, v[8:9]
	v_lshl_add_u64 v[4:5], s[18:19], 0, v[4:5]
	v_lshlrev_b64 v[10:11], 1, v[2:3]
	v_mov_b32_e32 v193, v192
	v_lshl_add_u64 v[2:3], v[4:5], 0, v[10:11]
	v_pk_mul_f32 v[6:7], v[192:193], v[162:163]
	v_pk_mul_f32 v[4:5], v[194:195], v[160:161]
	v_pk_mul_f32 v[12:13], v[192:193], v[158:159]
	ds_read_b128 v[26:29], v250
	ds_read_b128 v[30:33], v250 offset:1024
	ds_read_b128 v[18:21], v250 offset:2048
	ds_read_b128 v[22:25], v250 offset:3072
	ds_read_b128 v[200:203], v211
	ds_read_b128 v[204:207], v211 offset:1024
	ds_read_b128 v[212:215], v211 offset:2048
	ds_read_b128 v[216:219], v211 offset:3072
	ds_read_b128 v[220:223], v211 offset:4096
	ds_read_b128 v[224:227], v211 offset:5120
	ds_read_b128 v[234:237], v211 offset:6144
	ds_read_b128 v[238:241], v211 offset:7168
	v_pk_mul_f32 v[14:15], v[194:195], v[156:157]
	v_cvt_pk_bf16_f32 v4, v4, v5
	v_cvt_pk_bf16_f32 v5, v6, v7
	v_cvt_pk_bf16_f32 v6, v14, v15
	v_cvt_pk_bf16_f32 v7, v12, v13
	s_nop 15
	s_nop 15
	global_store_dwordx4 v[2:3], v[4:7], off sc0 sc1
	v_pk_mul_f32 v[12:13], v[192:193], v[142:143]
	v_pk_mul_f32 v[14:15], v[194:195], v[140:141]
	v_pk_mul_f32 v[6:7], v[192:193], v[150:151]
	v_pk_mul_f32 v[4:5], v[194:195], v[148:149]
	v_pk_mul_f32 v[16:17], v[194:195], v[144:145]
	v_cvt_pk_bf16_f32 v4, v4, v5
	v_cvt_pk_bf16_f32 v5, v6, v7
	v_cvt_pk_bf16_f32 v6, v14, v15
	v_cvt_pk_bf16_f32 v7, v12, v13
	global_store_dwordx4 v[2:3], v[4:7], off offset:256 sc0 sc1
	v_pk_mul_f32 v[14:15], v[192:193], v[146:147]
	s_mov_b64 s[40:41], 0x80000
	v_or_b32_e32 v4, 16, v8
	v_ashrrev_i32_e32 v5, 31, v4
	v_lshlrev_b64 v[4:5], 12, v[4:5]
	v_lshl_add_u64 v[4:5], s[18:19], 0, v[4:5]
	v_lshl_add_u64 v[12:13], v[4:5], 0, v[10:11]
	v_pk_mul_f32 v[6:7], v[192:193], v[154:155]
	v_pk_mul_f32 v[4:5], v[194:195], v[152:153]
	s_nop 0
	v_cvt_pk_bf16_f32 v4, v4, v5
	v_cvt_pk_bf16_f32 v5, v6, v7
	v_cvt_pk_bf16_f32 v6, v16, v17
	v_cvt_pk_bf16_f32 v7, v14, v15
	global_store_dwordx4 v[12:13], v[4:7], off sc0 sc1
	v_pk_mul_f32 v[14:15], v[192:193], v[126:127]
	v_pk_mul_f32 v[16:17], v[194:195], v[124:125]
	v_pk_mul_f32 v[6:7], v[192:193], v[134:135]
	v_pk_mul_f32 v[4:5], v[194:195], v[132:133]
	s_nop 0
	v_cvt_pk_bf16_f32 v4, v4, v5
	v_cvt_pk_bf16_f32 v5, v6, v7
	v_cvt_pk_bf16_f32 v6, v16, v17
	v_cvt_pk_bf16_f32 v7, v14, v15
	global_store_dwordx4 v[12:13], v[4:7], off offset:256 sc0 sc1
	v_pk_mul_f32 v[14:15], v[192:193], v[130:131]
	v_pk_mul_f32 v[16:17], v[194:195], v[128:129]
	v_or_b32_e32 v4, 32, v8
	v_ashrrev_i32_e32 v5, 31, v4
	v_lshlrev_b64 v[4:5], 12, v[4:5]
	v_lshl_add_u64 v[4:5], s[18:19], 0, v[4:5]
	v_lshl_add_u64 v[12:13], v[4:5], 0, v[10:11]
	v_pk_mul_f32 v[6:7], v[192:193], v[138:139]
	v_pk_mul_f32 v[4:5], v[194:195], v[136:137]
	s_nop 0
	v_cvt_pk_bf16_f32 v4, v4, v5
	v_cvt_pk_bf16_f32 v5, v6, v7
	v_cvt_pk_bf16_f32 v6, v16, v17
	v_cvt_pk_bf16_f32 v7, v14, v15
	global_store_dwordx4 v[12:13], v[4:7], off sc0 sc1
	v_pk_mul_f32 v[14:15], v[192:193], v[110:111]
	v_pk_mul_f32 v[16:17], v[194:195], v[108:109]
	v_pk_mul_f32 v[6:7], v[192:193], v[118:119]
	v_pk_mul_f32 v[4:5], v[194:195], v[116:117]
	s_nop 0
	v_cvt_pk_bf16_f32 v4, v4, v5
	v_cvt_pk_bf16_f32 v5, v6, v7
	v_cvt_pk_bf16_f32 v6, v16, v17
	v_cvt_pk_bf16_f32 v7, v14, v15
	global_store_dwordx4 v[12:13], v[4:7], off offset:256 sc0 sc1
	v_pk_mul_f32 v[12:13], v[194:195], v[112:113]
	s_nop 0
	v_or_b32_e32 v4, 48, v8
	v_ashrrev_i32_e32 v5, 31, v4
	v_lshlrev_b64 v[4:5], 12, v[4:5]
	v_lshl_add_u64 v[4:5], s[18:19], 0, v[4:5]
	v_lshl_add_u64 v[8:9], v[4:5], 0, v[10:11]
	v_pk_mul_f32 v[6:7], v[192:193], v[122:123]
	v_pk_mul_f32 v[4:5], v[194:195], v[120:121]
	v_pk_mul_f32 v[10:11], v[192:193], v[114:115]
	v_cvt_pk_bf16_f32 v4, v4, v5
	v_cvt_pk_bf16_f32 v5, v6, v7
	v_cvt_pk_bf16_f32 v6, v12, v13
	v_cvt_pk_bf16_f32 v7, v10, v11
	global_store_dwordx4 v[8:9], v[4:7], off sc0 sc1
	v_pk_mul_f32 v[10:11], v[192:193], v[102:103]
; __device__ __forceinline__ unsigned cvt_pk_bf16(float lo, float hi) { f32x2c v = {lo, hi}; bf16x2c b = __builtin_convertvector(v, bf16x2c); return __builtin_bit_cast(unsigned, b); }
;     __device__ __forceinline__ void operator()(const f32x4 (&acc)[2][2][4][2], const Unit& u, int wr, int wc, int fr, int fq) const {
;         const int row0 = u.pm * BM + wr * 64 + fr, col0 = u.pn * BM + wc * 32 + 8 * fq;
; #pragma unroll
;         for (int ai = 0; ai < 2; ++ai)
; #pragma unroll
;             for (int m = 0; m < 4; ++m) { bf16_t* rowp = O + (size_t)(row0 + ai * HALF + m * 16) * ldc + col0;
; #pragma unroll
;                 for (int bj = 0; bj < 2; ++bj) { const f32x4 v0 = acc[ai][bj][m][0] * sc, v1 = acc[ai][bj][m][1] * sc;
;                     u32x4 w; w.x = cvt_pk_bf16(v0[0], v0[1]); w.y = cvt_pk_bf16(v0[2], v0[3]); w.z = cvt_pk_bf16(v1[0], v1[1]); w.w = cvt_pk_bf16(v1[2], v1[3]);
;                     *(u32x4*)(rowp + bj * HALF) = w; } }
	v_pk_mul_f32 v[12:13], v[194:195], v[100:101]
	v_pk_mul_f32 v[6:7], v[192:193], v[106:107]
	v_pk_mul_f32 v[4:5], v[194:195], v[104:105]
	s_nop 0
	v_cvt_pk_bf16_f32 v4, v4, v5
	v_cvt_pk_bf16_f32 v5, v6, v7
	v_cvt_pk_bf16_f32 v6, v12, v13
	v_cvt_pk_bf16_f32 v7, v10, v11
	global_store_dwordx4 v[8:9], v[4:7], off offset:256 sc0 sc1
	v_lshl_add_u64 v[8:9], v[2:3], 0, s[40:41]
	v_pk_mul_f32 v[10:11], v[192:193], v[94:95]
	v_pk_mul_f32 v[6:7], v[192:193], v[98:99]
	v_pk_mul_f32 v[4:5], v[194:195], v[96:97]
	s_mov_b32 s40, 0x80000
	v_pk_mul_f32 v[12:13], v[194:195], v[92:93]
	v_cvt_pk_bf16_f32 v4, v4, v5
	v_cvt_pk_bf16_f32 v5, v6, v7
	v_cvt_pk_bf16_f32 v7, v10, v11
	v_add_co_u32_e32 v10, vcc, s40, v2
	v_cvt_pk_bf16_f32 v6, v12, v13
	s_nop 0
	v_addc_co_u32_e32 v11, vcc, 0, v3, vcc
	global_store_dwordx4 v[10:11], v[4:7], off sc0 sc1
	v_pk_mul_f32 v[10:11], v[192:193], v[78:79]
	v_pk_mul_f32 v[12:13], v[194:195], v[76:77]
	v_pk_mul_f32 v[6:7], v[192:193], v[86:87]
	v_pk_mul_f32 v[4:5], v[194:195], v[84:85]
	s_mov_b64 s[40:41], 0x90000
	v_cvt_pk_bf16_f32 v4, v4, v5
	v_cvt_pk_bf16_f32 v5, v6, v7
	v_cvt_pk_bf16_f32 v6, v12, v13
	v_cvt_pk_bf16_f32 v7, v10, v11
	global_store_dwordx4 v[8:9], v[4:7], off offset:256 sc0 sc1
	v_lshl_add_u64 v[8:9], v[2:3], 0, s[40:41]
	v_pk_mul_f32 v[10:11], v[192:193], v[82:83]
	v_pk_mul_f32 v[6:7], v[192:193], v[90:91]
	v_pk_mul_f32 v[4:5], v[194:195], v[88:89]
	s_mov_b32 s40, 0x90000
	v_pk_mul_f32 v[12:13], v[194:195], v[80:81]
	v_cvt_pk_bf16_f32 v4, v4, v5
	v_cvt_pk_bf16_f32 v5, v6, v7
	v_cvt_pk_bf16_f32 v7, v10, v11
	v_add_co_u32_e32 v10, vcc, s40, v2
	v_cvt_pk_bf16_f32 v6, v12, v13
	s_nop 0
	v_addc_co_u32_e32 v11, vcc, 0, v3, vcc
	global_store_dwordx4 v[10:11], v[4:7], off sc0 sc1
	v_pk_mul_f32 v[10:11], v[192:193], v[62:63]
	v_pk_mul_f32 v[12:13], v[194:195], v[60:61]
	v_pk_mul_f32 v[6:7], v[192:193], v[70:71]
	v_pk_mul_f32 v[4:5], v[194:195], v[68:69]
	s_mov_b64 s[40:41], 0xa0000
	v_cvt_pk_bf16_f32 v4, v4, v5
	v_cvt_pk_bf16_f32 v5, v6, v7
	v_cvt_pk_bf16_f32 v6, v12, v13
	v_cvt_pk_bf16_f32 v7, v10, v11
	global_store_dwordx4 v[8:9], v[4:7], off offset:256 sc0 sc1
	v_lshl_add_u64 v[8:9], v[2:3], 0, s[40:41]
	v_pk_mul_f32 v[10:11], v[192:193], v[66:67]
	v_pk_mul_f32 v[6:7], v[192:193], v[74:75]
	v_pk_mul_f32 v[4:5], v[194:195], v[72:73]
	s_mov_b32 s40, 0xa0000
	v_pk_mul_f32 v[12:13], v[194:195], v[64:65]
	v_cvt_pk_bf16_f32 v4, v4, v5
	v_cvt_pk_bf16_f32 v5, v6, v7
	v_cvt_pk_bf16_f32 v7, v10, v11
	v_add_co_u32_e32 v10, vcc, s40, v2
	v_cvt_pk_bf16_f32 v6, v12, v13
	s_nop 0
	v_addc_co_u32_e32 v11, vcc, 0, v3, vcc
	global_store_dwordx4 v[10:11], v[4:7], off sc0 sc1
	v_pk_mul_f32 v[10:11], v[192:193], v[46:47]
	v_pk_mul_f32 v[12:13], v[194:195], v[44:45]
	v_pk_mul_f32 v[6:7], v[192:193], v[54:55]
	v_pk_mul_f32 v[4:5], v[194:195], v[52:53]
	s_mov_b64 s[40:41], 0xb0000
	v_cvt_pk_bf16_f32 v4, v4, v5
	v_cvt_pk_bf16_f32 v5, v6, v7
	v_cvt_pk_bf16_f32 v6, v12, v13
	v_cvt_pk_bf16_f32 v7, v10, v11
	global_store_dwordx4 v[8:9], v[4:7], off offset:256 sc0 sc1
	v_lshl_add_u64 v[8:9], v[2:3], 0, s[40:41]
	s_mov_b32 s40, 0xb0000
	v_pk_mul_f32 v[6:7], v[192:193], v[58:59]
	v_pk_mul_f32 v[4:5], v[194:195], v[56:57]
	v_pk_mul_f32 v[10:11], v[192:193], v[50:51]
	v_pk_mul_f32 v[12:13], v[194:195], v[48:49]
	v_add_co_u32_e32 v2, vcc, s40, v2
	v_cvt_pk_bf16_f32 v4, v4, v5
	v_cvt_pk_bf16_f32 v5, v6, v7
	v_cvt_pk_bf16_f32 v6, v12, v13
	v_cvt_pk_bf16_f32 v7, v10, v11
	v_addc_co_u32_e32 v3, vcc, 0, v3, vcc
	global_store_dwordx4 v[2:3], v[4:7], off sc0 sc1
	v_pk_mul_f32 v[2:3], v[194:195], v[40:41]
	v_pk_mul_f32 v[10:11], v[194:195], v[36:37]
	v_pk_mul_f32 v[4:5], v[192:193], v[42:43]
	v_pk_mul_f32 v[6:7], v[192:193], v[38:39]
	v_cvt_pk_bf16_f32 v2, v2, v3
	v_cvt_pk_bf16_f32 v3, v4, v5
	v_cvt_pk_bf16_f32 v4, v10, v11
	v_cvt_pk_bf16_f32 v5, v6, v7
	s_and_b64 vcc, exec, s[38:39]
	s_mov_b64 s[38:39], -1
	global_store_dwordx4 v[8:9], v[2:5], off offset:256 sc0 sc1
	s_cbranch_vccnz .LBB0_714
	s_andn2_b64 vcc, exec, s[26:27]
	s_cbranch_vccnz .LBB0_713
	s_barrier
	s_branch .LBB0_713

;     __device__ __forceinline__ const char* pa(const Gemm& g, const Unit& u, size_t tstep) const { return (const char*)g.A + (size_t)u.pm * tstep; }
;     __device__ __forceinline__ const char* pb(const Gemm& g, const Unit& u, size_t tstep) const { return (const char*)g.Bt + (size_t)u.pn * tstep; }
;     __device__ __forceinline__ const char* pa(const Gemm& g, const Unit& u, size_t tstep) const { return (const char*)g.A + (size_t)(u.pn >> 1) * 512 + (size_t)u.pm * tstep; }
;     __device__ __forceinline__ bool next(int i, Unit& u) const { const int ti = i / 3, sg = i - 3 * ti; if (!StaticOrder::next(ti, u)) return false; u.seg = sg; return true; }
; #define PG8_WAIT_V(n) asm volatile("s_waitcnt vmcnt(" #n ")" ::: "memory")
; #define PG8_BAR __builtin_amdgcn_s_barrier()
;     ...
;     for (int i = 0; i < 2; ++i) { int R, C; stage_rc(tid * 16 + i * 8192, R, C); const int Rb = Epi::PERM ? ((R & ~31) + perm32(R & 31)) : R;
;         voffA[i] = (unsigned)(R * (LDA ? LDA : K) + C) * 2u; voffB[i] = (unsigned)(Rb * K + C) * 2u; }
;     const size_t kstep = (size_t)(BK * 2);
;     const size_t hstepB = (size_t)HALF * K * 2, hstepA = LDA ? (size_t)HALF * LDA * 2 : hstepB;
;     const size_t tstepA = 2 * hstepA, tstepB = 2 * hstepB;
;     const unsigned ldsw = (unsigned)wid * 1024u;
;     const int aoff = lds_byte(wr * 64 + fr, fq * 8), boff = lds_byte(wc * 32 + fr, fq * 8);
;     ...
;     Unit cur, nxt; int ui = 0;
;     if (!S.next(0, cur)) return;
;     f32x4 acc[2][2][4][2];
; #pragma unroll
;     for (int a = 0; a < 2; ++a)
; #pragma unroll
;         for (int b = 0; b < 2; ++b)
; #pragma unroll
;             for (int m = 0; m < 4; ++m)
; #pragma unroll
;                 for (int n = 0; n < 2; ++n) acc[a][b][m][n] = (f32x4){0.f, 0.f, 0.f, 0.f};
;     bf16x8 At[4][2], B0[2][2], B1[2][2];
;     const char* cA = S.pa(g, cur, tstepA); const char* cB = S.pb(g, cur, tstepB);
;     S.a_ready(cur);
;     if constexpr (SP2) {
;         PG8_STAGE(PG8_SB(0, 0), cB, voffB); PG8_STAGE(PG8_SB(0, 1), cB + hstepB, voffB); PG8_STAGE(PG8_SA(0, 0), cA, voffA); PG8_STAGE(PG8_SA(0, 1), cA + hstepA, voffA);
;         if (wr == 1) PG8_BAR;
;         PG8_WAIT_V(2); PG8_BAR;
;         PG8_STAGE(PG8_SB(1, 0), cB + kstep, voffB); PG8_STAGE(PG8_SA(1, 0), cA + kstep, voffA); PG8_STAGE(PG8_SB(1, 1), cB + hstepB + kstep, voffB);
;         PG8_WAIT_V(6); PG8_BAR;
.LBB0_917:
	s_lshl_b64 s[28:29], s[24:25], 2
	s_add_u32 s28, s44, s28
	v_lshrrev_b32_e32 v18, 1, v16
	s_addc_u32 s29, s45, s29
	v_and_b32_e32 v18, 24, v18
	s_add_u32 s28, s28, 0x100000
	v_and_b32_e32 v17, 15, v16
	v_lshlrev_b32_e32 v19, 1, v18
	v_lshlrev_b32_e32 v16, 2, v16
	s_addc_u32 s29, s29, 0
	v_lshl_or_b32 v152, s15, 6, v17
	v_lshl_or_b32 v17, v17, 6, v19
	s_lshl_b32 s15, s15, 13
	v_and_b32_e32 v16, 32, v16
	v_bitop3_b32 v19, v17, s15, v16 bitop3:0xde
	s_lshl_b32 s15, s30, 5
	s_and_b32 s15, s15, 0x60
	s_add_i32 m0, s10, 0x18000
	v_lshl_add_u64 v[8:9], v[8:9], 0, s[22:23]
	s_lshl_b32 s30, s15, 7
	s_waitcnt vmcnt(2)
	s_barrier
	global_load_lds_dwordx4 v[8:9], off
	v_lshl_add_u64 v[6:7], v[6:7], 0, s[22:23]
	s_add_i32 m0, s10, 0x1a000
	s_add_i32 s55, s10, 0x8000
	s_add_i32 s66, s10, 0xa000
	v_bitop3_b32 v153, v17, s30, v16 bitop3:0xde
	global_load_lds_dwordx4 v[6:7], off
	v_lshl_add_u64 v[2:3], v[2:3], 0, s[22:23]
	s_mov_b32 m0, s55
	s_add_u32 s30, s56, 0x80080
	global_load_lds_dwordx4 v[2:3], off
	v_lshl_add_u64 v[2:3], v[4:5], 0, s[22:23]
	s_mov_b32 m0, s66
	s_addc_u32 s31, s57, 0
	global_load_lds_dwordx4 v[2:3], off
	s_add_i32 m0, s10, 0x1c000
	v_lshl_add_u64 v[2:3], s[30:31], 0, v[142:143]
	global_load_lds_dwordx4 v[2:3], off
	v_lshl_add_u64 v[2:3], s[30:31], 0, v[146:147]
	s_add_i32 m0, s10, 0x1e000
	v_and_b32_e32 v4, 1, v10
	global_load_lds_dwordx4 v[2:3], off
	v_lshlrev_b32_e32 v3, 15, v10
	v_and_b32_e32 v3, 0xffff0000, v3
	v_lshl_add_u32 v3, v11, 12, v3
	v_lshl_or_b32 v3, v4, 6, v3
	v_lshl_add_u32 v148, v12, 1, v3
	v_lshlrev_b32_e32 v3, 15, v13
	v_and_b32_e32 v3, 0xffff0000, v3
	s_waitcnt vmcnt(6)
	v_lshl_add_u32 v3, v14, 12, v3
	v_and_b32_e32 v4, 1, v13
	s_cmpk_lt_u32 s6, 0x100
	v_or_b32_e32 v2, s15, v18
	v_lshl_or_b32 v3, v4, 6, v3
	s_cselect_b64 s[30:31], -1, 0
	v_or_b32_e32 v154, 0xffffe800, v2
	s_ashr_i32 s67, s64, 31
	s_ashr_i32 s74, s65, 31
	v_mov_b32_e32 v149, v35
	v_lshl_add_u32 v150, v15, 1, v3
	v_mov_b32_e32 v151, v35
	s_mov_b32 s75, 0
	v_add_u32_e32 v155, 0, v19
	v_lshlrev_b32_e32 v34, 1, v2
	s_barrier
	v_add_u32_e32 v226, 0x10000, v153
	ds_read_b128 v[206:209], v155 offset:1024
	ds_read_b128 v[210:213], v155 offset:2048
	ds_read_b128 v[214:217], v155 offset:3072
	ds_read_b128 v[218:221], v155 offset:4096
	ds_read_b128 v[222:225], v155 offset:5120
	ds_read_b128 v[234:237], v155 offset:6144
	ds_read_b128 v[238:241], v155 offset:7168
	s_branch .LBB0_920

;     __device__ __forceinline__ const char* pa(const Gemm& g, const Unit& u, size_t tstep) const { return (const char*)g.A + (size_t)u.pm * tstep; }
;     __device__ __forceinline__ const char* pb(const Gemm& g, const Unit& u, size_t tstep) const { return (const char*)g.Bt + (size_t)u.pn * tstep; }
;     __device__ __forceinline__ const char* pa(const Gemm& g, const Unit& u, size_t tstep) const { return (const char*)g.A + (size_t)(u.pn >> 1) * 512 + (size_t)u.pm * tstep; }
;     __device__ __forceinline__ bool next(int i, Unit& u) const { const int ti = i / 3, sg = i - 3 * ti; if (!StaticOrder::next(ti, u)) return false; u.seg = sg; return true; }
;     __device__ __forceinline__ const char* pa(const Gemm& g, const Unit& u, size_t tstep) const { return (const char*)g.A + (size_t)u.seg * astride + (size_t)u.pm * tstep; }
;     __device__ __forceinline__ const char* pb(const Gemm& g, const Unit& u, size_t tstep) const { return (const char*)g.Bt + (size_t)u.seg * bstride + (size_t)u.pn * tstep; }
; #define PG8_LDA(dst, b, h) do { _Pragma("unroll") for (int m = 0; m < 4; ++m) _Pragma("unroll") for (int k = 0; k < 2; ++k) dst[m][k] = *(const PG8_LAS bf16x8*)(lds + PG8_SA(b, h) + aoff + m * 2048 + k * 1024); } while (0)
;     ...
;         const bool has_next = S.next(ui + 1, nxt);
;         const char* nA = has_next ? S.pa(g, nxt, tstepA) : cA; const char* nB = has_next ? S.pb(g, nxt, tstepB) : cB;
;         for (int t = 0; t < nt; t += 2) {
;             const bool last = (t == nt - 2);
;             const char* a1 = cA + (size_t)(t + 1) * kstep;
;             const char* a2 = last ? nA : cA + (size_t)(t + 2) * kstep; const char* b2 = last ? nB : cB + (size_t)(t + 2) * kstep;
;             const char* a3 = a2 + kstep; const char* b3 = b2 + kstep;
;             if (last && has_next) S.a_ready(nxt);
;             if constexpr (SP2) {
;             PG8_LDB(B0, 0, 0); PG8_LDB(B1, 0, 1); PG8_SCHED; PG8_LDA(At, 0, 0); PG8_STAGE(PG8_SA(1, 1), a1 + hstepA, voffA);
;             PG8_WAIT_V(8); PG8_WAIT_L(0); PG8_BAR; PG8_MMA(0, 0, At, B0); PG8_MMA(0, 1, At, B1); PG8_BAR; PG8_SCHED;
;             PG8_LDA(At, 0, 1); PG8_STAGE(PG8_SB(0, 0), b2, voffB); PG8_STAGE(PG8_SB(0, 1), b2 + hstepB, voffB); PG8_STAGE(PG8_SA(0, 0), a2, voffA);
;             PG8_WAIT_V(8); PG8_WAIT_L(0); PG8_BAR; PG8_MMA(1, 0, At, B0); PG8_MMA(1, 1, At, B1); PG8_BAR; PG8_SCHED;
.LBB0_922:
	s_ashr_i32 s47, s46, 31
	s_lshl_b64 s[34:35], s[46:47], 20
	s_add_u32 s48, s60, s34
	s_addc_u32 s49, s61, s35
	s_and_b64 s[34:35], s[38:39], exec
	s_cselect_b32 s6, s49, s53
	s_cselect_b32 s15, s48, s52
	s_ashr_i32 s37, s36, 31
	s_lshl_b64 s[34:35], s[36:37], 20
	s_add_u32 s50, s62, s34
	s_addc_u32 s51, s63, s35
	s_and_b64 s[34:35], s[38:39], exec
	s_cselect_b32 s34, s51, s57
	s_cselect_b32 s35, s50, s56
	s_add_u32 s52, s52, 0x80080
	s_addc_u32 s53, s53, 0
	s_add_u32 s37, s56, 0x100
	s_addc_u32 s41, s57, 0
	s_mov_b32 s47, -2
	v_add_u32_e32 v226, 0x10000, v153
	s_add_u32 s56, s52, 0xfff80080
	s_addc_u32 s57, s53, -1
	s_add_i32 s68, 0, 0x10000
	s_cmp_eq_u32 s47, 28
	s_cselect_b32 s59, s6, s57
	s_cselect_b32 s58, s15, s56
	s_cselect_b32 s57, s34, s41
	s_cselect_b32 s56, s35, s37
	s_add_i32 s76, 0, 0x14000
	s_waitcnt vmcnt(0)
	ds_read_b128 v[132:135], v226
	ds_read_b128 v[136:139], v226 offset:1024
	ds_read_b128 v[156:159], v226 offset:2048
	ds_read_b128 v[160:163], v226 offset:3072
	ds_read_b128 v[186:189], v226 offset:16384
	ds_read_b128 v[190:193], v226 offset:17408
	ds_read_b128 v[194:197], v226 offset:18432
	ds_read_b128 v[198:201], v226 offset:19456
	s_add_i32 m0, s10, 0xc000
	ds_read_b128 v[202:205], v155
	global_load_lds_dwordx4 v148, s[52:53]
	s_add_i32 m0, s10, 0xe000
	s_nop 0
	global_load_lds_dwordx4 v150, s[52:53]
	s_waitcnt vmcnt(8)
	s_waitcnt lgkmcnt(0)
	s_barrier
	v_mfma_f32_16x16x32_bf16 v[128:131], v[132:135], v[202:205], 0
	v_mfma_f32_16x16x32_bf16 v[124:127], v[156:159], v[202:205], 0
	v_mfma_f32_16x16x32_bf16 v[112:115], v[132:135], v[210:213], 0
	v_mfma_f32_16x16x32_bf16 v[108:111], v[156:159], v[210:213], 0
	v_mfma_f32_16x16x32_bf16 v[96:99], v[132:135], v[218:221], 0
	v_mfma_f32_16x16x32_bf16 v[92:95], v[156:159], v[218:221], 0
	v_mfma_f32_16x16x32_bf16 v[80:83], v[132:135], v[234:237], 0
	v_mfma_f32_16x16x32_bf16 v[76:79], v[156:159], v[234:237], 0
	v_mfma_f32_16x16x32_bf16 v[128:131], v[136:139], v[206:209], v[128:131]
	v_mfma_f32_16x16x32_bf16 v[124:127], v[160:163], v[206:209], v[124:127]
	v_mfma_f32_16x16x32_bf16 v[112:115], v[136:139], v[214:217], v[112:115]
	v_mfma_f32_16x16x32_bf16 v[108:111], v[160:163], v[214:217], v[108:111]
	v_mfma_f32_16x16x32_bf16 v[96:99], v[136:139], v[222:225], v[96:99]
	v_mfma_f32_16x16x32_bf16 v[92:95], v[160:163], v[222:225], v[92:95]
	v_mfma_f32_16x16x32_bf16 v[80:83], v[136:139], v[238:241], v[80:83]
	v_mfma_f32_16x16x32_bf16 v[76:79], v[160:163], v[238:241], v[76:79]
	v_mfma_f32_16x16x32_bf16 v[120:123], v[186:189], v[202:205], 0
	v_mfma_f32_16x16x32_bf16 v[116:119], v[194:197], v[202:205], 0
	v_mfma_f32_16x16x32_bf16 v[104:107], v[186:189], v[210:213], 0
	v_mfma_f32_16x16x32_bf16 v[100:103], v[194:197], v[210:213], 0
	v_mfma_f32_16x16x32_bf16 v[88:91], v[186:189], v[218:221], 0
	v_mfma_f32_16x16x32_bf16 v[84:87], v[194:197], v[218:221], 0
	v_mfma_f32_16x16x32_bf16 v[72:75], v[186:189], v[234:237], 0
	v_mfma_f32_16x16x32_bf16 v[68:71], v[194:197], v[234:237], 0
	v_mfma_f32_16x16x32_bf16 v[120:123], v[190:193], v[206:209], v[120:123]
	v_mfma_f32_16x16x32_bf16 v[116:119], v[198:201], v[206:209], v[116:119]
	v_mfma_f32_16x16x32_bf16 v[104:107], v[190:193], v[214:217], v[104:107]
	v_mfma_f32_16x16x32_bf16 v[100:103], v[198:201], v[214:217], v[100:103]
	v_mfma_f32_16x16x32_bf16 v[88:91], v[190:193], v[222:225], v[88:91]
	v_mfma_f32_16x16x32_bf16 v[84:87], v[198:201], v[222:225], v[84:87]
	v_mfma_f32_16x16x32_bf16 v[72:75], v[190:193], v[238:241], v[72:75]
	v_mfma_f32_16x16x32_bf16 v[68:71], v[198:201], v[238:241], v[68:71]
	s_barrier
	s_add_i32 s68, s68, s9
	s_mov_b32 m0, s68
	ds_read_b128 v[202:205], v155 offset:16384
	ds_read_b128 v[206:209], v155 offset:17408
	ds_read_b128 v[210:213], v155 offset:18432
	ds_read_b128 v[214:217], v155 offset:19456
	ds_read_b128 v[218:221], v155 offset:20480
	ds_read_b128 v[222:225], v155 offset:21504
	ds_read_b128 v[234:237], v155 offset:22528
	ds_read_b128 v[238:241], v155 offset:23552
	global_load_lds_dwordx4 v142, s[56:57]
	s_add_i32 m0, s68, 0x2000
	s_add_u32 s70, s56, 0x80000
	s_addc_u32 s71, s57, 0
	s_add_i32 s68, s76, s9
	global_load_lds_dwordx4 v146, s[56:57]
	s_mov_b32 m0, s68
	s_add_u32 s98, s58, 0x80
	s_addc_u32 s99, s59, 0
	global_load_lds_dwordx4 v142, s[70:71]
	s_add_i32 m0, s68, 0x2000
	s_nop 0
	global_load_lds_dwordx4 v146, s[70:71]
	s_mov_b32 m0, s10
	s_nop 0
	global_load_lds_dwordx4 v140, s[58:59]
	s_mov_b32 m0, s11
	s_nop 0
	global_load_lds_dwordx4 v144, s[58:59]
	s_waitcnt vmcnt(8)
	s_waitcnt lgkmcnt(0)
	s_barrier
	v_mfma_f32_16x16x32_bf16 v[64:67], v[132:135], v[202:205], 0
	v_mfma_f32_16x16x32_bf16 v[60:63], v[156:159], v[202:205], 0
	v_mfma_f32_16x16x32_bf16 v[48:51], v[132:135], v[210:213], 0
	v_mfma_f32_16x16x32_bf16 v[44:47], v[156:159], v[210:213], 0
	v_mfma_f32_16x16x32_bf16 v[30:33], v[132:135], v[218:221], 0
	v_mfma_f32_16x16x32_bf16 v[26:29], v[156:159], v[218:221], 0
	v_mfma_f32_16x16x32_bf16 v[14:17], v[132:135], v[234:237], 0
	v_mfma_f32_16x16x32_bf16 v[10:13], v[156:159], v[234:237], 0
	v_mfma_f32_16x16x32_bf16 v[64:67], v[136:139], v[206:209], v[64:67]
	v_mfma_f32_16x16x32_bf16 v[60:63], v[160:163], v[206:209], v[60:63]
	v_mfma_f32_16x16x32_bf16 v[48:51], v[136:139], v[214:217], v[48:51]
	v_mfma_f32_16x16x32_bf16 v[44:47], v[160:163], v[214:217], v[44:47]
	v_mfma_f32_16x16x32_bf16 v[30:33], v[136:139], v[222:225], v[30:33]
	v_mfma_f32_16x16x32_bf16 v[26:29], v[160:163], v[222:225], v[26:29]
	v_mfma_f32_16x16x32_bf16 v[14:17], v[136:139], v[238:241], v[14:17]
	v_mfma_f32_16x16x32_bf16 v[10:13], v[160:163], v[238:241], v[10:13]
	v_mfma_f32_16x16x32_bf16 v[56:59], v[186:189], v[202:205], 0
	v_mfma_f32_16x16x32_bf16 v[52:55], v[194:197], v[202:205], 0
	v_mfma_f32_16x16x32_bf16 v[40:43], v[186:189], v[210:213], 0
	v_mfma_f32_16x16x32_bf16 v[36:39], v[194:197], v[210:213], 0
	v_mfma_f32_16x16x32_bf16 v[22:25], v[186:189], v[218:221], 0
	v_mfma_f32_16x16x32_bf16 v[18:21], v[194:197], v[218:221], 0
	v_mfma_f32_16x16x32_bf16 v[6:9], v[186:189], v[234:237], 0
	v_mfma_f32_16x16x32_bf16 v[2:5], v[194:197], v[234:237], 0
	v_mfma_f32_16x16x32_bf16 v[56:59], v[190:193], v[206:209], v[56:59]
	v_mfma_f32_16x16x32_bf16 v[52:55], v[198:201], v[206:209], v[52:55]
	v_mfma_f32_16x16x32_bf16 v[40:43], v[190:193], v[214:217], v[40:43]
	v_mfma_f32_16x16x32_bf16 v[36:39], v[198:201], v[214:217], v[36:39]
	v_mfma_f32_16x16x32_bf16 v[22:25], v[190:193], v[222:225], v[22:25]
	v_mfma_f32_16x16x32_bf16 v[18:21], v[198:201], v[222:225], v[18:21]
	v_mfma_f32_16x16x32_bf16 v[6:9], v[190:193], v[238:241], v[6:9]
	v_mfma_f32_16x16x32_bf16 v[2:5], v[198:201], v[238:241], v[2:5]
	s_barrier
	s_branch .Lpeel_mid_923
	.p2align	6

;     __device__ __forceinline__ void operator()(const f32x4 (&acc)[2][2][4][2], const Unit& u, int wr, int wc, int fr, int fq) const {
;         const int row0 = u.pm * BM + wr * 64 + fr, colt = wc * 32 + 8 * fq;
;         const int kind = (u.pn == 8 || u.pn == 9) ? 1 : ((u.pn >= 20 && u.pn < 24) ? 2 : ((u.pn >= 24 && u.pn < 28) ? 3 : 0));
;         float lbv[2][8];
; #pragma unroll
;         for (int bj = 0; bj < 2; ++bj)
; #pragma unroll
;             for (int k = 0; k < 8; ++k) lbv[bj][k] = kind == 3 ? lb[(u.pn - 24) * BM + bj * HALF + colt + k] : 0.f;
.LBB0_926:
	s_and_b32 s6, s40, -2
	s_and_b32 s15, s40, -4
	s_cmp_eq_u32 s15, 24
	s_cselect_b32 s34, 3, 0
	s_cmp_lg_u32 s15, 20
	s_cselect_b32 s15, s34, 2
	s_cmp_lg_u32 s6, 8
	ds_read_b128 v[206:209], v155 offset:1024
	ds_read_b128 v[210:213], v155 offset:2048
	ds_read_b128 v[214:217], v155 offset:3072
	ds_read_b128 v[218:221], v155 offset:4096
	ds_read_b128 v[222:225], v155 offset:5120
	ds_read_b128 v[234:237], v155 offset:6144
	ds_read_b128 v[238:241], v155 offset:7168
	s_cselect_b32 s37, s15, 1
	s_cmp_eq_u32 s37, 3
	s_cselect_b64 s[56:57], -1, 0
	s_lshl_b32 s52, s40, 8
	v_add_u32_e32 v132, s52, v154
	s_cmp_lg_u32 s37, 3
	v_mov_b32_e32 v190, 0
	v_ashrrev_i32_e32 v133, 31, v132
	v_mov_b32_e32 v192, 0
	s_cbranch_scc1 .LBB0_928
	v_lshl_add_u64 v[134:135], v[132:133], 2, s[28:29]
	global_load_dword v192, v[134:135], off

;     __device__ __forceinline__ const char* pa(const Gemm& g, const Unit& u, size_t tstep) const { return (const char*)g.A + (size_t)u.pm * tstep; }
;     __device__ __forceinline__ const char* pb(const Gemm& g, const Unit& u, size_t tstep) const { return (const char*)g.Bt + (size_t)u.pn * tstep; }
;     __device__ __forceinline__ const char* pa(const Gemm& g, const Unit& u, size_t tstep) const { return (const char*)g.A + (size_t)(u.pn >> 1) * 512 + (size_t)u.pm * tstep; }
; #define PG8_WAIT_V(n) asm volatile("s_waitcnt vmcnt(" #n ")" ::: "memory")
; #define PG8_BAR __builtin_amdgcn_s_barrier()
;     ...
;     for (int i = 0; i < 2; ++i) { int R, C; stage_rc(tid * 16 + i * 8192, R, C); const int Rb = Epi::PERM ? ((R & ~31) + perm32(R & 31)) : R;
;         voffA[i] = (unsigned)(R * (LDA ? LDA : K) + C) * 2u; voffB[i] = (unsigned)(Rb * K + C) * 2u; }
;     const size_t kstep = (size_t)(BK * 2);
;     const size_t hstepB = (size_t)HALF * K * 2, hstepA = LDA ? (size_t)HALF * LDA * 2 : hstepB;
;     const size_t tstepA = 2 * hstepA, tstepB = 2 * hstepB;
;     const unsigned ldsw = (unsigned)wid * 1024u;
;     const int aoff = lds_byte(wr * 64 + fr, fq * 8), boff = lds_byte(wc * 32 + fr, fq * 8);
;     ...
;     Unit cur, nxt; int ui = 0;
;     if (!S.next(0, cur)) return;
;     f32x4 acc[2][2][4][2];
; #pragma unroll
;     for (int a = 0; a < 2; ++a)
; #pragma unroll
;         for (int b = 0; b < 2; ++b)
; #pragma unroll
;             for (int m = 0; m < 4; ++m)
; #pragma unroll
;                 for (int n = 0; n < 2; ++n) acc[a][b][m][n] = (f32x4){0.f, 0.f, 0.f, 0.f};
;     bf16x8 At[4][2], B0[2][2], B1[2][2];
;     const char* cA = S.pa(g, cur, tstepA); const char* cB = S.pb(g, cur, tstepB);
;     S.a_ready(cur);
;     if constexpr (SP2) {
;         PG8_STAGE(PG8_SB(0, 0), cB, voffB); PG8_STAGE(PG8_SB(0, 1), cB + hstepB, voffB); PG8_STAGE(PG8_SA(0, 0), cA, voffA); PG8_STAGE(PG8_SA(0, 1), cA + hstepA, voffA);
;         if (wr == 1) PG8_BAR;
;         PG8_WAIT_V(2); PG8_BAR;
;         PG8_STAGE(PG8_SB(1, 0), cB + kstep, voffB); PG8_STAGE(PG8_SA(1, 0), cA + kstep, voffA); PG8_STAGE(PG8_SB(1, 1), cB + hstepB + kstep, voffB);
;         PG8_WAIT_V(6); PG8_BAR;
; __global__ void __launch_bounds__(NWAVES * 64, 2) fwd_kernel(Args args_unused) {
;     ...
;                   const float sc = 1.0f / (h8_scale(A->in[6] + (size_t)l * D, F2.lane) * wscale(ws, l));
.LBB0_1127:
	s_waitcnt lgkmcnt(0)
	v_max_f32_e32 v11, v11, v11
	v_max_f32_e32 v10, v10, v10
	v_max_f32_e32 v10, v10, v11
	v_mul_f32_e32 v10, 0x423504f3, v10
	v_max_f32_e32 v10, 0xda24260, v10
	s_mov_b32 s31, 0x43dc0000
	s_sext_i32_i16 s49, s26
	v_div_scale_f32 v11, s[26:27], v10, v10, s31
	v_rcp_f32_e32 v20, v11
	v_lshl_add_u64 v[8:9], v[8:9], 0, s[22:23]
	s_waitcnt vmcnt(2)
	s_barrier
	v_fma_f32 v21, -v11, v20, 1.0
	v_fmac_f32_e32 v20, v21, v20
	v_div_scale_f32 v21, vcc, s31, v10, s31
	v_mul_f32_e32 v22, v21, v20
	v_fma_f32 v23, -v11, v22, v21
	v_fmac_f32_e32 v22, v23, v20
	v_fma_f32 v11, -v11, v22, v21
	v_div_fmas_f32 v11, v11, v20, v22
	v_div_fixup_f32 v10, v11, v10, s31
	v_min_f32_e32 v10, 0x5368d4a5, v10
	v_and_b32_e32 v10, 0x7f800000, v10
	v_mul_f32_e32 v10, v19, v10
	v_div_scale_f32 v11, s[26:27], v10, v10, 1.0
	v_rcp_f32_e32 v19, v11
	s_add_u32 s26, s44, 0x54c00000
	s_addc_u32 s27, s45, 0
	s_lshl_b32 s29, s29, 5
	v_fma_f32 v20, -v11, v19, 1.0
	v_fmac_f32_e32 v19, v20, v19
	v_div_scale_f32 v20, vcc, 1.0, v10, 1.0
	v_mul_f32_e32 v21, v20, v19
	v_fma_f32 v22, -v11, v21, v20
	v_fmac_f32_e32 v21, v22, v19
	v_fma_f32 v11, -v11, v21, v20
	v_div_fmas_f32 v11, v11, v19, v21
	v_div_fixup_f32 v206, v11, v10, 1.0
	v_lshrrev_b32_e32 v11, 1, v18
	v_and_b32_e32 v11, 24, v11
	v_and_b32_e32 v10, 15, v18
	v_lshlrev_b32_e32 v19, 1, v11
	v_lshlrev_b32_e32 v18, 2, v18
	v_lshl_or_b32 v207, s30, 6, v10
	v_lshl_or_b32 v10, v10, 6, v19
	s_lshl_b32 s30, s30, 13
	v_and_b32_e32 v18, 32, v18
	v_bitop3_b32 v19, v10, s30, v18 bitop3:0xde
	s_and_b32 s30, s29, 0x60
	s_add_i32 m0, s57, 0x18000
	s_lshl_b32 s29, s30, 7
	global_load_lds_dwordx4 v[8:9], off
	v_lshl_add_u64 v[6:7], v[6:7], 0, s[22:23]
	s_add_i32 m0, s57, 0x1a000
	s_add_i32 s35, s57, 0x8000
	s_add_i32 s58, s57, 0xa000
	global_load_lds_dwordx4 v[6:7], off
	v_lshl_add_u64 v[2:3], v[2:3], 0, s[22:23]
	s_mov_b32 m0, s35
	s_add_u32 s36, s52, 0x40080
	global_load_lds_dwordx4 v[2:3], off
	v_lshl_add_u64 v[2:3], v[4:5], 0, s[22:23]
	s_mov_b32 m0, s58
	s_addc_u32 s37, s53, 0
	global_load_lds_dwordx4 v[2:3], off
	s_add_i32 m0, s57, 0x1c000
	v_lshl_add_u64 v[2:3], s[36:37], 0, v[34:35]
	global_load_lds_dwordx4 v[2:3], off
	v_lshl_add_u64 v[2:3], s[36:37], 0, v[186:187]
	s_add_i32 m0, s57, 0x1e000
	s_cmpk_lt_u32 s28, 0x100
	global_load_lds_dwordx4 v[2:3], off
	v_lshlrev_b32_e32 v2, 14, v16
	v_and_b32_e32 v2, 0xffff8000, v2
	v_lshl_add_u32 v2, v15, 11, v2
	v_and_b32_e32 v3, 1, v16
	v_lshl_or_b32 v2, v3, 6, v2
	v_lshl_add_u32 v194, v17, 1, v2
	v_lshlrev_b32_e32 v2, 14, v12
	v_and_b32_e32 v2, 0xffff8000, v2
	s_waitcnt vmcnt(6)
	v_lshl_add_u32 v2, v13, 11, v2
	v_and_b32_e32 v3, 1, v12
	v_lshl_or_b32 v2, v3, 6, v2
	v_bitop3_b32 v208, v10, s29, v18 bitop3:0xde
	s_cselect_b64 s[28:29], -1, 0
	v_or_b32_e32 v192, s30, v11
	v_mov_b32_e32 v193, v35
	s_ashr_i32 s59, s10, 31
	v_mov_b32_e32 v195, v35
	v_lshl_add_u32 v196, v14, 1, v2
	v_mov_b32_e32 v197, v35
	s_mov_b32 s66, 0
	v_add_u32_e32 v209, 0, v19
	s_barrier
	v_add_u32_e32 v226, 0x10000, v208
	ds_read_b128 v[10:13], v226 offset:16384
	ds_read_b128 v[198:201], v209
	ds_read_b128 v[202:205], v209 offset:1024
	ds_read_b128 v[210:213], v209 offset:2048
	ds_read_b128 v[214:217], v209 offset:3072
	ds_read_b128 v[218:221], v209 offset:4096
	ds_read_b128 v[222:225], v209 offset:5120
	ds_read_b128 v[234:237], v209 offset:6144
	ds_read_b128 v[238:241], v209 offset:7168
	s_branch .LBB0_1130

; #define PG8_STAGE(bufoff, gbase, voff) do { _Pragma("unroll") for (int _i = 0; _i < 2; ++_i) \
;         __builtin_amdgcn_global_load_lds((const unsigned*)((const char*)(gbase) + (voff)[_i]), (PG8_LAS unsigned*)(lds + (bufoff) + ldsw + _i * 8192), 16, 0, 0); } while (0)
; #define PG8_LDA(dst, b, h) do { _Pragma("unroll") for (int m = 0; m < 4; ++m) _Pragma("unroll") for (int k = 0; k < 2; ++k) dst[m][k] = *(const PG8_LAS bf16x8*)(lds + PG8_SA(b, h) + aoff + m * 2048 + k * 1024); } while (0)
; #define PG8_LDB(dst, b, h) do { _Pragma("unroll") for (int n = 0; n < 2; ++n) _Pragma("unroll") for (int k = 0; k < 2; ++k) dst[n][k] = *(const PG8_LAS bf16x8*)(lds + PG8_SB(b, h) + boff + n * 2048 + k * 1024); } while (0)
; #define PG8_WAIT_V(n) asm volatile("s_waitcnt vmcnt(" #n ")" ::: "memory")
; #define PG8_WAIT_L(n) asm volatile("s_waitcnt lgkmcnt(" #n ")" ::: "memory")
; #define PG8_BAR __builtin_amdgcn_s_barrier()
; #define PG8_SCHED __builtin_amdgcn_sched_barrier(0)
;     ...
;             PG8_LDB(B0, 0, 0); PG8_LDB(B1, 0, 1); PG8_SCHED; PG8_LDA(At, 0, 0); PG8_STAGE(PG8_SA(1, 1), a1 + hstepA, voffA);
;             PG8_WAIT_V(8); PG8_WAIT_L(0); PG8_BAR; PG8_MMA(0, 0, At, B0); PG8_MMA(0, 1, At, B1); PG8_BAR; PG8_SCHED;
;             PG8_LDA(At, 0, 1); PG8_STAGE(PG8_SB(0, 0), b2, voffB); PG8_STAGE(PG8_SB(0, 1), b2 + hstepB, voffB); PG8_STAGE(PG8_SA(0, 0), a2, voffA);
;             PG8_WAIT_V(8); PG8_WAIT_L(0); PG8_BAR; PG8_MMA(1, 0, At, B0); PG8_MMA(1, 1, At, B1); PG8_BAR; PG8_SCHED;
.LBB0_1132:
	s_ashr_i32 s37, s36, 31
	s_lshl_b64 s[40:41], s[36:37], 19
	s_add_u32 s40, s12, s40
	s_addc_u32 s41, s13, s41
	s_and_b64 s[46:47], s[38:39], exec
	s_cselect_b32 s37, s41, s51
	s_cselect_b32 s67, s40, s50
	s_ashr_i32 s31, s30, 31
	s_lshl_b64 s[46:47], s[30:31], 19
	s_add_u32 s46, s7, s46
	s_addc_u32 s47, s8, s47
	s_and_b64 s[54:55], s[38:39], exec
	s_cselect_b32 s31, s47, s53
	s_cselect_b32 s68, s46, s52
	s_add_u32 s50, s50, 0x40080
	s_addc_u32 s51, s51, 0
	s_add_u32 s70, s52, 0x100
	s_addc_u32 s71, s53, 0
	s_mov_b32 s74, -2
	v_add_u32_e32 v226, 0x10000, v208
	s_add_u32 s52, s50, 0xfffc0080
	s_addc_u32 s53, s51, -1
	s_add_i32 s75, 0, 0x10000
	s_cmp_eq_u32 s74, 12
	s_cselect_b32 s55, s37, s53
	s_cselect_b32 s54, s67, s52
	s_cselect_b32 s53, s31, s71
	s_cselect_b32 s52, s68, s70
	s_add_i32 s76, 0, 0x14000
	ds_read_b128 v[26:29], v226
	ds_read_b128 v[30:33], v226 offset:1024
	ds_read_b128 v[18:21], v226 offset:2048
	ds_read_b128 v[22:25], v226 offset:3072
	ds_read_b128 v[14:17], v226 offset:17408
	ds_read_b128 v[2:5], v226 offset:18432
	ds_read_b128 v[6:9], v226 offset:19456
	s_add_i32 m0, s57, 0xc000
	global_load_lds_dwordx4 v194, s[50:51]
	s_add_i32 m0, s57, 0xe000
	s_nop 0
	global_load_lds_dwordx4 v196, s[50:51]
	s_waitcnt vmcnt(8)
	s_waitcnt lgkmcnt(0)
	s_barrier
	v_mfma_f32_16x16x128_f8f6f4 v[160:163], v[26:33], v[198:205], 0
	v_mfma_f32_16x16x128_f8f6f4 v[156:159], v[18:25], v[198:205], 0
	v_mfma_f32_16x16x128_f8f6f4 v[144:147], v[26:33], v[210:217], 0
	v_mfma_f32_16x16x128_f8f6f4 v[140:143], v[18:25], v[210:217], 0
	v_mfma_f32_16x16x128_f8f6f4 v[128:131], v[26:33], v[218:225], 0
	v_mfma_f32_16x16x128_f8f6f4 v[124:127], v[18:25], v[218:225], 0
	v_mfma_f32_16x16x128_f8f6f4 v[112:115], v[26:33], v[234:241], 0
	v_mfma_f32_16x16x128_f8f6f4 v[108:111], v[18:25], v[234:241], 0
	v_mfma_f32_16x16x128_f8f6f4 v[152:155], v[10:17], v[198:205], 0
	v_mfma_f32_16x16x128_f8f6f4 v[148:151], v[2:9], v[198:205], 0
	v_mfma_f32_16x16x128_f8f6f4 v[136:139], v[10:17], v[210:217], 0
	v_mfma_f32_16x16x128_f8f6f4 v[132:135], v[2:9], v[210:217], 0
	v_mfma_f32_16x16x128_f8f6f4 v[120:123], v[10:17], v[218:225], 0
	v_mfma_f32_16x16x128_f8f6f4 v[116:119], v[2:9], v[218:225], 0
	v_mfma_f32_16x16x128_f8f6f4 v[104:107], v[10:17], v[234:241], 0
	v_mfma_f32_16x16x128_f8f6f4 v[100:103], v[2:9], v[234:241], 0
	s_barrier
	s_add_i32 s75, s75, s11
	s_mov_b32 m0, s75
	ds_read_b128 v[210:213], v209 offset:16384
	ds_read_b128 v[214:217], v209 offset:17408
	ds_read_b128 v[218:221], v209 offset:18432
	ds_read_b128 v[222:225], v209 offset:19456
	ds_read_b128 v[234:237], v209 offset:20480
	ds_read_b128 v[238:241], v209 offset:21504
	ds_read_b128 v[242:245], v209 offset:22528
	ds_read_b128 v[246:249], v209 offset:23552
	global_load_lds_dwordx4 v34, s[52:53]
	s_add_i32 m0, s75, 0x2000
	s_add_u32 s78, s52, 0x40000
	s_addc_u32 s79, s53, 0
	s_add_i32 s75, s76, s11
	global_load_lds_dwordx4 v186, s[52:53]
	s_mov_b32 m0, s75
	s_add_u32 s98, s54, 0x80
	s_addc_u32 s99, s55, 0
	global_load_lds_dwordx4 v34, s[78:79]
	s_add_i32 m0, s75, 0x2000
	s_nop 0
	global_load_lds_dwordx4 v186, s[78:79]
	s_mov_b32 m0, s57
	s_nop 0
	global_load_lds_dwordx4 v190, s[54:55]
	s_mov_b32 m0, s6
	s_nop 0
	global_load_lds_dwordx4 v188, s[54:55]
	s_waitcnt vmcnt(8)
	s_waitcnt lgkmcnt(0)
	s_barrier
	v_mfma_f32_16x16x128_f8f6f4 v[96:99], v[26:33], v[210:217], 0
	v_mfma_f32_16x16x128_f8f6f4 v[92:95], v[18:25], v[210:217], 0
	v_mfma_f32_16x16x128_f8f6f4 v[80:83], v[26:33], v[218:225], 0
	v_mfma_f32_16x16x128_f8f6f4 v[76:79], v[18:25], v[218:225], 0
	v_mfma_f32_16x16x128_f8f6f4 v[64:67], v[26:33], v[234:241], 0
	v_mfma_f32_16x16x128_f8f6f4 v[60:63], v[18:25], v[234:241], 0
	v_mfma_f32_16x16x128_f8f6f4 v[48:51], v[26:33], v[242:249], 0
	v_mfma_f32_16x16x128_f8f6f4 v[44:47], v[18:25], v[242:249], 0
	v_mfma_f32_16x16x128_f8f6f4 v[88:91], v[10:17], v[210:217], 0
	v_mfma_f32_16x16x128_f8f6f4 v[84:87], v[2:9], v[210:217], 0
	v_mfma_f32_16x16x128_f8f6f4 v[72:75], v[10:17], v[218:225], 0
	v_mfma_f32_16x16x128_f8f6f4 v[68:71], v[2:9], v[218:225], 0
	v_mfma_f32_16x16x128_f8f6f4 v[56:59], v[10:17], v[234:241], 0
	v_mfma_f32_16x16x128_f8f6f4 v[52:55], v[2:9], v[234:241], 0
	v_mfma_f32_16x16x128_f8f6f4 v[40:43], v[10:17], v[242:249], 0
	v_mfma_f32_16x16x128_f8f6f4 v[36:39], v[2:9], v[242:249], 0
	s_barrier
	s_branch .Lpeel_mid_1133
	.p2align	6

;     __device__ __forceinline__ void operator()(const f32x4 (&acc)[2][2][4][2], const Unit& u, int wr, int wc, int fr, int fq) const {
;         const int row0 = u.pm * BM + wr * 64 + fr, colt = wc * 32 + 8 * fq;
; #pragma unroll
;         for (int ai = 0; ai < 2; ++ai)
; #pragma unroll
;             for (int m = 0; m < 4; ++m) { const size_t row = (size_t)(row0 + ai * HALF + m * 16);
; #pragma unroll
;                 for (int bj = 0; bj < 2; ++bj) { const f32x4 v0 = acc[ai][bj][m][0] * sc, v1 = acc[ai][bj][m][1] * sc; unsigned q[8];
; #pragma unroll
;                     for (int j = 0; j < 4; ++j) { const float s0 = 255.0f * __builtin_amdgcn_rcpf(1.0f + __builtin_amdgcn_exp2f(-1.44269504089f * __builtin_amdgcn_fmed3f(v0[j], -30.f, 30.f))) + 0.5f,
;                                                               s1 = 255.0f * __builtin_amdgcn_rcpf(1.0f + __builtin_amdgcn_exp2f(-1.44269504089f * __builtin_amdgcn_fmed3f(v1[j], -30.f, 30.f))) + 0.5f;
;                         q[j] = (unsigned)__builtin_amdgcn_fmed3f(s0, 1.0f, 255.0f); q[4 + j] = (unsigned)__builtin_amdgcn_fmed3f(s1, 1.0f, 255.0f); }
;                     u32x2 w; w.x = q[0] | (q[1] << 8) | (q[2] << 16) | (q[3] << 24); w.y = q[4] | (q[5] << 8) | (q[6] << 16) | (q[7] << 24);
;                     *(u32x2*)(Q + row * 6144 + u.pn * BM + colt + bj * HALF) = w; } }
.LBB0_1136:
	s_mov_b32 s98, 0xbfb8aa3b
	s_mov_b32 s99, 0xbfb8aa3b
	v_mov_b32_e32 v14, s2
	v_lshl_add_u32 v4, s48, 8, v207
	s_lshl_b32 s48, s49, 8
	v_mov_b64_e32 v[2:3], s[26:27]
	s_ashr_i32 s49, s48, 31
	v_mad_i64_i32 v[8:9], s[50:51], v4, s33, v[2:3]
	v_lshl_add_u64 v[8:9], v[8:9], 0, s[48:49]
	ds_read_b128 v[10:13], v226 offset:16384
	ds_read_b128 v[198:201], v209
	ds_read_b128 v[202:205], v209 offset:1024
	ds_read_b128 v[210:213], v209 offset:2048
	ds_read_b128 v[214:217], v209 offset:3072
	ds_read_b128 v[218:221], v209 offset:4096
	ds_read_b128 v[222:225], v209 offset:5120
	ds_read_b128 v[234:237], v209 offset:6144
	ds_read_b128 v[238:241], v209 offset:7168
	v_lshl_add_u64 v[8:9], v[8:9], 0, v[192:193]
	s_nop 15
	s_nop 15
	v_pk_mul_f32 v[16:17], v[206:207], v[160:161] op_sel_hi:[0,1]
	v_pk_mul_f32 v[18:19], v[206:207], v[162:163] op_sel_hi:[0,1]
	v_pk_mul_f32 v[20:21], v[206:207], v[156:157] op_sel_hi:[0,1]
	v_pk_mul_f32 v[22:23], v[206:207], v[158:159] op_sel_hi:[0,1]
	v_med3_f32 v16, v16, s96, v231
	v_med3_f32 v17, v17, s96, v231
	v_med3_f32 v18, v18, s96, v231
	v_med3_f32 v19, v19, s96, v231
	v_med3_f32 v20, v20, s96, v231
	v_med3_f32 v21, v21, s96, v231
	v_med3_f32 v22, v22, s96, v231
	v_med3_f32 v23, v23, s96, v231
	v_pk_mul_f32 v[16:17], v[16:17], s[98:99]
	v_pk_mul_f32 v[18:19], v[18:19], s[98:99]
	v_pk_mul_f32 v[20:21], v[20:21], s[98:99]
	v_pk_mul_f32 v[22:23], v[22:23], s[98:99]
	v_exp_f32_e32 v16, v16
	v_exp_f32_e32 v17, v17
	v_exp_f32_e32 v18, v18
	v_exp_f32_e32 v19, v19
	v_exp_f32_e32 v20, v20
	v_exp_f32_e32 v21, v21
	v_exp_f32_e32 v22, v22
	v_exp_f32_e32 v23, v23
	v_pk_add_f32 v[16:17], v[16:17], 1.0 op_sel_hi:[1,0]
	v_pk_add_f32 v[18:19], v[18:19], 1.0 op_sel_hi:[1,0]
	v_pk_add_f32 v[20:21], v[20:21], 1.0 op_sel_hi:[1,0]
	v_pk_add_f32 v[22:23], v[22:23], 1.0 op_sel_hi:[1,0]
	v_rcp_f32_e32 v16, v16
	v_rcp_f32_e32 v17, v17
	v_rcp_f32_e32 v18, v18
	v_rcp_f32_e32 v19, v19
	v_rcp_f32_e32 v20, v20
	v_rcp_f32_e32 v21, v21
	v_rcp_f32_e32 v22, v22
	v_rcp_f32_e32 v23, v23
	v_pk_fma_f32 v[16:17], v[16:17], v[14:15], 0.5 op_sel_hi:[1,0,0]
	v_pk_fma_f32 v[18:19], v[18:19], v[14:15], 0.5 op_sel_hi:[1,0,0]
	v_pk_fma_f32 v[20:21], v[20:21], v[14:15], 0.5 op_sel_hi:[1,0,0]
	v_pk_fma_f32 v[22:23], v[22:23], v[14:15], 0.5 op_sel_hi:[1,0,0]
	v_med3_f32 v16, v16, 1.0, v232
	v_med3_f32 v17, v17, 1.0, v232
	v_med3_f32 v18, v18, 1.0, v232
	v_med3_f32 v19, v19, 1.0, v232
	v_med3_f32 v20, v20, 1.0, v232
	v_med3_f32 v21, v21, 1.0, v232
	v_med3_f32 v22, v22, 1.0, v232
	v_med3_f32 v23, v23, 1.0, v232
	v_cvt_u32_f32_e32 v16, v16
	v_cvt_u32_f32_e32 v17, v17
	v_cvt_u32_f32_sdwa v18, v18 dst_sel:WORD_1 dst_unused:UNUSED_PAD src0_sel:DWORD
	v_cvt_u32_f32_sdwa v19, v19 dst_sel:BYTE_3 dst_unused:UNUSED_PAD src0_sel:DWORD
	v_cvt_u32_f32_e32 v20, v20
	v_cvt_u32_f32_e32 v21, v21
	v_cvt_u32_f32_sdwa v22, v22 dst_sel:WORD_1 dst_unused:UNUSED_PAD src0_sel:DWORD
	v_cvt_u32_f32_sdwa v23, v23 dst_sel:BYTE_3 dst_unused:UNUSED_PAD src0_sel:DWORD
	v_lshl_or_b32 v16, v17, 8, v16
	v_lshl_or_b32 v20, v21, 8, v20
	v_or3_b32 v16, v16, v18, v19
	v_or3_b32 v17, v20, v22, v23
	global_store_dwordx2 v[8:9], v[16:17], off
	v_pk_mul_f32 v[24:25], v[206:207], v[152:153] op_sel_hi:[0,1]
	v_pk_mul_f32 v[26:27], v[206:207], v[154:155] op_sel_hi:[0,1]
	v_pk_mul_f32 v[28:29], v[206:207], v[148:149] op_sel_hi:[0,1]
	v_pk_mul_f32 v[30:31], v[206:207], v[150:151] op_sel_hi:[0,1]
	v_med3_f32 v24, v24, s96, v231
	v_med3_f32 v25, v25, s96, v231
	v_med3_f32 v26, v26, s96, v231
	v_med3_f32 v27, v27, s96, v231
	v_med3_f32 v28, v28, s96, v231
	v_med3_f32 v29, v29, s96, v231
	v_med3_f32 v30, v30, s96, v231
	v_med3_f32 v31, v31, s96, v231
	v_pk_mul_f32 v[24:25], v[24:25], s[98:99]
	v_pk_mul_f32 v[26:27], v[26:27], s[98:99]
	v_pk_mul_f32 v[28:29], v[28:29], s[98:99]
	v_pk_mul_f32 v[30:31], v[30:31], s[98:99]
	v_exp_f32_e32 v24, v24
	v_exp_f32_e32 v25, v25
	v_exp_f32_e32 v26, v26
	v_exp_f32_e32 v27, v27
	v_exp_f32_e32 v28, v28
	v_exp_f32_e32 v29, v29
	v_exp_f32_e32 v30, v30
	v_exp_f32_e32 v31, v31
	v_pk_add_f32 v[24:25], v[24:25], 1.0 op_sel_hi:[1,0]
	v_pk_add_f32 v[26:27], v[26:27], 1.0 op_sel_hi:[1,0]
	v_pk_add_f32 v[28:29], v[28:29], 1.0 op_sel_hi:[1,0]
	v_pk_add_f32 v[30:31], v[30:31], 1.0 op_sel_hi:[1,0]
	v_rcp_f32_e32 v24, v24
	v_rcp_f32_e32 v25, v25
	v_rcp_f32_e32 v26, v26
	v_rcp_f32_e32 v27, v27
	v_rcp_f32_e32 v28, v28
	v_rcp_f32_e32 v29, v29
	v_rcp_f32_e32 v30, v30
	v_rcp_f32_e32 v31, v31
	v_pk_fma_f32 v[24:25], v[24:25], v[14:15], 0.5 op_sel_hi:[1,0,0]
	v_pk_fma_f32 v[26:27], v[26:27], v[14:15], 0.5 op_sel_hi:[1,0,0]
	v_pk_fma_f32 v[28:29], v[28:29], v[14:15], 0.5 op_sel_hi:[1,0,0]
	v_pk_fma_f32 v[30:31], v[30:31], v[14:15], 0.5 op_sel_hi:[1,0,0]
	v_med3_f32 v24, v24, 1.0, v232
	v_med3_f32 v25, v25, 1.0, v232
	v_med3_f32 v26, v26, 1.0, v232
	v_med3_f32 v27, v27, 1.0, v232
	v_med3_f32 v28, v28, 1.0, v232
	v_med3_f32 v29, v29, 1.0, v232
	v_med3_f32 v30, v30, 1.0, v232
	v_med3_f32 v31, v31, 1.0, v232
	v_cvt_u32_f32_e32 v24, v24
	v_cvt_u32_f32_e32 v25, v25
	v_cvt_u32_f32_sdwa v26, v26 dst_sel:WORD_1 dst_unused:UNUSED_PAD src0_sel:DWORD
	v_cvt_u32_f32_sdwa v27, v27 dst_sel:BYTE_3 dst_unused:UNUSED_PAD src0_sel:DWORD
	v_cvt_u32_f32_e32 v28, v28
	v_cvt_u32_f32_e32 v29, v29
	v_cvt_u32_f32_sdwa v30, v30 dst_sel:WORD_1 dst_unused:UNUSED_PAD src0_sel:DWORD
	v_cvt_u32_f32_sdwa v31, v31 dst_sel:BYTE_3 dst_unused:UNUSED_PAD src0_sel:DWORD
	v_lshl_or_b32 v24, v25, 8, v24
	v_lshl_or_b32 v28, v29, 8, v28
	v_or3_b32 v24, v24, v26, v27
	v_or3_b32 v25, v28, v30, v31
	global_store_dwordx2 v[8:9], v[24:25], off offset:128
	v_or_b32_e32 v8, 16, v4
	v_mad_i64_i32 v[8:9], s[50:51], v8, s33, v[2:3]
;     __device__ __forceinline__ void operator()(const f32x4 (&acc)[2][2][4][2], const Unit& u, int wr, int wc, int fr, int fq) const {
;     ...
;         for (int ai = 0; ai < 2; ++ai)
; #pragma unroll
;             for (int m = 0; m < 4; ++m) { const size_t row = (size_t)(row0 + ai * HALF + m * 16);
; #pragma unroll
;                 for (int bj = 0; bj < 2; ++bj) { const f32x4 v0 = acc[ai][bj][m][0] * sc, v1 = acc[ai][bj][m][1] * sc; unsigned q[8];
; #pragma unroll
;                     for (int j = 0; j < 4; ++j) { const float s0 = 255.0f * __builtin_amdgcn_rcpf(1.0f + __builtin_amdgcn_exp2f(-1.44269504089f * __builtin_amdgcn_fmed3f(v0[j], -30.f, 30.f))) + 0.5f,
;                                                               s1 = 255.0f * __builtin_amdgcn_rcpf(1.0f + __builtin_amdgcn_exp2f(-1.44269504089f * __builtin_amdgcn_fmed3f(v1[j], -30.f, 30.f))) + 0.5f;
;                         q[j] = (unsigned)__builtin_amdgcn_fmed3f(s0, 1.0f, 255.0f); q[4 + j] = (unsigned)__builtin_amdgcn_fmed3f(s1, 1.0f, 255.0f); }
;                     u32x2 w; w.x = q[0] | (q[1] << 8) | (q[2] << 16) | (q[3] << 24); w.y = q[4] | (q[5] << 8) | (q[6] << 16) | (q[7] << 24);
;                     *(u32x2*)(Q + row * 6144 + u.pn * BM + colt + bj * HALF) = w; } }
	v_lshl_add_u64 v[8:9], v[8:9], 0, s[48:49]
	v_lshl_add_u64 v[8:9], v[8:9], 0, v[192:193]
	v_pk_mul_f32 v[16:17], v[206:207], v[144:145] op_sel_hi:[0,1]
	v_pk_mul_f32 v[18:19], v[206:207], v[146:147] op_sel_hi:[0,1]
	v_pk_mul_f32 v[20:21], v[206:207], v[140:141] op_sel_hi:[0,1]
	v_pk_mul_f32 v[22:23], v[206:207], v[142:143] op_sel_hi:[0,1]
	v_med3_f32 v16, v16, s96, v231
	v_med3_f32 v17, v17, s96, v231
	v_med3_f32 v18, v18, s96, v231
	v_med3_f32 v19, v19, s96, v231
	v_med3_f32 v20, v20, s96, v231
	v_med3_f32 v21, v21, s96, v231
	v_med3_f32 v22, v22, s96, v231
	v_med3_f32 v23, v23, s96, v231
	v_pk_mul_f32 v[16:17], v[16:17], s[98:99]
	v_pk_mul_f32 v[18:19], v[18:19], s[98:99]
	v_pk_mul_f32 v[20:21], v[20:21], s[98:99]
	v_pk_mul_f32 v[22:23], v[22:23], s[98:99]
	v_exp_f32_e32 v16, v16
	v_exp_f32_e32 v17, v17
	v_exp_f32_e32 v18, v18
	v_exp_f32_e32 v19, v19
	v_exp_f32_e32 v20, v20
	v_exp_f32_e32 v21, v21
	v_exp_f32_e32 v22, v22
	v_exp_f32_e32 v23, v23
	v_pk_add_f32 v[16:17], v[16:17], 1.0 op_sel_hi:[1,0]
	v_pk_add_f32 v[18:19], v[18:19], 1.0 op_sel_hi:[1,0]
	v_pk_add_f32 v[20:21], v[20:21], 1.0 op_sel_hi:[1,0]
	v_pk_add_f32 v[22:23], v[22:23], 1.0 op_sel_hi:[1,0]
	v_rcp_f32_e32 v16, v16
	v_rcp_f32_e32 v17, v17
	v_rcp_f32_e32 v18, v18
	v_rcp_f32_e32 v19, v19
	v_rcp_f32_e32 v20, v20
	v_rcp_f32_e32 v21, v21
	v_rcp_f32_e32 v22, v22
	v_rcp_f32_e32 v23, v23
	v_pk_fma_f32 v[16:17], v[16:17], v[14:15], 0.5 op_sel_hi:[1,0,0]
	v_pk_fma_f32 v[18:19], v[18:19], v[14:15], 0.5 op_sel_hi:[1,0,0]
	v_pk_fma_f32 v[20:21], v[20:21], v[14:15], 0.5 op_sel_hi:[1,0,0]
	v_pk_fma_f32 v[22:23], v[22:23], v[14:15], 0.5 op_sel_hi:[1,0,0]
	v_med3_f32 v16, v16, 1.0, v232
	v_med3_f32 v17, v17, 1.0, v232
	v_med3_f32 v18, v18, 1.0, v232
	v_med3_f32 v19, v19, 1.0, v232
	v_med3_f32 v20, v20, 1.0, v232
	v_med3_f32 v21, v21, 1.0, v232
	v_med3_f32 v22, v22, 1.0, v232
	v_med3_f32 v23, v23, 1.0, v232
	v_cvt_u32_f32_e32 v16, v16
	v_cvt_u32_f32_e32 v17, v17
	v_cvt_u32_f32_sdwa v18, v18 dst_sel:WORD_1 dst_unused:UNUSED_PAD src0_sel:DWORD
	v_cvt_u32_f32_sdwa v19, v19 dst_sel:BYTE_3 dst_unused:UNUSED_PAD src0_sel:DWORD
	v_cvt_u32_f32_e32 v20, v20
	v_cvt_u32_f32_e32 v21, v21
	v_cvt_u32_f32_sdwa v22, v22 dst_sel:WORD_1 dst_unused:UNUSED_PAD src0_sel:DWORD
	v_cvt_u32_f32_sdwa v23, v23 dst_sel:BYTE_3 dst_unused:UNUSED_PAD src0_sel:DWORD
	v_lshl_or_b32 v16, v17, 8, v16
	v_lshl_or_b32 v20, v21, 8, v20
	v_or3_b32 v16, v16, v18, v19
	v_or3_b32 v17, v20, v22, v23
	global_store_dwordx2 v[8:9], v[16:17], off
	v_pk_mul_f32 v[24:25], v[206:207], v[136:137] op_sel_hi:[0,1]
	v_pk_mul_f32 v[26:27], v[206:207], v[138:139] op_sel_hi:[0,1]
	v_pk_mul_f32 v[28:29], v[206:207], v[132:133] op_sel_hi:[0,1]
	v_pk_mul_f32 v[30:31], v[206:207], v[134:135] op_sel_hi:[0,1]
	v_med3_f32 v24, v24, s96, v231
	v_med3_f32 v25, v25, s96, v231
	v_med3_f32 v26, v26, s96, v231
	v_med3_f32 v27, v27, s96, v231
	v_med3_f32 v28, v28, s96, v231
	v_med3_f32 v29, v29, s96, v231
	v_med3_f32 v30, v30, s96, v231
	v_med3_f32 v31, v31, s96, v231
	v_pk_mul_f32 v[24:25], v[24:25], s[98:99]
	v_pk_mul_f32 v[26:27], v[26:27], s[98:99]
	v_pk_mul_f32 v[28:29], v[28:29], s[98:99]
	v_pk_mul_f32 v[30:31], v[30:31], s[98:99]
	v_exp_f32_e32 v24, v24
	v_exp_f32_e32 v25, v25
	v_exp_f32_e32 v26, v26
	v_exp_f32_e32 v27, v27
	v_exp_f32_e32 v28, v28
	v_exp_f32_e32 v29, v29
	v_exp_f32_e32 v30, v30
	v_exp_f32_e32 v31, v31
	v_pk_add_f32 v[24:25], v[24:25], 1.0 op_sel_hi:[1,0]
	v_pk_add_f32 v[26:27], v[26:27], 1.0 op_sel_hi:[1,0]
	v_pk_add_f32 v[28:29], v[28:29], 1.0 op_sel_hi:[1,0]
	v_pk_add_f32 v[30:31], v[30:31], 1.0 op_sel_hi:[1,0]
	v_rcp_f32_e32 v24, v24
	v_rcp_f32_e32 v25, v25
	v_rcp_f32_e32 v26, v26
	v_rcp_f32_e32 v27, v27
	v_rcp_f32_e32 v28, v28
	v_rcp_f32_e32 v29, v29
	v_rcp_f32_e32 v30, v30
	v_rcp_f32_e32 v31, v31
	v_pk_fma_f32 v[24:25], v[24:25], v[14:15], 0.5 op_sel_hi:[1,0,0]
	v_pk_fma_f32 v[26:27], v[26:27], v[14:15], 0.5 op_sel_hi:[1,0,0]
	v_pk_fma_f32 v[28:29], v[28:29], v[14:15], 0.5 op_sel_hi:[1,0,0]
	v_pk_fma_f32 v[30:31], v[30:31], v[14:15], 0.5 op_sel_hi:[1,0,0]
	v_med3_f32 v24, v24, 1.0, v232
	v_med3_f32 v25, v25, 1.0, v232
	v_med3_f32 v26, v26, 1.0, v232
	v_med3_f32 v27, v27, 1.0, v232
	v_med3_f32 v28, v28, 1.0, v232
	v_med3_f32 v29, v29, 1.0, v232
	v_med3_f32 v30, v30, 1.0, v232
	v_med3_f32 v31, v31, 1.0, v232
	v_cvt_u32_f32_e32 v24, v24
	v_cvt_u32_f32_e32 v25, v25
	v_cvt_u32_f32_sdwa v26, v26 dst_sel:WORD_1 dst_unused:UNUSED_PAD src0_sel:DWORD
	v_cvt_u32_f32_sdwa v27, v27 dst_sel:BYTE_3 dst_unused:UNUSED_PAD src0_sel:DWORD
	v_cvt_u32_f32_e32 v28, v28
	v_cvt_u32_f32_e32 v29, v29
	v_cvt_u32_f32_sdwa v30, v30 dst_sel:WORD_1 dst_unused:UNUSED_PAD src0_sel:DWORD
	v_cvt_u32_f32_sdwa v31, v31 dst_sel:BYTE_3 dst_unused:UNUSED_PAD src0_sel:DWORD
	v_lshl_or_b32 v24, v25, 8, v24
	v_lshl_or_b32 v28, v29, 8, v28
	v_or3_b32 v24, v24, v26, v27
	v_or3_b32 v25, v28, v30, v31
	global_store_dwordx2 v[8:9], v[24:25], off offset:128
	v_or_b32_e32 v8, 32, v4
	v_mad_i64_i32 v[8:9], s[50:51], v8, s33, v[2:3]
	v_lshl_add_u64 v[8:9], v[8:9], 0, s[48:49]
	v_lshl_add_u64 v[8:9], v[8:9], 0, v[192:193]
	v_pk_mul_f32 v[16:17], v[206:207], v[128:129] op_sel_hi:[0,1]
	v_pk_mul_f32 v[18:19], v[206:207], v[130:131] op_sel_hi:[0,1]
	v_pk_mul_f32 v[20:21], v[206:207], v[124:125] op_sel_hi:[0,1]
	v_pk_mul_f32 v[22:23], v[206:207], v[126:127] op_sel_hi:[0,1]
	v_med3_f32 v16, v16, s96, v231
	v_med3_f32 v17, v17, s96, v231
	v_med3_f32 v18, v18, s96, v231
	v_med3_f32 v19, v19, s96, v231
	v_med3_f32 v20, v20, s96, v231
	v_med3_f32 v21, v21, s96, v231
	v_med3_f32 v22, v22, s96, v231
	v_med3_f32 v23, v23, s96, v231
	v_pk_mul_f32 v[16:17], v[16:17], s[98:99]
;     __device__ __forceinline__ void operator()(const f32x4 (&acc)[2][2][4][2], const Unit& u, int wr, int wc, int fr, int fq) const {
;     ...
;         for (int ai = 0; ai < 2; ++ai)
; #pragma unroll
;             for (int m = 0; m < 4; ++m) { const size_t row = (size_t)(row0 + ai * HALF + m * 16);
; #pragma unroll
;                 for (int bj = 0; bj < 2; ++bj) { const f32x4 v0 = acc[ai][bj][m][0] * sc, v1 = acc[ai][bj][m][1] * sc; unsigned q[8];
; #pragma unroll
;                     for (int j = 0; j < 4; ++j) { const float s0 = 255.0f * __builtin_amdgcn_rcpf(1.0f + __builtin_amdgcn_exp2f(-1.44269504089f * __builtin_amdgcn_fmed3f(v0[j], -30.f, 30.f))) + 0.5f,
;                                                               s1 = 255.0f * __builtin_amdgcn_rcpf(1.0f + __builtin_amdgcn_exp2f(-1.44269504089f * __builtin_amdgcn_fmed3f(v1[j], -30.f, 30.f))) + 0.5f;
;                         q[j] = (unsigned)__builtin_amdgcn_fmed3f(s0, 1.0f, 255.0f); q[4 + j] = (unsigned)__builtin_amdgcn_fmed3f(s1, 1.0f, 255.0f); }
;                     u32x2 w; w.x = q[0] | (q[1] << 8) | (q[2] << 16) | (q[3] << 24); w.y = q[4] | (q[5] << 8) | (q[6] << 16) | (q[7] << 24);
;                     *(u32x2*)(Q + row * 6144 + u.pn * BM + colt + bj * HALF) = w; } }
	v_pk_mul_f32 v[18:19], v[18:19], s[98:99]
	v_pk_mul_f32 v[20:21], v[20:21], s[98:99]
	v_pk_mul_f32 v[22:23], v[22:23], s[98:99]
	v_exp_f32_e32 v16, v16
	v_exp_f32_e32 v17, v17
	v_exp_f32_e32 v18, v18
	v_exp_f32_e32 v19, v19
	v_exp_f32_e32 v20, v20
	v_exp_f32_e32 v21, v21
	v_exp_f32_e32 v22, v22
	v_exp_f32_e32 v23, v23
	v_pk_add_f32 v[16:17], v[16:17], 1.0 op_sel_hi:[1,0]
	v_pk_add_f32 v[18:19], v[18:19], 1.0 op_sel_hi:[1,0]
	v_pk_add_f32 v[20:21], v[20:21], 1.0 op_sel_hi:[1,0]
	v_pk_add_f32 v[22:23], v[22:23], 1.0 op_sel_hi:[1,0]
	v_rcp_f32_e32 v16, v16
	v_rcp_f32_e32 v17, v17
	v_rcp_f32_e32 v18, v18
	v_rcp_f32_e32 v19, v19
	v_rcp_f32_e32 v20, v20
	v_rcp_f32_e32 v21, v21
	v_rcp_f32_e32 v22, v22
	v_rcp_f32_e32 v23, v23
	v_pk_fma_f32 v[16:17], v[16:17], v[14:15], 0.5 op_sel_hi:[1,0,0]
	v_pk_fma_f32 v[18:19], v[18:19], v[14:15], 0.5 op_sel_hi:[1,0,0]
	v_pk_fma_f32 v[20:21], v[20:21], v[14:15], 0.5 op_sel_hi:[1,0,0]
	v_pk_fma_f32 v[22:23], v[22:23], v[14:15], 0.5 op_sel_hi:[1,0,0]
	v_med3_f32 v16, v16, 1.0, v232
	v_med3_f32 v17, v17, 1.0, v232
	v_med3_f32 v18, v18, 1.0, v232
	v_med3_f32 v19, v19, 1.0, v232
	v_med3_f32 v20, v20, 1.0, v232
	v_med3_f32 v21, v21, 1.0, v232
	v_med3_f32 v22, v22, 1.0, v232
	v_med3_f32 v23, v23, 1.0, v232
	v_cvt_u32_f32_e32 v16, v16
	v_cvt_u32_f32_e32 v17, v17
	v_cvt_u32_f32_sdwa v18, v18 dst_sel:WORD_1 dst_unused:UNUSED_PAD src0_sel:DWORD
	v_cvt_u32_f32_sdwa v19, v19 dst_sel:BYTE_3 dst_unused:UNUSED_PAD src0_sel:DWORD
	v_cvt_u32_f32_e32 v20, v20
	v_cvt_u32_f32_e32 v21, v21
	v_cvt_u32_f32_sdwa v22, v22 dst_sel:WORD_1 dst_unused:UNUSED_PAD src0_sel:DWORD
	v_cvt_u32_f32_sdwa v23, v23 dst_sel:BYTE_3 dst_unused:UNUSED_PAD src0_sel:DWORD
	v_lshl_or_b32 v16, v17, 8, v16
	v_lshl_or_b32 v20, v21, 8, v20
	v_or3_b32 v16, v16, v18, v19
	v_or3_b32 v17, v20, v22, v23
	global_store_dwordx2 v[8:9], v[16:17], off
	v_pk_mul_f32 v[24:25], v[206:207], v[120:121] op_sel_hi:[0,1]
	v_pk_mul_f32 v[26:27], v[206:207], v[122:123] op_sel_hi:[0,1]
	v_pk_mul_f32 v[28:29], v[206:207], v[116:117] op_sel_hi:[0,1]
	v_pk_mul_f32 v[30:31], v[206:207], v[118:119] op_sel_hi:[0,1]
	v_med3_f32 v24, v24, s96, v231
	v_med3_f32 v25, v25, s96, v231
	v_med3_f32 v26, v26, s96, v231
	v_med3_f32 v27, v27, s96, v231
	v_med3_f32 v28, v28, s96, v231
	v_med3_f32 v29, v29, s96, v231
	v_med3_f32 v30, v30, s96, v231
	v_med3_f32 v31, v31, s96, v231
	v_pk_mul_f32 v[24:25], v[24:25], s[98:99]
	v_pk_mul_f32 v[26:27], v[26:27], s[98:99]
	v_pk_mul_f32 v[28:29], v[28:29], s[98:99]
	v_pk_mul_f32 v[30:31], v[30:31], s[98:99]
	v_exp_f32_e32 v24, v24
	v_exp_f32_e32 v25, v25
	v_exp_f32_e32 v26, v26
	v_exp_f32_e32 v27, v27
	v_exp_f32_e32 v28, v28
	v_exp_f32_e32 v29, v29
	v_exp_f32_e32 v30, v30
	v_exp_f32_e32 v31, v31
	v_pk_add_f32 v[24:25], v[24:25], 1.0 op_sel_hi:[1,0]
	v_pk_add_f32 v[26:27], v[26:27], 1.0 op_sel_hi:[1,0]
	v_pk_add_f32 v[28:29], v[28:29], 1.0 op_sel_hi:[1,0]
	v_pk_add_f32 v[30:31], v[30:31], 1.0 op_sel_hi:[1,0]
	v_rcp_f32_e32 v24, v24
	v_rcp_f32_e32 v25, v25
	v_rcp_f32_e32 v26, v26
	v_rcp_f32_e32 v27, v27
	v_rcp_f32_e32 v28, v28
	v_rcp_f32_e32 v29, v29
	v_rcp_f32_e32 v30, v30
	v_rcp_f32_e32 v31, v31
	v_pk_fma_f32 v[24:25], v[24:25], v[14:15], 0.5 op_sel_hi:[1,0,0]
	v_pk_fma_f32 v[26:27], v[26:27], v[14:15], 0.5 op_sel_hi:[1,0,0]
	v_pk_fma_f32 v[28:29], v[28:29], v[14:15], 0.5 op_sel_hi:[1,0,0]
	v_pk_fma_f32 v[30:31], v[30:31], v[14:15], 0.5 op_sel_hi:[1,0,0]
	v_med3_f32 v24, v24, 1.0, v232
	v_med3_f32 v25, v25, 1.0, v232
	v_med3_f32 v26, v26, 1.0, v232
	v_med3_f32 v27, v27, 1.0, v232
	v_med3_f32 v28, v28, 1.0, v232
	v_med3_f32 v29, v29, 1.0, v232
	v_med3_f32 v30, v30, 1.0, v232
	v_med3_f32 v31, v31, 1.0, v232
	v_cvt_u32_f32_e32 v24, v24
	v_cvt_u32_f32_e32 v25, v25
	v_cvt_u32_f32_sdwa v26, v26 dst_sel:WORD_1 dst_unused:UNUSED_PAD src0_sel:DWORD
	v_cvt_u32_f32_sdwa v27, v27 dst_sel:BYTE_3 dst_unused:UNUSED_PAD src0_sel:DWORD
	v_cvt_u32_f32_e32 v28, v28
	v_cvt_u32_f32_e32 v29, v29
	v_cvt_u32_f32_sdwa v30, v30 dst_sel:WORD_1 dst_unused:UNUSED_PAD src0_sel:DWORD
	v_cvt_u32_f32_sdwa v31, v31 dst_sel:BYTE_3 dst_unused:UNUSED_PAD src0_sel:DWORD
	v_lshl_or_b32 v24, v25, 8, v24
	v_lshl_or_b32 v28, v29, 8, v28
	v_or3_b32 v24, v24, v26, v27
	v_or3_b32 v25, v28, v30, v31
	global_store_dwordx2 v[8:9], v[24:25], off offset:128
	v_or_b32_e32 v8, 48, v4
	v_mad_i64_i32 v[8:9], s[50:51], v8, s33, v[2:3]
	v_lshl_add_u64 v[8:9], v[8:9], 0, s[48:49]
	v_lshl_add_u64 v[8:9], v[8:9], 0, v[192:193]
	v_pk_mul_f32 v[16:17], v[206:207], v[112:113] op_sel_hi:[0,1]
	v_pk_mul_f32 v[18:19], v[206:207], v[114:115] op_sel_hi:[0,1]
	v_pk_mul_f32 v[20:21], v[206:207], v[108:109] op_sel_hi:[0,1]
	v_pk_mul_f32 v[22:23], v[206:207], v[110:111] op_sel_hi:[0,1]
	v_med3_f32 v16, v16, s96, v231
	v_med3_f32 v17, v17, s96, v231
	v_med3_f32 v18, v18, s96, v231
	v_med3_f32 v19, v19, s96, v231
	v_med3_f32 v20, v20, s96, v231
	v_med3_f32 v21, v21, s96, v231
	v_med3_f32 v22, v22, s96, v231
	v_med3_f32 v23, v23, s96, v231
	v_pk_mul_f32 v[16:17], v[16:17], s[98:99]
	v_pk_mul_f32 v[18:19], v[18:19], s[98:99]
	v_pk_mul_f32 v[20:21], v[20:21], s[98:99]
	v_pk_mul_f32 v[22:23], v[22:23], s[98:99]
	v_exp_f32_e32 v16, v16
	v_exp_f32_e32 v17, v17
	v_exp_f32_e32 v18, v18
	v_exp_f32_e32 v19, v19
	v_exp_f32_e32 v20, v20
	v_exp_f32_e32 v21, v21
	v_exp_f32_e32 v22, v22
	v_exp_f32_e32 v23, v23
	v_pk_add_f32 v[16:17], v[16:17], 1.0 op_sel_hi:[1,0]
	v_pk_add_f32 v[18:19], v[18:19], 1.0 op_sel_hi:[1,0]
	v_pk_add_f32 v[20:21], v[20:21], 1.0 op_sel_hi:[1,0]
	v_pk_add_f32 v[22:23], v[22:23], 1.0 op_sel_hi:[1,0]
	v_rcp_f32_e32 v16, v16
	v_rcp_f32_e32 v17, v17
	v_rcp_f32_e32 v18, v18
	v_rcp_f32_e32 v19, v19
	v_rcp_f32_e32 v20, v20
;     __device__ __forceinline__ void operator()(const f32x4 (&acc)[2][2][4][2], const Unit& u, int wr, int wc, int fr, int fq) const {
;     ...
;         for (int ai = 0; ai < 2; ++ai)
; #pragma unroll
;             for (int m = 0; m < 4; ++m) { const size_t row = (size_t)(row0 + ai * HALF + m * 16);
; #pragma unroll
;                 for (int bj = 0; bj < 2; ++bj) { const f32x4 v0 = acc[ai][bj][m][0] * sc, v1 = acc[ai][bj][m][1] * sc; unsigned q[8];
; #pragma unroll
;                     for (int j = 0; j < 4; ++j) { const float s0 = 255.0f * __builtin_amdgcn_rcpf(1.0f + __builtin_amdgcn_exp2f(-1.44269504089f * __builtin_amdgcn_fmed3f(v0[j], -30.f, 30.f))) + 0.5f,
;                                                               s1 = 255.0f * __builtin_amdgcn_rcpf(1.0f + __builtin_amdgcn_exp2f(-1.44269504089f * __builtin_amdgcn_fmed3f(v1[j], -30.f, 30.f))) + 0.5f;
;                         q[j] = (unsigned)__builtin_amdgcn_fmed3f(s0, 1.0f, 255.0f); q[4 + j] = (unsigned)__builtin_amdgcn_fmed3f(s1, 1.0f, 255.0f); }
;                     u32x2 w; w.x = q[0] | (q[1] << 8) | (q[2] << 16) | (q[3] << 24); w.y = q[4] | (q[5] << 8) | (q[6] << 16) | (q[7] << 24);
;                     *(u32x2*)(Q + row * 6144 + u.pn * BM + colt + bj * HALF) = w; } }
	v_rcp_f32_e32 v21, v21
	v_rcp_f32_e32 v22, v22
	v_rcp_f32_e32 v23, v23
	v_pk_fma_f32 v[16:17], v[16:17], v[14:15], 0.5 op_sel_hi:[1,0,0]
	v_pk_fma_f32 v[18:19], v[18:19], v[14:15], 0.5 op_sel_hi:[1,0,0]
	v_pk_fma_f32 v[20:21], v[20:21], v[14:15], 0.5 op_sel_hi:[1,0,0]
	v_pk_fma_f32 v[22:23], v[22:23], v[14:15], 0.5 op_sel_hi:[1,0,0]
	v_med3_f32 v16, v16, 1.0, v232
	v_med3_f32 v17, v17, 1.0, v232
	v_med3_f32 v18, v18, 1.0, v232
	v_med3_f32 v19, v19, 1.0, v232
	v_med3_f32 v20, v20, 1.0, v232
	v_med3_f32 v21, v21, 1.0, v232
	v_med3_f32 v22, v22, 1.0, v232
	v_med3_f32 v23, v23, 1.0, v232
	v_cvt_u32_f32_e32 v16, v16
	v_cvt_u32_f32_e32 v17, v17
	v_cvt_u32_f32_sdwa v18, v18 dst_sel:WORD_1 dst_unused:UNUSED_PAD src0_sel:DWORD
	v_cvt_u32_f32_sdwa v19, v19 dst_sel:BYTE_3 dst_unused:UNUSED_PAD src0_sel:DWORD
	v_cvt_u32_f32_e32 v20, v20
	v_cvt_u32_f32_e32 v21, v21
	v_cvt_u32_f32_sdwa v22, v22 dst_sel:WORD_1 dst_unused:UNUSED_PAD src0_sel:DWORD
	v_cvt_u32_f32_sdwa v23, v23 dst_sel:BYTE_3 dst_unused:UNUSED_PAD src0_sel:DWORD
	v_lshl_or_b32 v16, v17, 8, v16
	v_lshl_or_b32 v20, v21, 8, v20
	v_or3_b32 v16, v16, v18, v19
	v_or3_b32 v17, v20, v22, v23
	global_store_dwordx2 v[8:9], v[16:17], off
	v_pk_mul_f32 v[24:25], v[206:207], v[104:105] op_sel_hi:[0,1]
	v_pk_mul_f32 v[26:27], v[206:207], v[106:107] op_sel_hi:[0,1]
	v_pk_mul_f32 v[28:29], v[206:207], v[100:101] op_sel_hi:[0,1]
	v_pk_mul_f32 v[30:31], v[206:207], v[102:103] op_sel_hi:[0,1]
	v_med3_f32 v24, v24, s96, v231
	v_med3_f32 v25, v25, s96, v231
	v_med3_f32 v26, v26, s96, v231
	v_med3_f32 v27, v27, s96, v231
	v_med3_f32 v28, v28, s96, v231
	v_med3_f32 v29, v29, s96, v231
	v_med3_f32 v30, v30, s96, v231
	v_med3_f32 v31, v31, s96, v231
	v_pk_mul_f32 v[24:25], v[24:25], s[98:99]
	v_pk_mul_f32 v[26:27], v[26:27], s[98:99]
	v_pk_mul_f32 v[28:29], v[28:29], s[98:99]
	v_pk_mul_f32 v[30:31], v[30:31], s[98:99]
	v_exp_f32_e32 v24, v24
	v_exp_f32_e32 v25, v25
	v_exp_f32_e32 v26, v26
	v_exp_f32_e32 v27, v27
	v_exp_f32_e32 v28, v28
	v_exp_f32_e32 v29, v29
	v_exp_f32_e32 v30, v30
	v_exp_f32_e32 v31, v31
	v_pk_add_f32 v[24:25], v[24:25], 1.0 op_sel_hi:[1,0]
	v_pk_add_f32 v[26:27], v[26:27], 1.0 op_sel_hi:[1,0]
	v_pk_add_f32 v[28:29], v[28:29], 1.0 op_sel_hi:[1,0]
	v_pk_add_f32 v[30:31], v[30:31], 1.0 op_sel_hi:[1,0]
	v_rcp_f32_e32 v24, v24
	v_rcp_f32_e32 v25, v25
	v_rcp_f32_e32 v26, v26
	v_rcp_f32_e32 v27, v27
	v_rcp_f32_e32 v28, v28
	v_rcp_f32_e32 v29, v29
	v_rcp_f32_e32 v30, v30
	v_rcp_f32_e32 v31, v31
	v_pk_fma_f32 v[24:25], v[24:25], v[14:15], 0.5 op_sel_hi:[1,0,0]
	v_pk_fma_f32 v[26:27], v[26:27], v[14:15], 0.5 op_sel_hi:[1,0,0]
	v_pk_fma_f32 v[28:29], v[28:29], v[14:15], 0.5 op_sel_hi:[1,0,0]
	v_pk_fma_f32 v[30:31], v[30:31], v[14:15], 0.5 op_sel_hi:[1,0,0]
	v_med3_f32 v24, v24, 1.0, v232
	v_med3_f32 v25, v25, 1.0, v232
	v_med3_f32 v26, v26, 1.0, v232
	v_med3_f32 v27, v27, 1.0, v232
	v_med3_f32 v28, v28, 1.0, v232
	v_med3_f32 v29, v29, 1.0, v232
	v_med3_f32 v30, v30, 1.0, v232
	v_med3_f32 v31, v31, 1.0, v232
	v_cvt_u32_f32_e32 v24, v24
	v_cvt_u32_f32_e32 v25, v25
	v_cvt_u32_f32_sdwa v26, v26 dst_sel:WORD_1 dst_unused:UNUSED_PAD src0_sel:DWORD
	v_cvt_u32_f32_sdwa v27, v27 dst_sel:BYTE_3 dst_unused:UNUSED_PAD src0_sel:DWORD
	v_cvt_u32_f32_e32 v28, v28
	v_cvt_u32_f32_e32 v29, v29
	v_cvt_u32_f32_sdwa v30, v30 dst_sel:WORD_1 dst_unused:UNUSED_PAD src0_sel:DWORD
	v_cvt_u32_f32_sdwa v31, v31 dst_sel:BYTE_3 dst_unused:UNUSED_PAD src0_sel:DWORD
	v_lshl_or_b32 v24, v25, 8, v24
	v_lshl_or_b32 v28, v29, 8, v28
	v_or3_b32 v24, v24, v26, v27
	v_or3_b32 v25, v28, v30, v31
	global_store_dwordx2 v[8:9], v[24:25], off offset:128
	v_add_u32_e32 v8, 0x80, v4
	v_mad_i64_i32 v[8:9], s[50:51], v8, s33, v[2:3]
	v_lshl_add_u64 v[8:9], v[8:9], 0, s[48:49]
	v_lshl_add_u64 v[8:9], v[8:9], 0, v[192:193]
	v_pk_mul_f32 v[16:17], v[206:207], v[96:97] op_sel_hi:[0,1]
	v_pk_mul_f32 v[18:19], v[206:207], v[98:99] op_sel_hi:[0,1]
	v_pk_mul_f32 v[20:21], v[206:207], v[92:93] op_sel_hi:[0,1]
	v_pk_mul_f32 v[22:23], v[206:207], v[94:95] op_sel_hi:[0,1]
	v_med3_f32 v16, v16, s96, v231
	v_med3_f32 v17, v17, s96, v231
	v_med3_f32 v18, v18, s96, v231
	v_med3_f32 v19, v19, s96, v231
	v_med3_f32 v20, v20, s96, v231
	v_med3_f32 v21, v21, s96, v231
	v_med3_f32 v22, v22, s96, v231
	v_med3_f32 v23, v23, s96, v231
	v_pk_mul_f32 v[16:17], v[16:17], s[98:99]
	v_pk_mul_f32 v[18:19], v[18:19], s[98:99]
	v_pk_mul_f32 v[20:21], v[20:21], s[98:99]
	v_pk_mul_f32 v[22:23], v[22:23], s[98:99]
	v_exp_f32_e32 v16, v16
	v_exp_f32_e32 v17, v17
	v_exp_f32_e32 v18, v18
	v_exp_f32_e32 v19, v19
	v_exp_f32_e32 v20, v20
	v_exp_f32_e32 v21, v21
	v_exp_f32_e32 v22, v22
	v_exp_f32_e32 v23, v23
	v_pk_add_f32 v[16:17], v[16:17], 1.0 op_sel_hi:[1,0]
	v_pk_add_f32 v[18:19], v[18:19], 1.0 op_sel_hi:[1,0]
	v_pk_add_f32 v[20:21], v[20:21], 1.0 op_sel_hi:[1,0]
	v_pk_add_f32 v[22:23], v[22:23], 1.0 op_sel_hi:[1,0]
	v_rcp_f32_e32 v16, v16
	v_rcp_f32_e32 v17, v17
	v_rcp_f32_e32 v18, v18
	v_rcp_f32_e32 v19, v19
	v_rcp_f32_e32 v20, v20
	v_rcp_f32_e32 v21, v21
	v_rcp_f32_e32 v22, v22
	v_rcp_f32_e32 v23, v23
	v_pk_fma_f32 v[16:17], v[16:17], v[14:15], 0.5 op_sel_hi:[1,0,0]
	v_pk_fma_f32 v[18:19], v[18:19], v[14:15], 0.5 op_sel_hi:[1,0,0]
	v_pk_fma_f32 v[20:21], v[20:21], v[14:15], 0.5 op_sel_hi:[1,0,0]
	v_pk_fma_f32 v[22:23], v[22:23], v[14:15], 0.5 op_sel_hi:[1,0,0]
	v_med3_f32 v16, v16, 1.0, v232
	v_med3_f32 v17, v17, 1.0, v232
	v_med3_f32 v18, v18, 1.0, v232
	v_med3_f32 v19, v19, 1.0, v232
	v_med3_f32 v20, v20, 1.0, v232
	v_med3_f32 v21, v21, 1.0, v232
	v_med3_f32 v22, v22, 1.0, v232
	v_med3_f32 v23, v23, 1.0, v232
	v_cvt_u32_f32_e32 v16, v16
	v_cvt_u32_f32_e32 v17, v17
;     __device__ __forceinline__ void operator()(const f32x4 (&acc)[2][2][4][2], const Unit& u, int wr, int wc, int fr, int fq) const {
;     ...
;         for (int ai = 0; ai < 2; ++ai)
; #pragma unroll
;             for (int m = 0; m < 4; ++m) { const size_t row = (size_t)(row0 + ai * HALF + m * 16);
; #pragma unroll
;                 for (int bj = 0; bj < 2; ++bj) { const f32x4 v0 = acc[ai][bj][m][0] * sc, v1 = acc[ai][bj][m][1] * sc; unsigned q[8];
; #pragma unroll
;                     for (int j = 0; j < 4; ++j) { const float s0 = 255.0f * __builtin_amdgcn_rcpf(1.0f + __builtin_amdgcn_exp2f(-1.44269504089f * __builtin_amdgcn_fmed3f(v0[j], -30.f, 30.f))) + 0.5f,
;                                                               s1 = 255.0f * __builtin_amdgcn_rcpf(1.0f + __builtin_amdgcn_exp2f(-1.44269504089f * __builtin_amdgcn_fmed3f(v1[j], -30.f, 30.f))) + 0.5f;
;                         q[j] = (unsigned)__builtin_amdgcn_fmed3f(s0, 1.0f, 255.0f); q[4 + j] = (unsigned)__builtin_amdgcn_fmed3f(s1, 1.0f, 255.0f); }
;                     u32x2 w; w.x = q[0] | (q[1] << 8) | (q[2] << 16) | (q[3] << 24); w.y = q[4] | (q[5] << 8) | (q[6] << 16) | (q[7] << 24);
;                     *(u32x2*)(Q + row * 6144 + u.pn * BM + colt + bj * HALF) = w; } }
	v_cvt_u32_f32_sdwa v18, v18 dst_sel:WORD_1 dst_unused:UNUSED_PAD src0_sel:DWORD
	v_cvt_u32_f32_sdwa v19, v19 dst_sel:BYTE_3 dst_unused:UNUSED_PAD src0_sel:DWORD
	v_cvt_u32_f32_e32 v20, v20
	v_cvt_u32_f32_e32 v21, v21
	v_cvt_u32_f32_sdwa v22, v22 dst_sel:WORD_1 dst_unused:UNUSED_PAD src0_sel:DWORD
	v_cvt_u32_f32_sdwa v23, v23 dst_sel:BYTE_3 dst_unused:UNUSED_PAD src0_sel:DWORD
	v_lshl_or_b32 v16, v17, 8, v16
	v_lshl_or_b32 v20, v21, 8, v20
	v_or3_b32 v16, v16, v18, v19
	v_or3_b32 v17, v20, v22, v23
	global_store_dwordx2 v[8:9], v[16:17], off
	v_pk_mul_f32 v[24:25], v[206:207], v[88:89] op_sel_hi:[0,1]
	v_pk_mul_f32 v[26:27], v[206:207], v[90:91] op_sel_hi:[0,1]
	v_pk_mul_f32 v[28:29], v[206:207], v[84:85] op_sel_hi:[0,1]
	v_pk_mul_f32 v[30:31], v[206:207], v[86:87] op_sel_hi:[0,1]
	v_med3_f32 v24, v24, s96, v231
	v_med3_f32 v25, v25, s96, v231
	v_med3_f32 v26, v26, s96, v231
	v_med3_f32 v27, v27, s96, v231
	v_med3_f32 v28, v28, s96, v231
	v_med3_f32 v29, v29, s96, v231
	v_med3_f32 v30, v30, s96, v231
	v_med3_f32 v31, v31, s96, v231
	v_pk_mul_f32 v[24:25], v[24:25], s[98:99]
	v_pk_mul_f32 v[26:27], v[26:27], s[98:99]
	v_pk_mul_f32 v[28:29], v[28:29], s[98:99]
	v_pk_mul_f32 v[30:31], v[30:31], s[98:99]
	v_exp_f32_e32 v24, v24
	v_exp_f32_e32 v25, v25
	v_exp_f32_e32 v26, v26
	v_exp_f32_e32 v27, v27
	v_exp_f32_e32 v28, v28
	v_exp_f32_e32 v29, v29
	v_exp_f32_e32 v30, v30
	v_exp_f32_e32 v31, v31
	v_pk_add_f32 v[24:25], v[24:25], 1.0 op_sel_hi:[1,0]
	v_pk_add_f32 v[26:27], v[26:27], 1.0 op_sel_hi:[1,0]
	v_pk_add_f32 v[28:29], v[28:29], 1.0 op_sel_hi:[1,0]
	v_pk_add_f32 v[30:31], v[30:31], 1.0 op_sel_hi:[1,0]
	v_rcp_f32_e32 v24, v24
	v_rcp_f32_e32 v25, v25
	v_rcp_f32_e32 v26, v26
	v_rcp_f32_e32 v27, v27
	v_rcp_f32_e32 v28, v28
	v_rcp_f32_e32 v29, v29
	v_rcp_f32_e32 v30, v30
	v_rcp_f32_e32 v31, v31
	v_pk_fma_f32 v[24:25], v[24:25], v[14:15], 0.5 op_sel_hi:[1,0,0]
	v_pk_fma_f32 v[26:27], v[26:27], v[14:15], 0.5 op_sel_hi:[1,0,0]
	v_pk_fma_f32 v[28:29], v[28:29], v[14:15], 0.5 op_sel_hi:[1,0,0]
	v_pk_fma_f32 v[30:31], v[30:31], v[14:15], 0.5 op_sel_hi:[1,0,0]
	v_med3_f32 v24, v24, 1.0, v232
	v_med3_f32 v25, v25, 1.0, v232
	v_med3_f32 v26, v26, 1.0, v232
	v_med3_f32 v27, v27, 1.0, v232
	v_med3_f32 v28, v28, 1.0, v232
	v_med3_f32 v29, v29, 1.0, v232
	v_med3_f32 v30, v30, 1.0, v232
	v_med3_f32 v31, v31, 1.0, v232
	v_cvt_u32_f32_e32 v24, v24
	v_cvt_u32_f32_e32 v25, v25
	v_cvt_u32_f32_sdwa v26, v26 dst_sel:WORD_1 dst_unused:UNUSED_PAD src0_sel:DWORD
	v_cvt_u32_f32_sdwa v27, v27 dst_sel:BYTE_3 dst_unused:UNUSED_PAD src0_sel:DWORD
	v_cvt_u32_f32_e32 v28, v28
	v_cvt_u32_f32_e32 v29, v29
	v_cvt_u32_f32_sdwa v30, v30 dst_sel:WORD_1 dst_unused:UNUSED_PAD src0_sel:DWORD
	v_cvt_u32_f32_sdwa v31, v31 dst_sel:BYTE_3 dst_unused:UNUSED_PAD src0_sel:DWORD
	v_lshl_or_b32 v24, v25, 8, v24
	v_lshl_or_b32 v28, v29, 8, v28
	v_or3_b32 v24, v24, v26, v27
	v_or3_b32 v25, v28, v30, v31
	global_store_dwordx2 v[8:9], v[24:25], off offset:128
	v_add_u32_e32 v8, 0x90, v4
	v_mad_i64_i32 v[8:9], s[50:51], v8, s33, v[2:3]
	v_lshl_add_u64 v[8:9], v[8:9], 0, s[48:49]
	v_lshl_add_u64 v[8:9], v[8:9], 0, v[192:193]
	v_pk_mul_f32 v[16:17], v[206:207], v[80:81] op_sel_hi:[0,1]
	v_pk_mul_f32 v[18:19], v[206:207], v[82:83] op_sel_hi:[0,1]
	v_pk_mul_f32 v[20:21], v[206:207], v[76:77] op_sel_hi:[0,1]
	v_pk_mul_f32 v[22:23], v[206:207], v[78:79] op_sel_hi:[0,1]
	v_med3_f32 v16, v16, s96, v231
	v_med3_f32 v17, v17, s96, v231
	v_med3_f32 v18, v18, s96, v231
	v_med3_f32 v19, v19, s96, v231
	v_med3_f32 v20, v20, s96, v231
	v_med3_f32 v21, v21, s96, v231
	v_med3_f32 v22, v22, s96, v231
	v_med3_f32 v23, v23, s96, v231
	v_pk_mul_f32 v[16:17], v[16:17], s[98:99]
	v_pk_mul_f32 v[18:19], v[18:19], s[98:99]
	v_pk_mul_f32 v[20:21], v[20:21], s[98:99]
	v_pk_mul_f32 v[22:23], v[22:23], s[98:99]
	v_exp_f32_e32 v16, v16
	v_exp_f32_e32 v17, v17
	v_exp_f32_e32 v18, v18
	v_exp_f32_e32 v19, v19
	v_exp_f32_e32 v20, v20
	v_exp_f32_e32 v21, v21
	v_exp_f32_e32 v22, v22
	v_exp_f32_e32 v23, v23
	v_pk_add_f32 v[16:17], v[16:17], 1.0 op_sel_hi:[1,0]
	v_pk_add_f32 v[18:19], v[18:19], 1.0 op_sel_hi:[1,0]
	v_pk_add_f32 v[20:21], v[20:21], 1.0 op_sel_hi:[1,0]
	v_pk_add_f32 v[22:23], v[22:23], 1.0 op_sel_hi:[1,0]
	v_rcp_f32_e32 v16, v16
	v_rcp_f32_e32 v17, v17
	v_rcp_f32_e32 v18, v18
	v_rcp_f32_e32 v19, v19
	v_rcp_f32_e32 v20, v20
	v_rcp_f32_e32 v21, v21
	v_rcp_f32_e32 v22, v22
	v_rcp_f32_e32 v23, v23
	v_pk_fma_f32 v[16:17], v[16:17], v[14:15], 0.5 op_sel_hi:[1,0,0]
	v_pk_fma_f32 v[18:19], v[18:19], v[14:15], 0.5 op_sel_hi:[1,0,0]
	v_pk_fma_f32 v[20:21], v[20:21], v[14:15], 0.5 op_sel_hi:[1,0,0]
	v_pk_fma_f32 v[22:23], v[22:23], v[14:15], 0.5 op_sel_hi:[1,0,0]
	v_med3_f32 v16, v16, 1.0, v232
	v_med3_f32 v17, v17, 1.0, v232
	v_med3_f32 v18, v18, 1.0, v232
	v_med3_f32 v19, v19, 1.0, v232
	v_med3_f32 v20, v20, 1.0, v232
	v_med3_f32 v21, v21, 1.0, v232
	v_med3_f32 v22, v22, 1.0, v232
	v_med3_f32 v23, v23, 1.0, v232
	v_cvt_u32_f32_e32 v16, v16
	v_cvt_u32_f32_e32 v17, v17
	v_cvt_u32_f32_sdwa v18, v18 dst_sel:WORD_1 dst_unused:UNUSED_PAD src0_sel:DWORD
	v_cvt_u32_f32_sdwa v19, v19 dst_sel:BYTE_3 dst_unused:UNUSED_PAD src0_sel:DWORD
	v_cvt_u32_f32_e32 v20, v20
	v_cvt_u32_f32_e32 v21, v21
	v_cvt_u32_f32_sdwa v22, v22 dst_sel:WORD_1 dst_unused:UNUSED_PAD src0_sel:DWORD
	v_cvt_u32_f32_sdwa v23, v23 dst_sel:BYTE_3 dst_unused:UNUSED_PAD src0_sel:DWORD
	v_lshl_or_b32 v16, v17, 8, v16
	v_lshl_or_b32 v20, v21, 8, v20
	v_or3_b32 v16, v16, v18, v19
	v_or3_b32 v17, v20, v22, v23
	global_store_dwordx2 v[8:9], v[16:17], off
	v_pk_mul_f32 v[24:25], v[206:207], v[72:73] op_sel_hi:[0,1]
	v_pk_mul_f32 v[26:27], v[206:207], v[74:75] op_sel_hi:[0,1]
;     __device__ __forceinline__ void operator()(const f32x4 (&acc)[2][2][4][2], const Unit& u, int wr, int wc, int fr, int fq) const {
;     ...
;         for (int ai = 0; ai < 2; ++ai)
; #pragma unroll
;             for (int m = 0; m < 4; ++m) { const size_t row = (size_t)(row0 + ai * HALF + m * 16);
; #pragma unroll
;                 for (int bj = 0; bj < 2; ++bj) { const f32x4 v0 = acc[ai][bj][m][0] * sc, v1 = acc[ai][bj][m][1] * sc; unsigned q[8];
; #pragma unroll
;                     for (int j = 0; j < 4; ++j) { const float s0 = 255.0f * __builtin_amdgcn_rcpf(1.0f + __builtin_amdgcn_exp2f(-1.44269504089f * __builtin_amdgcn_fmed3f(v0[j], -30.f, 30.f))) + 0.5f,
;                                                               s1 = 255.0f * __builtin_amdgcn_rcpf(1.0f + __builtin_amdgcn_exp2f(-1.44269504089f * __builtin_amdgcn_fmed3f(v1[j], -30.f, 30.f))) + 0.5f;
;                         q[j] = (unsigned)__builtin_amdgcn_fmed3f(s0, 1.0f, 255.0f); q[4 + j] = (unsigned)__builtin_amdgcn_fmed3f(s1, 1.0f, 255.0f); }
;                     u32x2 w; w.x = q[0] | (q[1] << 8) | (q[2] << 16) | (q[3] << 24); w.y = q[4] | (q[5] << 8) | (q[6] << 16) | (q[7] << 24);
;                     *(u32x2*)(Q + row * 6144 + u.pn * BM + colt + bj * HALF) = w; } }
	v_pk_mul_f32 v[28:29], v[206:207], v[68:69] op_sel_hi:[0,1]
	v_pk_mul_f32 v[30:31], v[206:207], v[70:71] op_sel_hi:[0,1]
	v_med3_f32 v24, v24, s96, v231
	v_med3_f32 v25, v25, s96, v231
	v_med3_f32 v26, v26, s96, v231
	v_med3_f32 v27, v27, s96, v231
	v_med3_f32 v28, v28, s96, v231
	v_med3_f32 v29, v29, s96, v231
	v_med3_f32 v30, v30, s96, v231
	v_med3_f32 v31, v31, s96, v231
	v_pk_mul_f32 v[24:25], v[24:25], s[98:99]
	v_pk_mul_f32 v[26:27], v[26:27], s[98:99]
	v_pk_mul_f32 v[28:29], v[28:29], s[98:99]
	v_pk_mul_f32 v[30:31], v[30:31], s[98:99]
	v_exp_f32_e32 v24, v24
	v_exp_f32_e32 v25, v25
	v_exp_f32_e32 v26, v26
	v_exp_f32_e32 v27, v27
	v_exp_f32_e32 v28, v28
	v_exp_f32_e32 v29, v29
	v_exp_f32_e32 v30, v30
	v_exp_f32_e32 v31, v31
	v_pk_add_f32 v[24:25], v[24:25], 1.0 op_sel_hi:[1,0]
	v_pk_add_f32 v[26:27], v[26:27], 1.0 op_sel_hi:[1,0]
	v_pk_add_f32 v[28:29], v[28:29], 1.0 op_sel_hi:[1,0]
	v_pk_add_f32 v[30:31], v[30:31], 1.0 op_sel_hi:[1,0]
	v_rcp_f32_e32 v24, v24
	v_rcp_f32_e32 v25, v25
	v_rcp_f32_e32 v26, v26
	v_rcp_f32_e32 v27, v27
	v_rcp_f32_e32 v28, v28
	v_rcp_f32_e32 v29, v29
	v_rcp_f32_e32 v30, v30
	v_rcp_f32_e32 v31, v31
	v_pk_fma_f32 v[24:25], v[24:25], v[14:15], 0.5 op_sel_hi:[1,0,0]
	v_pk_fma_f32 v[26:27], v[26:27], v[14:15], 0.5 op_sel_hi:[1,0,0]
	v_pk_fma_f32 v[28:29], v[28:29], v[14:15], 0.5 op_sel_hi:[1,0,0]
	v_pk_fma_f32 v[30:31], v[30:31], v[14:15], 0.5 op_sel_hi:[1,0,0]
	v_med3_f32 v24, v24, 1.0, v232
	v_med3_f32 v25, v25, 1.0, v232
	v_med3_f32 v26, v26, 1.0, v232
	v_med3_f32 v27, v27, 1.0, v232
	v_med3_f32 v28, v28, 1.0, v232
	v_med3_f32 v29, v29, 1.0, v232
	v_med3_f32 v30, v30, 1.0, v232
	v_med3_f32 v31, v31, 1.0, v232
	v_cvt_u32_f32_e32 v24, v24
	v_cvt_u32_f32_e32 v25, v25
	v_cvt_u32_f32_sdwa v26, v26 dst_sel:WORD_1 dst_unused:UNUSED_PAD src0_sel:DWORD
	v_cvt_u32_f32_sdwa v27, v27 dst_sel:BYTE_3 dst_unused:UNUSED_PAD src0_sel:DWORD
	v_cvt_u32_f32_e32 v28, v28
	v_cvt_u32_f32_e32 v29, v29
	v_cvt_u32_f32_sdwa v30, v30 dst_sel:WORD_1 dst_unused:UNUSED_PAD src0_sel:DWORD
	v_cvt_u32_f32_sdwa v31, v31 dst_sel:BYTE_3 dst_unused:UNUSED_PAD src0_sel:DWORD
	v_lshl_or_b32 v24, v25, 8, v24
	v_lshl_or_b32 v28, v29, 8, v28
	v_or3_b32 v24, v24, v26, v27
	v_or3_b32 v25, v28, v30, v31
	global_store_dwordx2 v[8:9], v[24:25], off offset:128
	v_add_u32_e32 v8, 0xa0, v4
	v_mad_i64_i32 v[8:9], s[50:51], v8, s33, v[2:3]
	v_lshl_add_u64 v[8:9], v[8:9], 0, s[48:49]
	v_lshl_add_u64 v[8:9], v[8:9], 0, v[192:193]
	v_pk_mul_f32 v[16:17], v[206:207], v[64:65] op_sel_hi:[0,1]
	v_pk_mul_f32 v[18:19], v[206:207], v[66:67] op_sel_hi:[0,1]
	v_pk_mul_f32 v[20:21], v[206:207], v[60:61] op_sel_hi:[0,1]
	v_pk_mul_f32 v[22:23], v[206:207], v[62:63] op_sel_hi:[0,1]
	v_med3_f32 v16, v16, s96, v231
	v_med3_f32 v17, v17, s96, v231
	v_med3_f32 v18, v18, s96, v231
	v_med3_f32 v19, v19, s96, v231
	v_med3_f32 v20, v20, s96, v231
	v_med3_f32 v21, v21, s96, v231
	v_med3_f32 v22, v22, s96, v231
	v_med3_f32 v23, v23, s96, v231
	v_pk_mul_f32 v[16:17], v[16:17], s[98:99]
	v_pk_mul_f32 v[18:19], v[18:19], s[98:99]
	v_pk_mul_f32 v[20:21], v[20:21], s[98:99]
	v_pk_mul_f32 v[22:23], v[22:23], s[98:99]
	v_exp_f32_e32 v16, v16
	v_exp_f32_e32 v17, v17
	v_exp_f32_e32 v18, v18
	v_exp_f32_e32 v19, v19
	v_exp_f32_e32 v20, v20
	v_exp_f32_e32 v21, v21
	v_exp_f32_e32 v22, v22
	v_exp_f32_e32 v23, v23
	v_pk_add_f32 v[16:17], v[16:17], 1.0 op_sel_hi:[1,0]
	v_pk_add_f32 v[18:19], v[18:19], 1.0 op_sel_hi:[1,0]
	v_pk_add_f32 v[20:21], v[20:21], 1.0 op_sel_hi:[1,0]
	v_pk_add_f32 v[22:23], v[22:23], 1.0 op_sel_hi:[1,0]
	v_rcp_f32_e32 v16, v16
	v_rcp_f32_e32 v17, v17
	v_rcp_f32_e32 v18, v18
	v_rcp_f32_e32 v19, v19
	v_rcp_f32_e32 v20, v20
	v_rcp_f32_e32 v21, v21
	v_rcp_f32_e32 v22, v22
	v_rcp_f32_e32 v23, v23
	v_pk_fma_f32 v[16:17], v[16:17], v[14:15], 0.5 op_sel_hi:[1,0,0]
	v_pk_fma_f32 v[18:19], v[18:19], v[14:15], 0.5 op_sel_hi:[1,0,0]
	v_pk_fma_f32 v[20:21], v[20:21], v[14:15], 0.5 op_sel_hi:[1,0,0]
	v_pk_fma_f32 v[22:23], v[22:23], v[14:15], 0.5 op_sel_hi:[1,0,0]
	v_med3_f32 v16, v16, 1.0, v232
	v_med3_f32 v17, v17, 1.0, v232
	v_med3_f32 v18, v18, 1.0, v232
	v_med3_f32 v19, v19, 1.0, v232
	v_med3_f32 v20, v20, 1.0, v232
	v_med3_f32 v21, v21, 1.0, v232
	v_med3_f32 v22, v22, 1.0, v232
	v_med3_f32 v23, v23, 1.0, v232
	v_cvt_u32_f32_e32 v16, v16
	v_cvt_u32_f32_e32 v17, v17
	v_cvt_u32_f32_sdwa v18, v18 dst_sel:WORD_1 dst_unused:UNUSED_PAD src0_sel:DWORD
	v_cvt_u32_f32_sdwa v19, v19 dst_sel:BYTE_3 dst_unused:UNUSED_PAD src0_sel:DWORD
	v_cvt_u32_f32_e32 v20, v20
	v_cvt_u32_f32_e32 v21, v21
	v_cvt_u32_f32_sdwa v22, v22 dst_sel:WORD_1 dst_unused:UNUSED_PAD src0_sel:DWORD
	v_cvt_u32_f32_sdwa v23, v23 dst_sel:BYTE_3 dst_unused:UNUSED_PAD src0_sel:DWORD
	v_lshl_or_b32 v16, v17, 8, v16
	v_lshl_or_b32 v20, v21, 8, v20
	v_or3_b32 v16, v16, v18, v19
	v_or3_b32 v17, v20, v22, v23
	global_store_dwordx2 v[8:9], v[16:17], off
	v_pk_mul_f32 v[24:25], v[206:207], v[56:57] op_sel_hi:[0,1]
	v_pk_mul_f32 v[26:27], v[206:207], v[58:59] op_sel_hi:[0,1]
	v_pk_mul_f32 v[28:29], v[206:207], v[52:53] op_sel_hi:[0,1]
	v_pk_mul_f32 v[30:31], v[206:207], v[54:55] op_sel_hi:[0,1]
	v_med3_f32 v24, v24, s96, v231
	v_med3_f32 v25, v25, s96, v231
	v_med3_f32 v26, v26, s96, v231
	v_med3_f32 v27, v27, s96, v231
	v_med3_f32 v28, v28, s96, v231
	v_med3_f32 v29, v29, s96, v231
	v_med3_f32 v30, v30, s96, v231
	v_med3_f32 v31, v31, s96, v231
	v_pk_mul_f32 v[24:25], v[24:25], s[98:99]
	v_pk_mul_f32 v[26:27], v[26:27], s[98:99]
	v_pk_mul_f32 v[28:29], v[28:29], s[98:99]
	v_pk_mul_f32 v[30:31], v[30:31], s[98:99]
	v_exp_f32_e32 v24, v24
	v_exp_f32_e32 v25, v25
	v_exp_f32_e32 v26, v26
	v_exp_f32_e32 v27, v27
	v_exp_f32_e32 v28, v28
; #define PG8_BAR __builtin_amdgcn_s_barrier()
;     __device__ __forceinline__ void operator()(const f32x4 (&acc)[2][2][4][2], const Unit& u, int wr, int wc, int fr, int fq) const {
;     ...
;         for (int ai = 0; ai < 2; ++ai)
; #pragma unroll
;             for (int m = 0; m < 4; ++m) { const size_t row = (size_t)(row0 + ai * HALF + m * 16);
; #pragma unroll
;                 for (int bj = 0; bj < 2; ++bj) { const f32x4 v0 = acc[ai][bj][m][0] * sc, v1 = acc[ai][bj][m][1] * sc; unsigned q[8];
; #pragma unroll
;                     for (int j = 0; j < 4; ++j) { const float s0 = 255.0f * __builtin_amdgcn_rcpf(1.0f + __builtin_amdgcn_exp2f(-1.44269504089f * __builtin_amdgcn_fmed3f(v0[j], -30.f, 30.f))) + 0.5f,
;                                                               s1 = 255.0f * __builtin_amdgcn_rcpf(1.0f + __builtin_amdgcn_exp2f(-1.44269504089f * __builtin_amdgcn_fmed3f(v1[j], -30.f, 30.f))) + 0.5f;
;                         q[j] = (unsigned)__builtin_amdgcn_fmed3f(s0, 1.0f, 255.0f); q[4 + j] = (unsigned)__builtin_amdgcn_fmed3f(s1, 1.0f, 255.0f); }
;                     u32x2 w; w.x = q[0] | (q[1] << 8) | (q[2] << 16) | (q[3] << 24); w.y = q[4] | (q[5] << 8) | (q[6] << 16) | (q[7] << 24);
;                     *(u32x2*)(Q + row * 6144 + u.pn * BM + colt + bj * HALF) = w; } }
;     ...
;         if constexpr (!Epi::AFTER_DRAIN) { E(acc, cur, wr, wc, fr, fq); S.done(cur); }
;         if (!has_next) break;
;         if (!Epi::SEGMENTED || cur.seg == 2)
; #pragma unroll
;         for (int a = 0; a < 2; ++a)
; #pragma unroll
;             for (int b = 0; b < 2; ++b)
; #pragma unroll
;                 for (int m = 0; m < 4; ++m)
; #pragma unroll
;                     for (int n = 0; n < 2; ++n) acc[a][b][m][n] = (f32x4){0.f, 0.f, 0.f, 0.f};
;         cur = nxt; cA = nA; cB = nB; ++ui;
;         if constexpr (ALIGN_EPI) { if (wr == 1) PG8_BAR; }
	v_exp_f32_e32 v29, v29
	v_exp_f32_e32 v30, v30
	v_exp_f32_e32 v31, v31
	v_pk_add_f32 v[24:25], v[24:25], 1.0 op_sel_hi:[1,0]
	v_pk_add_f32 v[26:27], v[26:27], 1.0 op_sel_hi:[1,0]
	v_pk_add_f32 v[28:29], v[28:29], 1.0 op_sel_hi:[1,0]
	v_pk_add_f32 v[30:31], v[30:31], 1.0 op_sel_hi:[1,0]
	v_rcp_f32_e32 v24, v24
	v_rcp_f32_e32 v25, v25
	v_rcp_f32_e32 v26, v26
	v_rcp_f32_e32 v27, v27
	v_rcp_f32_e32 v28, v28
	v_rcp_f32_e32 v29, v29
	v_rcp_f32_e32 v30, v30
	v_rcp_f32_e32 v31, v31
	v_pk_fma_f32 v[24:25], v[24:25], v[14:15], 0.5 op_sel_hi:[1,0,0]
	v_pk_fma_f32 v[26:27], v[26:27], v[14:15], 0.5 op_sel_hi:[1,0,0]
	v_pk_fma_f32 v[28:29], v[28:29], v[14:15], 0.5 op_sel_hi:[1,0,0]
	v_pk_fma_f32 v[30:31], v[30:31], v[14:15], 0.5 op_sel_hi:[1,0,0]
	v_med3_f32 v24, v24, 1.0, v232
	v_med3_f32 v25, v25, 1.0, v232
	v_med3_f32 v26, v26, 1.0, v232
	v_med3_f32 v27, v27, 1.0, v232
	v_med3_f32 v28, v28, 1.0, v232
	v_med3_f32 v29, v29, 1.0, v232
	v_med3_f32 v30, v30, 1.0, v232
	v_med3_f32 v31, v31, 1.0, v232
	v_cvt_u32_f32_e32 v24, v24
	v_cvt_u32_f32_e32 v25, v25
	v_cvt_u32_f32_sdwa v26, v26 dst_sel:WORD_1 dst_unused:UNUSED_PAD src0_sel:DWORD
	v_cvt_u32_f32_sdwa v27, v27 dst_sel:BYTE_3 dst_unused:UNUSED_PAD src0_sel:DWORD
	v_cvt_u32_f32_e32 v28, v28
	v_cvt_u32_f32_e32 v29, v29
	v_cvt_u32_f32_sdwa v30, v30 dst_sel:WORD_1 dst_unused:UNUSED_PAD src0_sel:DWORD
	v_cvt_u32_f32_sdwa v31, v31 dst_sel:BYTE_3 dst_unused:UNUSED_PAD src0_sel:DWORD
	v_lshl_or_b32 v24, v25, 8, v24
	v_lshl_or_b32 v28, v29, 8, v28
	v_or3_b32 v24, v24, v26, v27
	v_or3_b32 v25, v28, v30, v31
	global_store_dwordx2 v[8:9], v[24:25], off offset:128
	v_add_u32_e32 v6, 0xb0, v4
	v_mad_i64_i32 v[2:3], s[50:51], v6, s33, v[2:3]
	v_lshl_add_u64 v[2:3], v[2:3], 0, s[48:49]
	v_lshl_add_u64 v[2:3], v[2:3], 0, v[192:193]
	v_pk_mul_f32 v[16:17], v[206:207], v[48:49] op_sel_hi:[0,1]
	v_pk_mul_f32 v[18:19], v[206:207], v[50:51] op_sel_hi:[0,1]
	v_pk_mul_f32 v[20:21], v[206:207], v[44:45] op_sel_hi:[0,1]
	v_pk_mul_f32 v[22:23], v[206:207], v[46:47] op_sel_hi:[0,1]
	v_med3_f32 v16, v16, s96, v231
	v_med3_f32 v17, v17, s96, v231
	v_med3_f32 v18, v18, s96, v231
	v_med3_f32 v19, v19, s96, v231
	v_med3_f32 v20, v20, s96, v231
	v_med3_f32 v21, v21, s96, v231
	v_med3_f32 v22, v22, s96, v231
	v_med3_f32 v23, v23, s96, v231
	v_pk_mul_f32 v[16:17], v[16:17], s[98:99]
	v_pk_mul_f32 v[18:19], v[18:19], s[98:99]
	v_pk_mul_f32 v[20:21], v[20:21], s[98:99]
	v_pk_mul_f32 v[22:23], v[22:23], s[98:99]
	v_exp_f32_e32 v16, v16
	v_exp_f32_e32 v17, v17
	v_exp_f32_e32 v18, v18
	v_exp_f32_e32 v19, v19
	v_exp_f32_e32 v20, v20
	v_exp_f32_e32 v21, v21
	v_exp_f32_e32 v22, v22
	v_exp_f32_e32 v23, v23
	v_pk_add_f32 v[16:17], v[16:17], 1.0 op_sel_hi:[1,0]
	v_pk_add_f32 v[18:19], v[18:19], 1.0 op_sel_hi:[1,0]
	v_pk_add_f32 v[20:21], v[20:21], 1.0 op_sel_hi:[1,0]
	v_pk_add_f32 v[22:23], v[22:23], 1.0 op_sel_hi:[1,0]
	v_rcp_f32_e32 v16, v16
	v_rcp_f32_e32 v17, v17
	v_rcp_f32_e32 v18, v18
	v_rcp_f32_e32 v19, v19
	v_rcp_f32_e32 v20, v20
	v_rcp_f32_e32 v21, v21
	v_rcp_f32_e32 v22, v22
	v_rcp_f32_e32 v23, v23
	v_pk_fma_f32 v[16:17], v[16:17], v[14:15], 0.5 op_sel_hi:[1,0,0]
	v_pk_fma_f32 v[18:19], v[18:19], v[14:15], 0.5 op_sel_hi:[1,0,0]
	v_pk_fma_f32 v[20:21], v[20:21], v[14:15], 0.5 op_sel_hi:[1,0,0]
	v_pk_fma_f32 v[22:23], v[22:23], v[14:15], 0.5 op_sel_hi:[1,0,0]
	v_med3_f32 v16, v16, 1.0, v232
	v_med3_f32 v17, v17, 1.0, v232
	v_med3_f32 v18, v18, 1.0, v232
	v_med3_f32 v19, v19, 1.0, v232
	v_med3_f32 v20, v20, 1.0, v232
	v_med3_f32 v21, v21, 1.0, v232
	v_med3_f32 v22, v22, 1.0, v232
	v_med3_f32 v23, v23, 1.0, v232
	v_cvt_u32_f32_e32 v16, v16
	v_cvt_u32_f32_e32 v17, v17
	v_cvt_u32_f32_sdwa v18, v18 dst_sel:WORD_1 dst_unused:UNUSED_PAD src0_sel:DWORD
	v_cvt_u32_f32_sdwa v19, v19 dst_sel:BYTE_3 dst_unused:UNUSED_PAD src0_sel:DWORD
	v_cvt_u32_f32_e32 v20, v20
	v_cvt_u32_f32_e32 v21, v21
	v_cvt_u32_f32_sdwa v22, v22 dst_sel:WORD_1 dst_unused:UNUSED_PAD src0_sel:DWORD
	v_cvt_u32_f32_sdwa v23, v23 dst_sel:BYTE_3 dst_unused:UNUSED_PAD src0_sel:DWORD
	v_lshl_or_b32 v16, v17, 8, v16
	v_lshl_or_b32 v20, v21, 8, v20
	v_or3_b32 v16, v16, v18, v19
	v_or3_b32 v17, v20, v22, v23
	global_store_dwordx2 v[2:3], v[16:17], off
	s_andn2_b64 vcc, exec, s[38:39]
	s_mov_b64 s[38:39], -1
	s_movk_i32 s71, 0x6ff
	v_pk_mul_f32 v[24:25], v[206:207], v[40:41] op_sel_hi:[0,1]
	v_pk_mul_f32 v[26:27], v[206:207], v[42:43] op_sel_hi:[0,1]
	v_pk_mul_f32 v[28:29], v[206:207], v[36:37] op_sel_hi:[0,1]
	v_pk_mul_f32 v[30:31], v[206:207], v[38:39] op_sel_hi:[0,1]
	v_med3_f32 v24, v24, s96, v231
	v_med3_f32 v25, v25, s96, v231
	v_med3_f32 v26, v26, s96, v231
	v_med3_f32 v27, v27, s96, v231
	v_med3_f32 v28, v28, s96, v231
	v_med3_f32 v29, v29, s96, v231
	v_med3_f32 v30, v30, s96, v231
	v_med3_f32 v31, v31, s96, v231
	v_pk_mul_f32 v[24:25], v[24:25], s[98:99]
	v_pk_mul_f32 v[26:27], v[26:27], s[98:99]
	v_pk_mul_f32 v[28:29], v[28:29], s[98:99]
	v_pk_mul_f32 v[30:31], v[30:31], s[98:99]
	v_exp_f32_e32 v24, v24
	v_exp_f32_e32 v25, v25
	v_exp_f32_e32 v26, v26
	v_exp_f32_e32 v27, v27
	v_exp_f32_e32 v28, v28
	v_exp_f32_e32 v29, v29
	v_exp_f32_e32 v30, v30
	v_exp_f32_e32 v31, v31
	v_pk_add_f32 v[24:25], v[24:25], 1.0 op_sel_hi:[1,0]
	v_pk_add_f32 v[26:27], v[26:27], 1.0 op_sel_hi:[1,0]
	v_pk_add_f32 v[28:29], v[28:29], 1.0 op_sel_hi:[1,0]
	v_pk_add_f32 v[30:31], v[30:31], 1.0 op_sel_hi:[1,0]
	v_rcp_f32_e32 v24, v24
	v_rcp_f32_e32 v25, v25
	v_rcp_f32_e32 v26, v26
	v_rcp_f32_e32 v27, v27
	v_rcp_f32_e32 v28, v28
	v_rcp_f32_e32 v29, v29
	v_rcp_f32_e32 v30, v30
	v_rcp_f32_e32 v31, v31
	v_pk_fma_f32 v[24:25], v[24:25], v[14:15], 0.5 op_sel_hi:[1,0,0]
	v_pk_fma_f32 v[26:27], v[26:27], v[14:15], 0.5 op_sel_hi:[1,0,0]
	v_pk_fma_f32 v[28:29], v[28:29], v[14:15], 0.5 op_sel_hi:[1,0,0]
	v_pk_fma_f32 v[30:31], v[30:31], v[14:15], 0.5 op_sel_hi:[1,0,0]
	v_med3_f32 v24, v24, 1.0, v232
	v_med3_f32 v25, v25, 1.0, v232
	v_med3_f32 v26, v26, 1.0, v232
	v_med3_f32 v27, v27, 1.0, v232
	v_med3_f32 v28, v28, 1.0, v232
	v_med3_f32 v29, v29, 1.0, v232
	v_med3_f32 v30, v30, 1.0, v232
	v_med3_f32 v31, v31, 1.0, v232
	v_cvt_u32_f32_e32 v24, v24
	v_cvt_u32_f32_e32 v25, v25
	v_cvt_u32_f32_sdwa v26, v26 dst_sel:WORD_1 dst_unused:UNUSED_PAD src0_sel:DWORD
	v_cvt_u32_f32_sdwa v27, v27 dst_sel:BYTE_3 dst_unused:UNUSED_PAD src0_sel:DWORD
	v_cvt_u32_f32_e32 v28, v28
	v_cvt_u32_f32_e32 v29, v29
	v_cvt_u32_f32_sdwa v30, v30 dst_sel:WORD_1 dst_unused:UNUSED_PAD src0_sel:DWORD
	v_cvt_u32_f32_sdwa v31, v31 dst_sel:BYTE_3 dst_unused:UNUSED_PAD src0_sel:DWORD
	v_lshl_or_b32 v24, v25, 8, v24
	v_lshl_or_b32 v28, v29, 8, v28
	v_or3_b32 v24, v24, v26, v27
	v_or3_b32 v25, v28, v30, v31
	global_store_dwordx2 v[2:3], v[24:25], off offset:128
	s_cbranch_vccnz .LBB0_1129
	s_andn2_b64 vcc, exec, s[18:19]
	s_cbranch_vccnz .LBB0_1128
	s_barrier
	s_branch .LBB0_1128

;     __device__ __forceinline__ const char* pa(const Gemm& g, const Unit& u, size_t tstep) const { return (const char*)g.A + (size_t)u.pm * tstep; }
;     __device__ __forceinline__ const char* pb(const Gemm& g, const Unit& u, size_t tstep) const { return (const char*)g.Bt + (size_t)u.pn * tstep; }
;     __device__ __forceinline__ const char* pa(const Gemm& g, const Unit& u, size_t tstep) const { return (const char*)g.A + (size_t)(u.pn >> 1) * 512 + (size_t)u.pm * tstep; }
;     __device__ __forceinline__ bool next(int i, Unit& u) const { const int ti = i / 3, sg = i - 3 * ti; if (!StaticOrder::next(ti, u)) return false; u.seg = sg; return true; }
; #define PG8_WAIT_V(n) asm volatile("s_waitcnt vmcnt(" #n ")" ::: "memory")
; #define PG8_BAR __builtin_amdgcn_s_barrier()
;     ...
;     for (int i = 0; i < 2; ++i) { int R, C; stage_rc(tid * 16 + i * 8192, R, C); const int Rb = Epi::PERM ? ((R & ~31) + perm32(R & 31)) : R;
;         voffA[i] = (unsigned)(R * (LDA ? LDA : K) + C) * 2u; voffB[i] = (unsigned)(Rb * K + C) * 2u; }
;     const size_t kstep = (size_t)(BK * 2);
;     const size_t hstepB = (size_t)HALF * K * 2, hstepA = LDA ? (size_t)HALF * LDA * 2 : hstepB;
;     const size_t tstepA = 2 * hstepA, tstepB = 2 * hstepB;
;     const unsigned ldsw = (unsigned)wid * 1024u;
;     const int aoff = lds_byte(wr * 64 + fr, fq * 8), boff = lds_byte(wc * 32 + fr, fq * 8);
;     ...
;     Unit cur, nxt; int ui = 0;
;     if (!S.next(0, cur)) return;
;     f32x4 acc[2][2][4][2];
; #pragma unroll
;     for (int a = 0; a < 2; ++a)
; #pragma unroll
;         for (int b = 0; b < 2; ++b)
; #pragma unroll
;             for (int m = 0; m < 4; ++m)
; #pragma unroll
;                 for (int n = 0; n < 2; ++n) acc[a][b][m][n] = (f32x4){0.f, 0.f, 0.f, 0.f};
;     bf16x8 At[4][2], B0[2][2], B1[2][2];
;     const char* cA = S.pa(g, cur, tstepA); const char* cB = S.pb(g, cur, tstepB);
;     S.a_ready(cur);
;     if constexpr (SP2) {
;         PG8_STAGE(PG8_SB(0, 0), cB, voffB); PG8_STAGE(PG8_SB(0, 1), cB + hstepB, voffB); PG8_STAGE(PG8_SA(0, 0), cA, voffA); PG8_STAGE(PG8_SA(0, 1), cA + hstepA, voffA);
;         if (wr == 1) PG8_BAR;
;         PG8_WAIT_V(2); PG8_BAR;
;         PG8_STAGE(PG8_SB(1, 0), cB + kstep, voffB); PG8_STAGE(PG8_SA(1, 0), cA + kstep, voffA); PG8_STAGE(PG8_SB(1, 1), cB + hstepB + kstep, voffB);
;         PG8_WAIT_V(6); PG8_BAR;
.LBB0_1147:
	s_add_u32 s30, s44, 0x54c00000
	v_lshrrev_b32_e32 v18, 1, v16
	s_addc_u32 s31, s45, 0
	v_and_b32_e32 v18, 24, v18
	s_add_u32 s44, s44, 0x100000
	v_and_b32_e32 v17, 15, v16
	v_lshlrev_b32_e32 v19, 1, v18
	v_lshlrev_b32_e32 v16, 2, v16
	s_addc_u32 s45, s45, 0
	v_lshl_or_b32 v154, s10, 6, v17
	v_lshl_or_b32 v17, v17, 6, v19
	s_lshl_b32 s10, s10, 13
	v_and_b32_e32 v16, 32, v16
	v_bitop3_b32 v19, v17, s10, v16 bitop3:0xde
	s_lshl_b32 s10, s11, 5
	s_and_b32 s12, s10, 0x60
	s_add_i32 m0, s8, 0x18000
	v_lshl_add_u64 v[8:9], v[8:9], 0, s[22:23]
	s_lshl_b32 s10, s12, 7
	s_waitcnt vmcnt(2)
	s_barrier
	global_load_lds_dwordx4 v[8:9], off
	v_lshl_add_u64 v[6:7], v[6:7], 0, s[22:23]
	s_add_i32 m0, s8, 0x1a000
	s_add_i32 s66, s8, 0x8000
	s_add_i32 s67, s8, 0xa000
	v_bitop3_b32 v155, v17, s10, v16 bitop3:0xde
	global_load_lds_dwordx4 v[6:7], off
	v_lshl_add_u64 v[2:3], v[2:3], 0, s[22:23]
	s_mov_b32 m0, s66
	s_add_u32 s10, s40, 0x80080
	global_load_lds_dwordx4 v[2:3], off
	v_lshl_add_u64 v[2:3], v[4:5], 0, s[22:23]
	s_mov_b32 m0, s67
	s_addc_u32 s11, s41, 0
	global_load_lds_dwordx4 v[2:3], off
	s_add_i32 m0, s8, 0x1c000
	v_lshl_add_u64 v[2:3], s[10:11], 0, v[142:143]
	global_load_lds_dwordx4 v[2:3], off
	v_lshl_add_u64 v[2:3], s[10:11], 0, v[146:147]
	s_add_i32 m0, s8, 0x1e000
	s_cmpk_lt_u32 s6, 0x100
	global_load_lds_dwordx4 v[2:3], off
	v_lshlrev_b32_e32 v2, 15, v10
	v_and_b32_e32 v2, 0xffff0000, v2
	v_lshl_add_u32 v2, v11, 12, v2
	v_and_b32_e32 v3, 1, v10
	v_lshl_or_b32 v2, v3, 6, v2
	v_lshl_add_u32 v150, v12, 1, v2
	v_lshlrev_b32_e32 v2, 15, v13
	v_and_b32_e32 v2, 0xffff0000, v2
	s_waitcnt vmcnt(6)
	v_lshl_add_u32 v2, v14, 12, v2
	v_and_b32_e32 v3, 1, v13
	v_or_b32_e32 v148, s12, v18
	v_lshl_or_b32 v2, v3, 6, v2
	s_cselect_b64 s[46:47], -1, 0
	v_or_b32_e32 v156, 0xffffe800, v148
	v_mov_b32_e32 v149, v35
	s_ashr_i32 s74, s64, 31
	s_ashr_i32 s75, s65, 31
	v_mov_b32_e32 v151, v35
	v_lshl_add_u32 v152, v15, 1, v2
	v_mov_b32_e32 v153, v35
	s_mov_b32 s76, 0
	v_add_u32_e32 v157, 0, v19
	s_barrier
	v_add_u32_e32 v162, 0x10000, v155
	ds_read_b128 v[198:201], v162 offset:18432
	ds_read_b128 v[202:205], v162 offset:19456
	ds_read_b128 v[206:209], v157
	ds_read_b128 v[210:213], v157 offset:1024
	ds_read_b128 v[214:217], v157 offset:2048
	ds_read_b128 v[218:221], v157 offset:3072
	ds_read_b128 v[222:225], v157 offset:4096
	ds_read_b128 v[234:237], v157 offset:5120
	ds_read_b128 v[238:241], v157 offset:6144
	ds_read_b128 v[242:245], v157 offset:7168
	s_branch .LBB0_1150

; #define PG8_STAGE(bufoff, gbase, voff) do { _Pragma("unroll") for (int _i = 0; _i < 2; ++_i) \
;         __builtin_amdgcn_global_load_lds((const unsigned*)((const char*)(gbase) + (voff)[_i]), (PG8_LAS unsigned*)(lds + (bufoff) + ldsw + _i * 8192), 16, 0, 0); } while (0)
; #define PG8_LDA(dst, b, h) do { _Pragma("unroll") for (int m = 0; m < 4; ++m) _Pragma("unroll") for (int k = 0; k < 2; ++k) dst[m][k] = *(const PG8_LAS bf16x8*)(lds + PG8_SA(b, h) + aoff + m * 2048 + k * 1024); } while (0)
; #define PG8_LDB(dst, b, h) do { _Pragma("unroll") for (int n = 0; n < 2; ++n) _Pragma("unroll") for (int k = 0; k < 2; ++k) dst[n][k] = *(const PG8_LAS bf16x8*)(lds + PG8_SB(b, h) + boff + n * 2048 + k * 1024); } while (0)
; #define PG8_WAIT_V(n) asm volatile("s_waitcnt vmcnt(" #n ")" ::: "memory")
; #define PG8_WAIT_L(n) asm volatile("s_waitcnt lgkmcnt(" #n ")" ::: "memory")
; #define PG8_BAR __builtin_amdgcn_s_barrier()
; #define PG8_SCHED __builtin_amdgcn_sched_barrier(0)
;     ...
;             PG8_LDB(B0, 0, 0); PG8_LDB(B1, 0, 1); PG8_SCHED; PG8_LDA(At, 0, 0); PG8_STAGE(PG8_SA(1, 1), a1 + hstepA, voffA);
;             PG8_WAIT_V(8); PG8_WAIT_L(0); PG8_BAR; PG8_MMA(0, 0, At, B0); PG8_MMA(0, 1, At, B1); PG8_BAR; PG8_SCHED;
;             PG8_LDA(At, 0, 1); PG8_STAGE(PG8_SB(0, 0), b2, voffB); PG8_STAGE(PG8_SB(0, 1), b2 + hstepB, voffB); PG8_STAGE(PG8_SA(0, 0), a2, voffA);
;             PG8_WAIT_V(8); PG8_WAIT_L(0); PG8_BAR; PG8_MMA(1, 0, At, B0); PG8_MMA(1, 1, At, B1); PG8_BAR; PG8_SCHED;
.LBB0_1152:
	s_ashr_i32 s49, s48, 31
	s_lshl_b64 s[10:11], s[48:49], 20
	s_add_u32 s50, s60, s10
	s_addc_u32 s51, s61, s11
	s_and_b64 s[10:11], s[38:39], exec
	s_cselect_b32 s6, s51, s27
	s_cselect_b32 s10, s50, s26
	s_ashr_i32 s19, s18, 31
	s_lshl_b64 s[12:13], s[18:19], 20
	s_add_u32 s52, s62, s12
	s_addc_u32 s53, s63, s13
	s_and_b64 s[12:13], s[38:39], exec
	s_cselect_b32 s11, s53, s41
	s_cselect_b32 s12, s52, s40
	s_add_u32 s26, s26, 0x80080
	s_addc_u32 s27, s27, 0
	s_add_u32 s13, s40, 0x100
	s_addc_u32 s15, s41, 0
	s_mov_b32 s19, -2
	v_add_u32_e32 v162, 0x10000, v155
	s_add_u32 s34, s26, 0xfff80080
	s_addc_u32 s35, s27, -1
	s_add_i32 s37, 0, 0x10000
	s_cmp_eq_u32 s19, 28
	s_cselect_b32 s57, s6, s35
	s_cselect_b32 s56, s10, s34
	s_cselect_b32 s41, s11, s15
	s_cselect_b32 s40, s12, s13
	s_add_i32 s49, 0, 0x14000
	ds_read_b128 v[132:135], v162
	ds_read_b128 v[136:139], v162 offset:1024
	s_waitcnt vmcnt(0)
	ds_read_b128 v[158:161], v162 offset:2048
	ds_read_b128 v[186:189], v162 offset:3072
	ds_read_b128 v[190:193], v162 offset:16384
	ds_read_b128 v[194:197], v162 offset:17408
	s_add_i32 m0, s8, 0xc000
	global_load_lds_dwordx4 v150, s[26:27]
	s_add_i32 m0, s8, 0xe000
	s_nop 0
	global_load_lds_dwordx4 v152, s[26:27]
	s_waitcnt vmcnt(8)
	s_waitcnt lgkmcnt(0)
	s_barrier
	v_mfma_f32_16x16x32_bf16 v[128:131], v[132:135], v[206:209], 0
	v_mfma_f32_16x16x32_bf16 v[124:127], v[158:161], v[206:209], 0
	v_mfma_f32_16x16x32_bf16 v[112:115], v[132:135], v[214:217], 0
	v_mfma_f32_16x16x32_bf16 v[108:111], v[158:161], v[214:217], 0
	v_mfma_f32_16x16x32_bf16 v[96:99], v[132:135], v[222:225], 0
	v_mfma_f32_16x16x32_bf16 v[92:95], v[158:161], v[222:225], 0
	v_mfma_f32_16x16x32_bf16 v[80:83], v[132:135], v[238:241], 0
	v_mfma_f32_16x16x32_bf16 v[76:79], v[158:161], v[238:241], 0
	v_mfma_f32_16x16x32_bf16 v[128:131], v[136:139], v[210:213], v[128:131]
	v_mfma_f32_16x16x32_bf16 v[124:127], v[186:189], v[210:213], v[124:127]
	v_mfma_f32_16x16x32_bf16 v[112:115], v[136:139], v[218:221], v[112:115]
	v_mfma_f32_16x16x32_bf16 v[108:111], v[186:189], v[218:221], v[108:111]
	v_mfma_f32_16x16x32_bf16 v[96:99], v[136:139], v[234:237], v[96:99]
	v_mfma_f32_16x16x32_bf16 v[92:95], v[186:189], v[234:237], v[92:95]
	v_mfma_f32_16x16x32_bf16 v[80:83], v[136:139], v[242:245], v[80:83]
	v_mfma_f32_16x16x32_bf16 v[76:79], v[186:189], v[242:245], v[76:79]
	v_mfma_f32_16x16x32_bf16 v[120:123], v[190:193], v[206:209], 0
	v_mfma_f32_16x16x32_bf16 v[116:119], v[198:201], v[206:209], 0
	v_mfma_f32_16x16x32_bf16 v[104:107], v[190:193], v[214:217], 0
	v_mfma_f32_16x16x32_bf16 v[100:103], v[198:201], v[214:217], 0
	v_mfma_f32_16x16x32_bf16 v[88:91], v[190:193], v[222:225], 0
	v_mfma_f32_16x16x32_bf16 v[84:87], v[198:201], v[222:225], 0
	v_mfma_f32_16x16x32_bf16 v[72:75], v[190:193], v[238:241], 0
	v_mfma_f32_16x16x32_bf16 v[68:71], v[198:201], v[238:241], 0
	v_mfma_f32_16x16x32_bf16 v[120:123], v[194:197], v[210:213], v[120:123]
	v_mfma_f32_16x16x32_bf16 v[116:119], v[202:205], v[210:213], v[116:119]
	v_mfma_f32_16x16x32_bf16 v[104:107], v[194:197], v[218:221], v[104:107]
	v_mfma_f32_16x16x32_bf16 v[100:103], v[202:205], v[218:221], v[100:103]
	v_mfma_f32_16x16x32_bf16 v[88:91], v[194:197], v[234:237], v[88:91]
	v_mfma_f32_16x16x32_bf16 v[84:87], v[202:205], v[234:237], v[84:87]
	v_mfma_f32_16x16x32_bf16 v[72:75], v[194:197], v[242:245], v[72:75]
	v_mfma_f32_16x16x32_bf16 v[68:71], v[202:205], v[242:245], v[68:71]
	s_barrier
	s_add_i32 s34, s37, s7
	s_mov_b32 m0, s34
	ds_read_b128 v[206:209], v157 offset:16384
	ds_read_b128 v[210:213], v157 offset:17408
	ds_read_b128 v[214:217], v157 offset:18432
	ds_read_b128 v[218:221], v157 offset:19456
	ds_read_b128 v[222:225], v157 offset:20480
	ds_read_b128 v[234:237], v157 offset:21504
	ds_read_b128 v[238:241], v157 offset:22528
	ds_read_b128 v[242:245], v157 offset:23552
	global_load_lds_dwordx4 v142, s[40:41]
	s_add_i32 m0, s34, 0x2000
	s_add_u32 s34, s40, 0x80000
	s_addc_u32 s35, s41, 0
	s_add_i32 s37, s49, s7
	global_load_lds_dwordx4 v146, s[40:41]
	s_mov_b32 m0, s37
	s_nop 0
	global_load_lds_dwordx4 v142, s[34:35]
	s_add_i32 m0, s37, 0x2000
	s_nop 0
	global_load_lds_dwordx4 v146, s[34:35]
	s_mov_b32 m0, s8
	s_nop 0
	global_load_lds_dwordx4 v140, s[56:57]
	s_mov_b32 m0, s9
	s_nop 0
	global_load_lds_dwordx4 v144, s[56:57]
	s_waitcnt vmcnt(8)
	s_waitcnt lgkmcnt(0)
	s_barrier
	v_mfma_f32_16x16x32_bf16 v[64:67], v[132:135], v[206:209], 0
	v_mfma_f32_16x16x32_bf16 v[60:63], v[158:161], v[206:209], 0
	v_mfma_f32_16x16x32_bf16 v[48:51], v[132:135], v[214:217], 0
	v_mfma_f32_16x16x32_bf16 v[44:47], v[158:161], v[214:217], 0
	v_mfma_f32_16x16x32_bf16 v[30:33], v[132:135], v[222:225], 0
	v_mfma_f32_16x16x32_bf16 v[26:29], v[158:161], v[222:225], 0
	v_mfma_f32_16x16x32_bf16 v[14:17], v[132:135], v[238:241], 0
	v_mfma_f32_16x16x32_bf16 v[10:13], v[158:161], v[238:241], 0
	v_mfma_f32_16x16x32_bf16 v[64:67], v[136:139], v[210:213], v[64:67]
	v_mfma_f32_16x16x32_bf16 v[60:63], v[186:189], v[210:213], v[60:63]
	v_mfma_f32_16x16x32_bf16 v[48:51], v[136:139], v[218:221], v[48:51]
	v_mfma_f32_16x16x32_bf16 v[44:47], v[186:189], v[218:221], v[44:47]
	v_mfma_f32_16x16x32_bf16 v[30:33], v[136:139], v[234:237], v[30:33]
	v_mfma_f32_16x16x32_bf16 v[26:29], v[186:189], v[234:237], v[26:29]
	v_mfma_f32_16x16x32_bf16 v[14:17], v[136:139], v[242:245], v[14:17]
	v_mfma_f32_16x16x32_bf16 v[10:13], v[186:189], v[242:245], v[10:13]
	v_mfma_f32_16x16x32_bf16 v[56:59], v[190:193], v[206:209], 0
	v_mfma_f32_16x16x32_bf16 v[52:55], v[198:201], v[206:209], 0
	v_mfma_f32_16x16x32_bf16 v[40:43], v[190:193], v[214:217], 0
	v_mfma_f32_16x16x32_bf16 v[36:39], v[198:201], v[214:217], 0
	v_mfma_f32_16x16x32_bf16 v[22:25], v[190:193], v[222:225], 0
	v_mfma_f32_16x16x32_bf16 v[18:21], v[198:201], v[222:225], 0
	v_mfma_f32_16x16x32_bf16 v[6:9], v[190:193], v[238:241], 0
	v_mfma_f32_16x16x32_bf16 v[2:5], v[198:201], v[238:241], 0
	v_mfma_f32_16x16x32_bf16 v[56:59], v[194:197], v[210:213], v[56:59]
	v_mfma_f32_16x16x32_bf16 v[52:55], v[202:205], v[210:213], v[52:55]
	v_mfma_f32_16x16x32_bf16 v[40:43], v[194:197], v[218:221], v[40:43]
	v_mfma_f32_16x16x32_bf16 v[36:39], v[202:205], v[218:221], v[36:39]
	v_mfma_f32_16x16x32_bf16 v[22:25], v[194:197], v[234:237], v[22:25]
	v_mfma_f32_16x16x32_bf16 v[18:21], v[202:205], v[234:237], v[18:21]
	v_mfma_f32_16x16x32_bf16 v[6:9], v[194:197], v[242:245], v[6:9]
	v_mfma_f32_16x16x32_bf16 v[2:5], v[202:205], v[242:245], v[2:5]
	s_barrier
	s_branch .Lpeel_mid_1153
	.p2align	6

;     __device__ __forceinline__ void operator()(const f32x4 (&acc)[2][2][4][2], const Unit& u, int wr, int wc, int fr, int fq) const {
;         const int row0 = u.pm * BM + wr * 64 + fr, colt = wc * 32 + 8 * fq;
;         const int kind = (u.pn == 8 || u.pn == 9) ? 1 : ((u.pn >= 20 && u.pn < 24) ? 2 : ((u.pn >= 24 && u.pn < 28) ? 3 : 0));
;         float lbv[2][8];
; #pragma unroll
;         for (int bj = 0; bj < 2; ++bj)
; #pragma unroll
;             for (int k = 0; k < 8; ++k) lbv[bj][k] = kind == 3 ? lb[(u.pn - 24) * BM + bj * HALF + colt + k] : 0.f;
.LBB0_1156:
	s_and_b32 s6, s36, -2
	s_and_b32 s10, s36, -4
	s_cmp_eq_u32 s10, 24
	s_cselect_b32 s11, 3, 0
	s_cmp_lg_u32 s10, 20
	s_cselect_b32 s10, s11, 2
	s_cmp_lg_u32 s6, 8
	s_cselect_b32 s19, s10, 1
	s_cmp_eq_u32 s19, 3
	s_cselect_b64 s[56:57], -1, 0
	ds_read_b128 v[198:201], v162 offset:18432
	ds_read_b128 v[202:205], v162 offset:19456
	ds_read_b128 v[206:209], v157
	ds_read_b128 v[210:213], v157 offset:1024
	ds_read_b128 v[214:217], v157 offset:2048
	ds_read_b128 v[218:221], v157 offset:3072
	ds_read_b128 v[222:225], v157 offset:4096
	ds_read_b128 v[234:237], v157 offset:5120
	ds_read_b128 v[238:241], v157 offset:6144
	ds_read_b128 v[242:245], v157 offset:7168
	s_lshl_b32 s26, s36, 8
	v_add_u32_e32 v132, s26, v156
	s_cmp_lg_u32 s19, 3
	v_mov_b32_e32 v192, 0
	v_ashrrev_i32_e32 v133, 31, v132
	v_mov_b32_e32 v194, 0
	s_cbranch_scc1 .LBB0_1172
	v_lshl_add_u64 v[134:135], v[132:133], 2, s[44:45]
	global_load_dword v194, v[134:135], off
	v_cndmask_b32_e64 v34, 0, 1, s[56:57]
	v_cmp_ne_u32_e64 s[40:41], 1, v34
	s_andn2_b64 vcc, exec, s[56:57]
	s_cbranch_vccz .LBB0_1173

;     __device__ __forceinline__ const char* pa(const Gemm& g, const Unit& u, size_t tstep) const { return (const char*)g.A + (size_t)u.pm * tstep; }
;     __device__ __forceinline__ const char* pb(const Gemm& g, const Unit& u, size_t tstep) const { return (const char*)g.Bt + (size_t)u.pn * tstep; }
;     __device__ __forceinline__ const char* pa(const Gemm& g, const Unit& u, size_t tstep) const { return (const char*)g.A + (size_t)(u.pn >> 1) * 512 + (size_t)u.pm * tstep; }
;     __device__ __forceinline__ bool next(int i, Unit& u) const { const int ti = i / 3, sg = i - 3 * ti; if (!StaticOrder::next(ti, u)) return false; u.seg = sg; return true; }
; #define PG8_WAIT_V(n) asm volatile("s_waitcnt vmcnt(" #n ")" ::: "memory")
; #define PG8_BAR __builtin_amdgcn_s_barrier()
;     ...
;     for (int i = 0; i < 2; ++i) { int R, C; stage_rc(tid * 16 + i * 8192, R, C); const int Rb = Epi::PERM ? ((R & ~31) + perm32(R & 31)) : R;
;         voffA[i] = (unsigned)(R * (LDA ? LDA : K) + C) * 2u; voffB[i] = (unsigned)(Rb * K + C) * 2u; }
;     const size_t kstep = (size_t)(BK * 2);
;     const size_t hstepB = (size_t)HALF * K * 2, hstepA = LDA ? (size_t)HALF * LDA * 2 : hstepB;
;     const size_t tstepA = 2 * hstepA, tstepB = 2 * hstepB;
;     const unsigned ldsw = (unsigned)wid * 1024u;
;     const int aoff = lds_byte(wr * 64 + fr, fq * 8), boff = lds_byte(wc * 32 + fr, fq * 8);
;     ...
;     Unit cur, nxt; int ui = 0;
;     if (!S.next(0, cur)) return;
;     f32x4 acc[2][2][4][2];
; #pragma unroll
;     for (int a = 0; a < 2; ++a)
; #pragma unroll
;         for (int b = 0; b < 2; ++b)
; #pragma unroll
;             for (int m = 0; m < 4; ++m)
; #pragma unroll
;                 for (int n = 0; n < 2; ++n) acc[a][b][m][n] = (f32x4){0.f, 0.f, 0.f, 0.f};
;     bf16x8 At[4][2], B0[2][2], B1[2][2];
;     const char* cA = S.pa(g, cur, tstepA); const char* cB = S.pb(g, cur, tstepB);
;     S.a_ready(cur);
;     if constexpr (SP2) {
;         PG8_STAGE(PG8_SB(0, 0), cB, voffB); PG8_STAGE(PG8_SB(0, 1), cB + hstepB, voffB); PG8_STAGE(PG8_SA(0, 0), cA, voffA); PG8_STAGE(PG8_SA(0, 1), cA + hstepA, voffA);
;         if (wr == 1) PG8_BAR;
;         PG8_WAIT_V(2); PG8_BAR;
;         PG8_STAGE(PG8_SB(1, 0), cB + kstep, voffB); PG8_STAGE(PG8_SA(1, 0), cA + kstep, voffA); PG8_STAGE(PG8_SB(1, 1), cB + hstepB + kstep, voffB);
;         PG8_WAIT_V(6); PG8_BAR;
.LBB0_2128:
	v_lshrrev_b32_e32 v18, 1, v16
	v_and_b32_e32 v18, 24, v18
	s_add_u32 s26, s26, 0x52c00000
	v_and_b32_e32 v17, 15, v16
	v_lshlrev_b32_e32 v19, 1, v18
	v_lshlrev_b32_e32 v16, 2, v16
	s_sext_i32_i8 s31, s24
	s_addc_u32 s27, s27, 0
	v_lshl_or_b32 v142, s29, 6, v17
	v_lshl_or_b32 v17, v17, 6, v19
	s_lshl_b32 s24, s29, 13
	v_and_b32_e32 v16, 32, v16
	v_bitop3_b32 v19, v17, s24, v16 bitop3:0xde
	s_lshl_b32 s24, s28, 5
	s_and_b32 s37, s24, 0x60
	s_lshl_b32 s24, s37, 7
	s_add_i32 m0, s21, 0x18000
	v_lshl_add_u64 v[8:9], v[8:9], 0, s[22:23]
	v_bitop3_b32 v143, v17, s24, v16 bitop3:0xde
	s_waitcnt vmcnt(2)
	s_barrier
	global_load_lds_dwordx4 v[8:9], off
	v_lshl_add_u64 v[6:7], v[6:7], 0, s[22:23]
	s_add_i32 m0, s21, 0x1a000
	s_add_i32 s24, s21, 0x8000
	s_add_i32 s53, s21, 0xa000
	global_load_lds_dwordx4 v[6:7], off
	v_lshl_add_u64 v[2:3], v[2:3], 0, s[22:23]
	s_mov_b32 m0, s24
	s_add_u32 s28, s48, 0x80080
	global_load_lds_dwordx4 v[2:3], off
	v_lshl_add_u64 v[2:3], v[4:5], 0, s[22:23]
	s_mov_b32 m0, s53
	s_addc_u32 s29, s49, 0
	global_load_lds_dwordx4 v[2:3], off
	s_add_i32 m0, s21, 0x1c000
	v_lshl_add_u64 v[2:3], s[28:29], 0, v[34:35]
	global_load_lds_dwordx4 v[2:3], off
	v_lshl_add_u64 v[2:3], s[28:29], 0, v[136:137]
	s_add_i32 m0, s21, 0x1e000
	s_cmpk_lt_u32 s36, 0x100
	global_load_lds_dwordx4 v[2:3], off
	v_lshlrev_b32_e32 v2, 15, v10
	v_and_b32_e32 v2, 0xffff0000, v2
	v_lshl_add_u32 v2, v11, 12, v2
	v_and_b32_e32 v3, 1, v10
	v_lshl_or_b32 v2, v3, 6, v2
	v_lshl_add_u32 v138, v12, 1, v2
	v_lshlrev_b32_e32 v2, 15, v13
	v_and_b32_e32 v2, 0xffff0000, v2
	s_waitcnt vmcnt(6)
	v_lshl_add_u32 v2, v14, 12, v2
	v_and_b32_e32 v3, 1, v13
	v_lshl_or_b32 v2, v3, 6, v2
	s_cselect_b64 s[28:29], -1, 0
	s_ashr_i32 s54, s8, 31
	v_or_b32_e32 v144, s37, v18
	v_mov_b32_e32 v139, v35
	v_lshl_add_u32 v140, v15, 1, v2
	v_mov_b32_e32 v141, v35
	s_mov_b32 s55, 0
	v_add_u32_e32 v145, 0, v19
	s_barrier
	v_add_u32_e32 v163, 0x10000, v143
	ds_read_b128 v[154:157], v163 offset:2048
	ds_read_b128 v[158:161], v163 offset:3072
	ds_read_b128 v[186:189], v163 offset:16384
	ds_read_b128 v[190:193], v163 offset:17408
	ds_read_b128 v[194:197], v163 offset:18432
	ds_read_b128 v[198:201], v163 offset:19456
	ds_read_b128 v[202:205], v145
	ds_read_b128 v[206:209], v145 offset:1024
	ds_read_b128 v[210:213], v145 offset:2048
	ds_read_b128 v[214:217], v145 offset:3072
	ds_read_b128 v[218:221], v145 offset:4096
	ds_read_b128 v[222:225], v145 offset:5120
	ds_read_b128 v[234:237], v145 offset:6144
	ds_read_b128 v[238:241], v145 offset:7168
	s_branch .LBB0_2131

; #define PG8_STAGE(bufoff, gbase, voff) do { _Pragma("unroll") for (int _i = 0; _i < 2; ++_i) \
;         __builtin_amdgcn_global_load_lds((const unsigned*)((const char*)(gbase) + (voff)[_i]), (PG8_LAS unsigned*)(lds + (bufoff) + ldsw + _i * 8192), 16, 0, 0); } while (0)
; #define PG8_LDA(dst, b, h) do { _Pragma("unroll") for (int m = 0; m < 4; ++m) _Pragma("unroll") for (int k = 0; k < 2; ++k) dst[m][k] = *(const PG8_LAS bf16x8*)(lds + PG8_SA(b, h) + aoff + m * 2048 + k * 1024); } while (0)
; #define PG8_LDB(dst, b, h) do { _Pragma("unroll") for (int n = 0; n < 2; ++n) _Pragma("unroll") for (int k = 0; k < 2; ++k) dst[n][k] = *(const PG8_LAS bf16x8*)(lds + PG8_SB(b, h) + boff + n * 2048 + k * 1024); } while (0)
; #define PG8_WAIT_V(n) asm volatile("s_waitcnt vmcnt(" #n ")" ::: "memory")
; #define PG8_WAIT_L(n) asm volatile("s_waitcnt lgkmcnt(" #n ")" ::: "memory")
; #define PG8_BAR __builtin_amdgcn_s_barrier()
; #define PG8_SCHED __builtin_amdgcn_sched_barrier(0)
;     ...
;             PG8_LDB(B0, 0, 0); PG8_LDB(B1, 0, 1); PG8_SCHED; PG8_LDA(At, 0, 0); PG8_STAGE(PG8_SA(1, 1), a1 + hstepA, voffA);
;             PG8_WAIT_V(8); PG8_WAIT_L(0); PG8_BAR; PG8_MMA(0, 0, At, B0); PG8_MMA(0, 1, At, B1); PG8_BAR; PG8_SCHED;
;             PG8_LDA(At, 0, 1); PG8_STAGE(PG8_SB(0, 0), b2, voffB); PG8_STAGE(PG8_SB(0, 1), b2 + hstepB, voffB); PG8_STAGE(PG8_SA(0, 0), a2, voffA);
;             PG8_WAIT_V(8); PG8_WAIT_L(0); PG8_BAR; PG8_MMA(1, 0, At, B0); PG8_MMA(1, 1, At, B1); PG8_BAR; PG8_SCHED;
.LBB0_2137:
	s_ashr_i32 s41, s40, 31
	s_lshl_b64 s[42:43], s[40:41], 20
	s_add_u32 s42, s10, s42
	s_addc_u32 s43, s11, s43
	s_and_b64 s[44:45], s[38:39], exec
	s_cselect_b32 s41, s43, s47
	s_cselect_b32 s56, s42, s46
	s_ashr_i32 s37, s36, 31
	s_lshl_b64 s[44:45], s[36:37], 20
	s_add_u32 s44, s12, s44
	s_addc_u32 s45, s13, s45
	s_and_b64 s[50:51], s[38:39], exec
	s_cselect_b32 s37, s45, s49
	s_cselect_b32 s57, s44, s48
	s_add_u32 s46, s46, 0x80080
	s_addc_u32 s47, s47, 0
	s_add_u32 s58, s48, 0x100
	s_addc_u32 s59, s49, 0
	s_mov_b32 s60, -2
	v_add_u32_e32 v163, 0x10000, v143
	s_add_u32 s48, s46, 0xfff80080
	s_addc_u32 s49, s47, -1
	s_add_i32 s61, 0, 0x10000
	s_cmp_eq_u32 s60, 28
	s_cselect_b32 s51, s41, s49
	s_cselect_b32 s50, s56, s48
	s_cselect_b32 s49, s37, s59
	s_cselect_b32 s48, s57, s58
	s_add_i32 s64, 0, 0x14000
	ds_read_b128 v[146:149], v163
	ds_read_b128 v[150:153], v163 offset:1024
	s_add_i32 m0, s21, 0xc000
	global_load_lds_dwordx4 v138, s[46:47]
	s_add_i32 m0, s21, 0xe000
	s_nop 0
	global_load_lds_dwordx4 v140, s[46:47]
	s_waitcnt vmcnt(8)
	s_waitcnt lgkmcnt(0)
	s_barrier
	v_mfma_f32_16x16x32_bf16 v[128:131], v[146:149], v[202:205], 0
	v_mfma_f32_16x16x32_bf16 v[124:127], v[154:157], v[202:205], 0
	v_mfma_f32_16x16x32_bf16 v[120:123], v[146:149], v[210:213], 0
	v_mfma_f32_16x16x32_bf16 v[116:119], v[154:157], v[210:213], 0
	v_mfma_f32_16x16x32_bf16 v[104:107], v[146:149], v[218:221], 0
	v_mfma_f32_16x16x32_bf16 v[100:103], v[154:157], v[218:221], 0
	v_mfma_f32_16x16x32_bf16 v[88:91], v[146:149], v[234:237], 0
	v_mfma_f32_16x16x32_bf16 v[84:87], v[154:157], v[234:237], 0
	v_mfma_f32_16x16x32_bf16 v[128:131], v[150:153], v[206:209], v[128:131]
	v_mfma_f32_16x16x32_bf16 v[124:127], v[158:161], v[206:209], v[124:127]
	v_mfma_f32_16x16x32_bf16 v[120:123], v[150:153], v[214:217], v[120:123]
	v_mfma_f32_16x16x32_bf16 v[116:119], v[158:161], v[214:217], v[116:119]
	v_mfma_f32_16x16x32_bf16 v[104:107], v[150:153], v[222:225], v[104:107]
	v_mfma_f32_16x16x32_bf16 v[100:103], v[158:161], v[222:225], v[100:103]
	v_mfma_f32_16x16x32_bf16 v[88:91], v[150:153], v[238:241], v[88:91]
	v_mfma_f32_16x16x32_bf16 v[84:87], v[158:161], v[238:241], v[84:87]
	v_mfma_f32_16x16x32_bf16 v[112:115], v[186:189], v[202:205], 0
	v_mfma_f32_16x16x32_bf16 v[108:111], v[194:197], v[202:205], 0
	v_mfma_f32_16x16x32_bf16 v[96:99], v[186:189], v[210:213], 0
	v_mfma_f32_16x16x32_bf16 v[92:95], v[194:197], v[210:213], 0
	v_mfma_f32_16x16x32_bf16 v[80:83], v[186:189], v[218:221], 0
	v_mfma_f32_16x16x32_bf16 v[76:79], v[194:197], v[218:221], 0
	v_mfma_f32_16x16x32_bf16 v[72:75], v[186:189], v[234:237], 0
	v_mfma_f32_16x16x32_bf16 v[68:71], v[194:197], v[234:237], 0
	v_mfma_f32_16x16x32_bf16 v[112:115], v[190:193], v[206:209], v[112:115]
	v_mfma_f32_16x16x32_bf16 v[108:111], v[198:201], v[206:209], v[108:111]
	v_mfma_f32_16x16x32_bf16 v[96:99], v[190:193], v[214:217], v[96:99]
	v_mfma_f32_16x16x32_bf16 v[92:95], v[198:201], v[214:217], v[92:95]
	v_mfma_f32_16x16x32_bf16 v[80:83], v[190:193], v[222:225], v[80:83]
	v_mfma_f32_16x16x32_bf16 v[76:79], v[198:201], v[222:225], v[76:79]
	v_mfma_f32_16x16x32_bf16 v[72:75], v[190:193], v[238:241], v[72:75]
	v_mfma_f32_16x16x32_bf16 v[68:71], v[198:201], v[238:241], v[68:71]
	s_barrier
	s_add_i32 s61, s61, s15
	s_mov_b32 m0, s61
	ds_read_b128 v[202:205], v145 offset:16384
	ds_read_b128 v[206:209], v145 offset:17408
	ds_read_b128 v[210:213], v145 offset:18432
	ds_read_b128 v[214:217], v145 offset:19456
	ds_read_b128 v[218:221], v145 offset:20480
	ds_read_b128 v[222:225], v145 offset:21504
	ds_read_b128 v[234:237], v145 offset:22528
	ds_read_b128 v[238:241], v145 offset:23552
	global_load_lds_dwordx4 v34, s[48:49]
	s_add_i32 m0, s61, 0x2000
	s_add_u32 s62, s48, 0x80000
	s_addc_u32 s63, s49, 0
	s_add_i32 s61, s64, s15
	global_load_lds_dwordx4 v136, s[48:49]
	s_mov_b32 m0, s61
	s_add_u32 s98, s50, 0x80
	s_addc_u32 s99, s51, 0
	global_load_lds_dwordx4 v34, s[62:63]
	s_add_i32 m0, s61, 0x2000
	s_nop 0
	global_load_lds_dwordx4 v136, s[62:63]
	s_mov_b32 m0, s21
	s_nop 0
	global_load_lds_dwordx4 v132, s[50:51]
	s_mov_b32 m0, s34
	s_nop 0
	global_load_lds_dwordx4 v134, s[50:51]
	s_waitcnt vmcnt(8)
	s_waitcnt lgkmcnt(0)
	s_barrier
	v_mfma_f32_16x16x32_bf16 v[64:67], v[146:149], v[202:205], 0
	v_mfma_f32_16x16x32_bf16 v[60:63], v[154:157], v[202:205], 0
	v_mfma_f32_16x16x32_bf16 v[56:59], v[146:149], v[210:213], 0
	v_mfma_f32_16x16x32_bf16 v[52:55], v[154:157], v[210:213], 0
	v_mfma_f32_16x16x32_bf16 v[40:43], v[146:149], v[218:221], 0
	v_mfma_f32_16x16x32_bf16 v[36:39], v[154:157], v[218:221], 0
	v_mfma_f32_16x16x32_bf16 v[22:25], v[146:149], v[234:237], 0
	v_mfma_f32_16x16x32_bf16 v[18:21], v[154:157], v[234:237], 0
	v_mfma_f32_16x16x32_bf16 v[64:67], v[150:153], v[206:209], v[64:67]
	v_mfma_f32_16x16x32_bf16 v[60:63], v[158:161], v[206:209], v[60:63]
	v_mfma_f32_16x16x32_bf16 v[56:59], v[150:153], v[214:217], v[56:59]
	v_mfma_f32_16x16x32_bf16 v[52:55], v[158:161], v[214:217], v[52:55]
	v_mfma_f32_16x16x32_bf16 v[40:43], v[150:153], v[222:225], v[40:43]
	v_mfma_f32_16x16x32_bf16 v[36:39], v[158:161], v[222:225], v[36:39]
	v_mfma_f32_16x16x32_bf16 v[22:25], v[150:153], v[238:241], v[22:25]
	v_mfma_f32_16x16x32_bf16 v[18:21], v[158:161], v[238:241], v[18:21]
	v_mfma_f32_16x16x32_bf16 v[48:51], v[186:189], v[202:205], 0
	v_mfma_f32_16x16x32_bf16 v[44:47], v[194:197], v[202:205], 0
	v_mfma_f32_16x16x32_bf16 v[30:33], v[186:189], v[210:213], 0
	v_mfma_f32_16x16x32_bf16 v[26:29], v[194:197], v[210:213], 0
	v_mfma_f32_16x16x32_bf16 v[14:17], v[186:189], v[218:221], 0
	v_mfma_f32_16x16x32_bf16 v[10:13], v[194:197], v[218:221], 0
	v_mfma_f32_16x16x32_bf16 v[6:9], v[186:189], v[234:237], 0
	v_mfma_f32_16x16x32_bf16 v[2:5], v[194:197], v[234:237], 0
	v_mfma_f32_16x16x32_bf16 v[48:51], v[190:193], v[206:209], v[48:51]
	v_mfma_f32_16x16x32_bf16 v[44:47], v[198:201], v[206:209], v[44:47]
	v_mfma_f32_16x16x32_bf16 v[30:33], v[190:193], v[214:217], v[30:33]
	v_mfma_f32_16x16x32_bf16 v[26:29], v[198:201], v[214:217], v[26:29]
	v_mfma_f32_16x16x32_bf16 v[14:17], v[190:193], v[222:225], v[14:17]
	v_mfma_f32_16x16x32_bf16 v[10:13], v[198:201], v[222:225], v[10:13]
	v_mfma_f32_16x16x32_bf16 v[6:9], v[190:193], v[238:241], v[6:9]
	v_mfma_f32_16x16x32_bf16 v[2:5], v[198:201], v[238:241], v[2:5]
	s_barrier
	s_branch .Lpeel_mid_2138
	.p2align	6

; __device__ __forceinline__ unsigned cvt_pk_bf16(float lo, float hi) { f32x2c v = {lo, hi}; bf16x2c b = __builtin_convertvector(v, bf16x2c); return __builtin_bit_cast(unsigned, b); }
;     __device__ __forceinline__ void operator()(const f32x4 (&acc)[2][2][4][2], const Unit& u, int wr, int wc, int fr, int fq) const {
;         const int row0 = u.pm * BM + wr * 64 + fr, col0 = u.pn * BM + wc * 32 + 8 * fq;
; #pragma unroll
;         for (int ai = 0; ai < 2; ++ai)
; #pragma unroll
;             for (int m = 0; m < 4; ++m) { bf16_t* rowp = O + (size_t)(row0 + ai * HALF + m * 16) * ldc + col0;
; #pragma unroll
;                 for (int bj = 0; bj < 2; ++bj) { const f32x4 v0 = acc[ai][bj][m][0], v1 = acc[ai][bj][m][1];
;                     u32x4 w; w.x = cvt_pk_bf16(v0[0], v0[1]); w.y = cvt_pk_bf16(v0[2], v0[3]); w.z = cvt_pk_bf16(v1[0], v1[1]); w.w = cvt_pk_bf16(v1[2], v1[3]);
;                     *(u32x4*)(rowp + bj * HALF) = w; } }
.LBB0_2141:
	v_lshl_add_u32 v146, s30, 8, v142
	v_lshl_or_b32 v148, s31, 8, v144
	v_ashrrev_i32_e32 v147, 31, v146
	v_ashrrev_i32_e32 v149, 31, v148
	v_lshlrev_b64 v[150:151], 12, v[146:147]
	v_lshl_add_u64 v[150:151], s[26:27], 0, v[150:151]
	v_lshlrev_b64 v[148:149], 1, v[148:149]
	v_lshl_add_u64 v[150:151], v[150:151], 0, v[148:149]
	s_mov_b64 s[30:31], 0x80000
	v_cvt_pk_bf16_f32 v72, v72, v73
	v_cvt_pk_bf16_f32 v73, v74, v75
	v_cvt_pk_bf16_f32 v74, v68, v69
	v_lshl_add_u64 v[68:69], v[150:151], 0, s[30:31]
	s_mov_b32 s30, 0x80000
	ds_read_b128 v[154:157], v163 offset:2048
	ds_read_b128 v[158:161], v163 offset:3072
	ds_read_b128 v[186:189], v163 offset:16384
	ds_read_b128 v[190:193], v163 offset:17408
	ds_read_b128 v[194:197], v163 offset:18432
	ds_read_b128 v[198:201], v163 offset:19456
	ds_read_b128 v[202:205], v145
	ds_read_b128 v[206:209], v145 offset:1024
	ds_read_b128 v[210:213], v145 offset:2048
	ds_read_b128 v[214:217], v145 offset:3072
	ds_read_b128 v[218:221], v145 offset:4096
	ds_read_b128 v[222:225], v145 offset:5120
	ds_read_b128 v[234:237], v145 offset:6144
	ds_read_b128 v[238:241], v145 offset:7168
	v_cvt_pk_bf16_f32 v64, v64, v65
	v_cvt_pk_bf16_f32 v65, v66, v67
	v_cvt_pk_bf16_f32 v66, v60, v61
	v_add_co_u32_e32 v60, vcc, s30, v150
	v_cvt_pk_bf16_f32 v48, v48, v49
	v_cvt_pk_bf16_f32 v49, v50, v51
	v_cvt_pk_bf16_f32 v50, v44, v45
	v_cvt_pk_bf16_f32 v51, v46, v47
	s_mov_b64 s[30:31], 0x90000
	v_addc_co_u32_e32 v61, vcc, 0, v151, vcc
	global_store_dwordx4 v[68:69], v[48:51], off offset:256 sc0 sc1
	v_cvt_pk_bf16_f32 v112, v112, v113
	v_cvt_pk_bf16_f32 v113, v114, v115
	v_lshl_add_u64 v[48:49], v[150:151], 0, s[30:31]
	s_mov_b32 s30, 0x90000
	v_cvt_pk_bf16_f32 v114, v108, v109
	v_or_b32_e32 v108, 16, v146
	v_add_co_u32_e32 v50, vcc, s30, v150
	v_cvt_pk_bf16_f32 v30, v30, v31
	v_cvt_pk_bf16_f32 v31, v32, v33
	v_cvt_pk_bf16_f32 v32, v26, v27
	v_cvt_pk_bf16_f32 v33, v28, v29
	s_mov_b64 s[30:31], 0xa0000
	v_ashrrev_i32_e32 v109, 31, v108
	v_cvt_pk_bf16_f32 v96, v96, v97
	v_cvt_pk_bf16_f32 v97, v98, v99
	v_cvt_pk_bf16_f32 v98, v92, v93
	v_or_b32_e32 v92, 32, v146
	v_addc_co_u32_e32 v51, vcc, 0, v151, vcc
	global_store_dwordx4 v[48:49], v[30:33], off offset:256 sc0 sc1
	v_lshlrev_b64 v[108:109], 12, v[108:109]
	v_ashrrev_i32_e32 v93, 31, v92
	v_lshl_add_u64 v[30:31], v[150:151], 0, s[30:31]
	s_mov_b32 s30, 0xa0000
	v_cvt_pk_bf16_f32 v80, v80, v81
	v_cvt_pk_bf16_f32 v81, v82, v83
	v_cvt_pk_bf16_f32 v82, v76, v77
	v_or_b32_e32 v76, 48, v146
	v_add_co_u32_e32 v32, vcc, s30, v150
	v_cvt_pk_bf16_f32 v14, v14, v15
	v_cvt_pk_bf16_f32 v15, v16, v17
	v_cvt_pk_bf16_f32 v16, v10, v11
	v_cvt_pk_bf16_f32 v17, v12, v13
	s_mov_b64 s[30:31], 0xb0000
	v_cvt_pk_bf16_f32 v115, v110, v111
	v_lshl_add_u64 v[108:109], s[26:27], 0, v[108:109]
	v_lshlrev_b64 v[92:93], 12, v[92:93]
	v_ashrrev_i32_e32 v77, 31, v76
	v_addc_co_u32_e32 v33, vcc, 0, v151, vcc
	global_store_dwordx4 v[30:31], v[14:17], off offset:256 sc0 sc1
	global_store_dwordx4 v[150:151], v[112:115], off offset:256 sc0 sc1
	v_cvt_pk_bf16_f32 v99, v94, v95
	v_lshl_add_u64 v[14:15], v[150:151], 0, s[30:31]
	s_mov_b32 s30, 0xb0000
	v_lshl_add_u64 v[112:113], v[108:109], 0, v[148:149]
	v_lshl_add_u64 v[92:93], s[26:27], 0, v[92:93]
	v_lshlrev_b64 v[76:77], 12, v[76:77]
	v_add_co_u32_e32 v16, vcc, s30, v150
	global_store_dwordx4 v[112:113], v[96:99], off offset:256 sc0 sc1
	v_cvt_pk_bf16_f32 v83, v78, v79
	v_lshl_add_u64 v[76:77], s[26:27], 0, v[76:77]
	v_lshl_add_u64 v[96:97], v[92:93], 0, v[148:149]
	v_addc_co_u32_e32 v17, vcc, 0, v151, vcc
	v_cvt_pk_bf16_f32 v128, v128, v129
	v_cvt_pk_bf16_f32 v129, v130, v131
	v_cvt_pk_bf16_f32 v130, v124, v125
	v_cvt_pk_bf16_f32 v131, v126, v127
	v_cvt_pk_bf16_f32 v108, v120, v121
	v_cvt_pk_bf16_f32 v109, v122, v123
	v_cvt_pk_bf16_f32 v110, v116, v117
	v_cvt_pk_bf16_f32 v111, v118, v119
	v_cvt_pk_bf16_f32 v92, v104, v105
	v_cvt_pk_bf16_f32 v93, v106, v107
	v_cvt_pk_bf16_f32 v94, v100, v101
	v_cvt_pk_bf16_f32 v95, v102, v103
	global_store_dwordx4 v[96:97], v[80:83], off offset:256 sc0 sc1
	v_cvt_pk_bf16_f32 v78, v84, v85
	v_cvt_pk_bf16_f32 v79, v86, v87
	v_lshl_add_u64 v[80:81], v[76:77], 0, v[148:149]
	v_cvt_pk_bf16_f32 v76, v88, v89
	v_cvt_pk_bf16_f32 v77, v90, v91
	v_cvt_pk_bf16_f32 v75, v70, v71
	v_cvt_pk_bf16_f32 v67, v62, v63
	v_cvt_pk_bf16_f32 v44, v56, v57
	v_cvt_pk_bf16_f32 v45, v58, v59
	v_cvt_pk_bf16_f32 v46, v52, v53
	v_cvt_pk_bf16_f32 v47, v54, v55
	v_cvt_pk_bf16_f32 v26, v40, v41
	v_cvt_pk_bf16_f32 v27, v42, v43
	v_cvt_pk_bf16_f32 v28, v36, v37
	v_cvt_pk_bf16_f32 v29, v38, v39
	v_cvt_pk_bf16_f32 v10, v22, v23
	v_cvt_pk_bf16_f32 v11, v24, v25
	v_cvt_pk_bf16_f32 v12, v18, v19
	v_cvt_pk_bf16_f32 v13, v20, v21
	v_cvt_pk_bf16_f32 v6, v6, v7
	v_cvt_pk_bf16_f32 v7, v8, v9
	v_cvt_pk_bf16_f32 v8, v2, v3
	v_cvt_pk_bf16_f32 v9, v4, v5
	s_andn2_b64 vcc, exec, s[38:39]
	s_mov_b64 s[30:31], -1
	global_store_dwordx4 v[150:151], v[128:131], off sc0 sc1
	global_store_dwordx4 v[112:113], v[108:111], off sc0 sc1
	global_store_dwordx4 v[96:97], v[92:95], off sc0 sc1
	global_store_dwordx4 v[80:81], v[76:79], off sc0 sc1
	global_store_dwordx4 v[80:81], v[72:75], off offset:256 sc0 sc1
	global_store_dwordx4 v[60:61], v[64:67], off sc0 sc1
	global_store_dwordx4 v[50:51], v[44:47], off sc0 sc1
	global_store_dwordx4 v[32:33], v[26:29], off sc0 sc1
	global_store_dwordx4 v[16:17], v[10:13], off sc0 sc1
	global_store_dwordx4 v[14:15], v[6:9], off offset:256 sc0 sc1
	s_cbranch_vccnz .LBB0_2130
	s_andn2_b64 vcc, exec, s[18:19]
	s_cbranch_vccnz .LBB0_2129
	s_barrier
	s_branch .LBB0_2129
